# nt cache hint on once-read row loads in norm1/norm2/final phases
# speedup vs baseline: 1.0118x; 1.0068x over previous
; __device__ __forceinline__ void unpack8(const u32x4 w, f32x4& a, f32x4& c) { a = (f32x4){bf_lo(w.x), bf_hi(w.x), bf_lo(w.y), bf_hi(w.y)}; c = (f32x4){bf_lo(w.z), bf_hi(w.z), bf_lo(w.w), bf_hi(w.w)}; }
; template <bool X_F32> __device__ __forceinline__ void phase_norm_mod(const Ctx& C, const void* xin, const float* modl, int shift_idx, int scale_idx) {
;     ...
;         for (int r0_ = (gw % (NGW >> 3)) * NR; r0_ < T / 8; r0_ += (NGW >> 3) * NR) { const int m0 = (gw / (NGW >> 3)) * (T / 8) + r0_;
;             const int b = m0 >> 12;
;             u32x4 raw[NR][2]; float s[NR];
; #pragma unroll
;             for (int r = 0; r < NR; ++r)
; #pragma unroll
;                 for (int j = 0; j < 2; ++j) raw[r][j] = ((const u32x4*)((const bf16*)xin + (size_t)(m0 + r) * DM + 512 * j))[lane];
; #pragma unroll
;             for (int r = 0; r < NR; ++r) { s[r] = 0.f;
; #pragma unroll
;                 for (int j = 0; j < 2; ++j) { f32x4 t0, t1; unpack8(raw[r][j], t0, t1);
;                     s[r] += ((t0.x * t0.x + t0.y * t0.y) + (t0.z * t0.z + t0.w * t0.w)) + ((t1.x * t1.x + t1.y * t1.y) + (t1.z * t1.z + t1.w * t1.w)); } }
.LBB0_129:
	s_add_i32 s20, s12, s50
	s_ashr_i32 s21, s20, 31
	s_lshl_b64 s[48:49], s[20:21], 11
	v_lshl_add_u64 v[4:5], v[16:17], 0, s[48:49]
	global_load_dwordx4 v[0:3], v[4:5], off nt
	s_nop 0
	global_load_dwordx4 v[4:7], v[4:5], off offset:1024 nt
	s_add_i32 s2, s20, 1
	s_ashr_i32 s3, s2, 31
	s_lshl_b64 s[14:15], s[2:3], 11
	v_lshl_add_u64 v[12:13], v[16:17], 0, s[14:15]
	global_load_dwordx4 v[8:11], v[12:13], off nt
	s_nop 0
	global_load_dwordx4 v[12:15], v[12:13], off offset:1024 nt
	s_add_i32 s2, s20, 2
	s_ashr_i32 s3, s2, 31
	s_lshl_b64 s[4:5], s[2:3], 11
	v_lshl_add_u64 v[26:27], v[16:17], 0, s[4:5]
	global_load_dwordx4 v[22:25], v[26:27], off nt
	s_nop 0
	global_load_dwordx4 v[26:29], v[26:27], off offset:1024 nt
	s_add_i32 s2, s20, 3
	s_ashr_i32 s3, s2, 31
	s_lshl_b64 s[46:47], s[2:3], 11
	v_lshl_add_u64 v[34:35], v[16:17], 0, s[46:47]
	global_load_dwordx4 v[30:33], v[34:35], off nt
	s_nop 0
	global_load_dwordx4 v[34:37], v[34:35], off offset:1024 nt
	s_add_i32 s2, s20, 4
	s_ashr_i32 s3, s2, 31
	s_lshl_b64 s[44:45], s[2:3], 11
	v_lshl_add_u64 v[42:43], v[16:17], 0, s[44:45]
	global_load_dwordx4 v[38:41], v[42:43], off nt
	s_nop 0
	global_load_dwordx4 v[42:45], v[42:43], off offset:1024 nt
	s_add_i32 s2, s20, 5
	s_ashr_i32 s3, s2, 31
	s_lshl_b64 s[42:43], s[2:3], 11
	v_lshl_add_u64 v[50:51], v[16:17], 0, s[42:43]
	global_load_dwordx4 v[46:49], v[50:51], off nt
	s_nop 0
	global_load_dwordx4 v[50:53], v[50:51], off offset:1024 nt
	s_add_i32 s2, s20, 6
	s_ashr_i32 s3, s2, 31
	s_lshl_b64 s[40:41], s[2:3], 11
	v_lshl_add_u64 v[54:55], v[16:17], 0, s[40:41]
	global_load_dwordx4 v[104:107], v[54:55], off nt
	global_load_dwordx4 v[108:111], v[54:55], off offset:1024 nt
	s_add_i32 s2, s20, 7
	s_ashr_i32 s3, s2, 31
	s_lshl_b64 s[38:39], s[2:3], 11
	v_lshl_add_u64 v[54:55], v[16:17], 0, s[38:39]
	global_load_dwordx4 v[112:115], v[54:55], off nt
	global_load_dwordx4 v[116:119], v[54:55], off offset:1024 nt
	s_ashr_i32 s2, s20, 12
	s_mul_hi_i32 s3, s2, 0x6000
	s_mulk_i32 s2, 0x6000
	s_add_u32 s2, s78, s2
	s_addc_u32 s3, s1, s3
	v_lshl_add_u64 v[198:199], v[20:21], 0, s[48:49]
	s_add_i32 s13, s13, s10
	s_add_i32 s50, s50, s10
	s_waitcnt vmcnt(0)
	v_and_b32_e32 v154, 0xffff0000, v0
	v_and_b32_e32 v155, 0xffff0000, v4
	v_and_b32_e32 v175, 0xffff0000, v5
	v_and_b32_e32 v174, 0xffff0000, v1
	v_lshlrev_b32_e32 v153, 16, v4
	v_lshlrev_b32_e32 v152, 16, v0
	v_lshlrev_b32_e32 v159, 16, v5
	v_lshlrev_b32_e32 v158, 16, v1
	v_lshlrev_b32_e32 v156, 16, v2
	v_and_b32_e32 v160, 0xffff0000, v2
	v_lshlrev_b32_e32 v176, 16, v3
	v_and_b32_e32 v178, 0xffff0000, v3
	v_pk_mul_f32 v[0:1], v[154:155], v[154:155]
	v_pk_mul_f32 v[2:3], v[174:175], v[174:175]
	v_and_b32_e32 v161, 0xffff0000, v6
	v_and_b32_e32 v179, 0xffff0000, v7
	v_pk_fma_f32 v[0:1], v[152:153], v[152:153], v[0:1]
	v_pk_fma_f32 v[2:3], v[158:159], v[158:159], v[2:3]
	v_lshlrev_b32_e32 v157, 16, v6
	v_lshlrev_b32_e32 v177, 16, v7
	v_pk_add_f32 v[0:1], v[0:1], v[2:3]
	v_pk_mul_f32 v[2:3], v[160:161], v[160:161]
	v_pk_mul_f32 v[4:5], v[178:179], v[178:179]
	v_pk_fma_f32 v[2:3], v[156:157], v[156:157], v[2:3]
	v_pk_fma_f32 v[4:5], v[176:177], v[176:177], v[4:5]
	v_and_b32_e32 v139, 0xffff0000, v12
	v_pk_add_f32 v[2:3], v[2:3], v[4:5]
	v_and_b32_e32 v138, 0xffff0000, v8
	v_and_b32_e32 v147, 0xffff0000, v13
	v_and_b32_e32 v146, 0xffff0000, v9
	v_pk_add_f32 v[0:1], v[0:1], v[2:3]
	v_lshlrev_b32_e32 v137, 16, v12
	v_lshlrev_b32_e32 v136, 16, v8
	v_lshlrev_b32_e32 v143, 16, v13
	v_lshlrev_b32_e32 v142, 16, v9
	v_pk_mul_f32 v[2:3], v[138:139], v[138:139]
	v_pk_mul_f32 v[4:5], v[146:147], v[146:147]
	v_and_b32_e32 v145, 0xffff0000, v14
	v_and_b32_e32 v144, 0xffff0000, v10
	v_and_b32_e32 v151, 0xffff0000, v15
	v_and_b32_e32 v150, 0xffff0000, v11
	v_pk_fma_f32 v[2:3], v[136:137], v[136:137], v[2:3]
	v_pk_fma_f32 v[4:5], v[142:143], v[142:143], v[4:5]
	v_lshlrev_b32_e32 v141, 16, v14
	v_lshlrev_b32_e32 v140, 16, v10
	v_lshlrev_b32_e32 v149, 16, v15
	v_lshlrev_b32_e32 v148, 16, v11
	v_pk_add_f32 v[2:3], v[2:3], v[4:5]
	v_pk_mul_f32 v[4:5], v[144:145], v[144:145]
	v_pk_mul_f32 v[6:7], v[150:151], v[150:151]
	v_pk_fma_f32 v[4:5], v[140:141], v[140:141], v[4:5]
	v_pk_fma_f32 v[6:7], v[148:149], v[148:149], v[6:7]
	v_and_b32_e32 v123, 0xffff0000, v26
	v_pk_add_f32 v[4:5], v[4:5], v[6:7]
	v_and_b32_e32 v122, 0xffff0000, v22
	v_pk_add_f32 v[2:3], v[2:3], v[4:5]
	v_and_b32_e32 v131, 0xffff0000, v27
	v_and_b32_e32 v130, 0xffff0000, v23
	v_add_f32_e32 v0, v0, v1
	v_add_f32_e32 v1, v2, v3
	v_lshlrev_b32_e32 v121, 16, v26
	v_lshlrev_b32_e32 v120, 16, v22
	v_lshlrev_b32_e32 v127, 16, v27
	v_lshlrev_b32_e32 v126, 16, v23
	v_pk_mul_f32 v[2:3], v[122:123], v[122:123]
	v_pk_mul_f32 v[4:5], v[130:131], v[130:131]
	v_and_b32_e32 v129, 0xffff0000, v28
	v_and_b32_e32 v128, 0xffff0000, v24
	v_and_b32_e32 v135, 0xffff0000, v29
	v_and_b32_e32 v134, 0xffff0000, v25
	v_pk_fma_f32 v[2:3], v[120:121], v[120:121], v[2:3]
	v_pk_fma_f32 v[4:5], v[126:127], v[126:127], v[4:5]
	v_lshlrev_b32_e32 v125, 16, v28
	v_lshlrev_b32_e32 v124, 16, v24
	v_lshlrev_b32_e32 v133, 16, v29
	v_lshlrev_b32_e32 v132, 16, v25
	v_pk_add_f32 v[2:3], v[2:3], v[4:5]
	v_pk_mul_f32 v[4:5], v[128:129], v[128:129]
	v_pk_mul_f32 v[6:7], v[134:135], v[134:135]
	v_pk_fma_f32 v[4:5], v[124:125], v[124:125], v[4:5]
	v_pk_fma_f32 v[6:7], v[132:133], v[132:133], v[6:7]
	v_and_b32_e32 v91, 0xffff0000, v34
	v_pk_add_f32 v[4:5], v[4:5], v[6:7]
	v_and_b32_e32 v90, 0xffff0000, v30
	v_and_b32_e32 v99, 0xffff0000, v35
	v_and_b32_e32 v98, 0xffff0000, v31
	v_pk_add_f32 v[2:3], v[2:3], v[4:5]
	v_lshlrev_b32_e32 v89, 16, v34
	v_lshlrev_b32_e32 v88, 16, v30
	v_lshlrev_b32_e32 v95, 16, v35
; __device__ __forceinline__ void unpack8(const u32x4 w, f32x4& a, f32x4& c) { a = (f32x4){bf_lo(w.x), bf_hi(w.x), bf_lo(w.y), bf_hi(w.y)}; c = (f32x4){bf_lo(w.z), bf_hi(w.z), bf_lo(w.w), bf_hi(w.w)}; }
; template <bool X_F32> __device__ __forceinline__ void phase_norm_mod(const Ctx& C, const void* xin, const float* modl, int shift_idx, int scale_idx) {
;     ...
;             for (int r = 0; r < NR; ++r) { s[r] = 0.f;
; #pragma unroll
;                 for (int j = 0; j < 2; ++j) { f32x4 t0, t1; unpack8(raw[r][j], t0, t1);
;                     s[r] += ((t0.x * t0.x + t0.y * t0.y) + (t0.z * t0.z + t0.w * t0.w)) + ((t1.x * t1.x + t1.y * t1.y) + (t1.z * t1.z + t1.w * t1.w)); } }
;             wave_sumN<NR>(s);
	v_lshlrev_b32_e32 v94, 16, v31
	v_pk_mul_f32 v[4:5], v[90:91], v[90:91]
	v_pk_mul_f32 v[6:7], v[98:99], v[98:99]
	v_and_b32_e32 v97, 0xffff0000, v36
	v_and_b32_e32 v96, 0xffff0000, v32
	v_and_b32_e32 v103, 0xffff0000, v37
	v_and_b32_e32 v102, 0xffff0000, v33
	v_pk_fma_f32 v[4:5], v[88:89], v[88:89], v[4:5]
	v_pk_fma_f32 v[6:7], v[94:95], v[94:95], v[6:7]
	v_lshlrev_b32_e32 v93, 16, v36
	v_lshlrev_b32_e32 v92, 16, v32
	v_lshlrev_b32_e32 v101, 16, v37
	v_lshlrev_b32_e32 v100, 16, v33
	v_pk_add_f32 v[4:5], v[4:5], v[6:7]
	v_pk_mul_f32 v[6:7], v[96:97], v[96:97]
	v_pk_mul_f32 v[8:9], v[102:103], v[102:103]
	v_pk_fma_f32 v[6:7], v[92:93], v[92:93], v[6:7]
	v_pk_fma_f32 v[8:9], v[100:101], v[100:101], v[8:9]
	v_and_b32_e32 v73, 0xffff0000, v42
	v_pk_add_f32 v[6:7], v[6:7], v[8:9]
	v_and_b32_e32 v72, 0xffff0000, v38
	v_pk_add_f32 v[4:5], v[4:5], v[6:7]
	v_and_b32_e32 v83, 0xffff0000, v43
	v_and_b32_e32 v82, 0xffff0000, v39
	v_add_f32_e32 v2, v2, v3
	v_add_f32_e32 v3, v4, v5
	v_lshlrev_b32_e32 v71, 16, v42
	v_lshlrev_b32_e32 v70, 16, v38
	v_lshlrev_b32_e32 v77, 16, v43
	v_lshlrev_b32_e32 v76, 16, v39
	v_pk_mul_f32 v[4:5], v[72:73], v[72:73]
	v_pk_mul_f32 v[6:7], v[82:83], v[82:83]
	v_and_b32_e32 v79, 0xffff0000, v44
	v_and_b32_e32 v78, 0xffff0000, v40
	v_and_b32_e32 v87, 0xffff0000, v45
	v_and_b32_e32 v86, 0xffff0000, v41
	v_pk_fma_f32 v[4:5], v[70:71], v[70:71], v[4:5]
	v_pk_fma_f32 v[6:7], v[76:77], v[76:77], v[6:7]
	v_lshlrev_b32_e32 v75, 16, v44
	v_lshlrev_b32_e32 v74, 16, v40
	v_lshlrev_b32_e32 v85, 16, v45
	v_lshlrev_b32_e32 v84, 16, v41
	v_pk_add_f32 v[4:5], v[4:5], v[6:7]
	v_pk_mul_f32 v[6:7], v[78:79], v[78:79]
	v_pk_mul_f32 v[8:9], v[86:87], v[86:87]
	v_pk_fma_f32 v[6:7], v[74:75], v[74:75], v[6:7]
	v_pk_fma_f32 v[8:9], v[84:85], v[84:85], v[8:9]
	v_and_b32_e32 v57, 0xffff0000, v50
	v_pk_add_f32 v[6:7], v[6:7], v[8:9]
	v_and_b32_e32 v56, 0xffff0000, v46
	v_and_b32_e32 v65, 0xffff0000, v51
	v_and_b32_e32 v64, 0xffff0000, v47
	v_pk_add_f32 v[4:5], v[4:5], v[6:7]
	v_lshlrev_b32_e32 v55, 16, v50
	v_lshlrev_b32_e32 v54, 16, v46
	v_lshlrev_b32_e32 v61, 16, v51
	v_lshlrev_b32_e32 v60, 16, v47
	v_pk_mul_f32 v[6:7], v[56:57], v[56:57]
	v_pk_mul_f32 v[8:9], v[64:65], v[64:65]
	v_and_b32_e32 v63, 0xffff0000, v52
	v_and_b32_e32 v62, 0xffff0000, v48
	v_and_b32_e32 v69, 0xffff0000, v53
	v_and_b32_e32 v68, 0xffff0000, v49
	v_pk_fma_f32 v[6:7], v[54:55], v[54:55], v[6:7]
	v_pk_fma_f32 v[8:9], v[60:61], v[60:61], v[8:9]
	v_lshlrev_b32_e32 v59, 16, v52
	v_lshlrev_b32_e32 v58, 16, v48
	v_lshlrev_b32_e32 v67, 16, v53
	v_lshlrev_b32_e32 v66, 16, v49
	v_pk_add_f32 v[6:7], v[6:7], v[8:9]
	v_pk_mul_f32 v[8:9], v[62:63], v[62:63]
	v_pk_mul_f32 v[10:11], v[68:69], v[68:69]
	v_pk_fma_f32 v[8:9], v[58:59], v[58:59], v[8:9]
	v_pk_fma_f32 v[10:11], v[66:67], v[66:67], v[10:11]
	v_and_b32_e32 v41, 0xffff0000, v108
	v_pk_add_f32 v[8:9], v[8:9], v[10:11]
	v_and_b32_e32 v40, 0xffff0000, v104
	v_pk_add_f32 v[6:7], v[6:7], v[8:9]
	v_and_b32_e32 v49, 0xffff0000, v109
	v_and_b32_e32 v48, 0xffff0000, v105
	v_add_f32_e32 v4, v4, v5
	v_add_f32_e32 v5, v6, v7
	v_lshlrev_b32_e32 v39, 16, v108
	v_lshlrev_b32_e32 v38, 16, v104
	v_lshlrev_b32_e32 v45, 16, v109
	v_lshlrev_b32_e32 v44, 16, v105
	v_pk_mul_f32 v[6:7], v[40:41], v[40:41]
	v_pk_mul_f32 v[8:9], v[48:49], v[48:49]
	v_and_b32_e32 v47, 0xffff0000, v110
	v_and_b32_e32 v46, 0xffff0000, v106
	v_and_b32_e32 v53, 0xffff0000, v111
	v_and_b32_e32 v52, 0xffff0000, v107
	v_pk_fma_f32 v[6:7], v[38:39], v[38:39], v[6:7]
	v_pk_fma_f32 v[8:9], v[44:45], v[44:45], v[8:9]
	v_lshlrev_b32_e32 v43, 16, v110
	v_lshlrev_b32_e32 v42, 16, v106
	v_lshlrev_b32_e32 v51, 16, v111
	v_lshlrev_b32_e32 v50, 16, v107
	v_pk_add_f32 v[6:7], v[6:7], v[8:9]
	v_pk_mul_f32 v[8:9], v[46:47], v[46:47]
	v_pk_mul_f32 v[10:11], v[52:53], v[52:53]
	v_pk_fma_f32 v[8:9], v[42:43], v[42:43], v[8:9]
	v_pk_fma_f32 v[10:11], v[50:51], v[50:51], v[10:11]
	v_and_b32_e32 v25, 0xffff0000, v116
	v_pk_add_f32 v[8:9], v[8:9], v[10:11]
	v_and_b32_e32 v24, 0xffff0000, v112
	v_and_b32_e32 v33, 0xffff0000, v117
	v_and_b32_e32 v32, 0xffff0000, v113
	v_pk_add_f32 v[6:7], v[6:7], v[8:9]
	v_lshlrev_b32_e32 v23, 16, v116
	v_lshlrev_b32_e32 v22, 16, v112
	v_lshlrev_b32_e32 v29, 16, v117
	v_lshlrev_b32_e32 v28, 16, v113
	v_pk_mul_f32 v[8:9], v[24:25], v[24:25]
	v_pk_mul_f32 v[10:11], v[32:33], v[32:33]
	v_and_b32_e32 v31, 0xffff0000, v118
	v_and_b32_e32 v30, 0xffff0000, v114
	v_and_b32_e32 v37, 0xffff0000, v119
	v_and_b32_e32 v36, 0xffff0000, v115
	v_pk_fma_f32 v[8:9], v[22:23], v[22:23], v[8:9]
	v_pk_fma_f32 v[10:11], v[28:29], v[28:29], v[10:11]
	v_lshlrev_b32_e32 v27, 16, v118
	v_lshlrev_b32_e32 v26, 16, v114
	v_lshlrev_b32_e32 v35, 16, v119
	v_lshlrev_b32_e32 v34, 16, v115
	v_pk_add_f32 v[8:9], v[8:9], v[10:11]
	v_pk_mul_f32 v[10:11], v[30:31], v[30:31]
	v_pk_mul_f32 v[12:13], v[36:37], v[36:37]
	v_pk_fma_f32 v[10:11], v[26:27], v[26:27], v[10:11]
	v_pk_fma_f32 v[12:13], v[34:35], v[34:35], v[12:13]
	v_add_f32_e32 v6, v6, v7
	v_pk_add_f32 v[10:11], v[10:11], v[12:13]
	ds_bpermute_b32 v12, v180, v4
	v_pk_add_f32 v[8:9], v[8:9], v[10:11]
	ds_bpermute_b32 v10, v180, v2
	v_add_f32_e32 v7, v8, v9
	ds_bpermute_b32 v8, v180, v0
	ds_bpermute_b32 v9, v180, v1
	ds_bpermute_b32 v11, v180, v3
	ds_bpermute_b32 v13, v180, v5
	ds_bpermute_b32 v14, v180, v6
	ds_bpermute_b32 v15, v180, v7
	s_waitcnt lgkmcnt(0)
	v_add_f32_e32 v0, v0, v8
	s_waitcnt lgkmcnt(4)
	v_add_f32_e32 v1, v1, v9
	ds_bpermute_b32 v8, v181, v0
	v_add_f32_e32 v2, v2, v10
	s_waitcnt lgkmcnt(4)
	v_add_f32_e32 v3, v3, v11
	v_add_f32_e32 v4, v4, v12
	s_waitcnt lgkmcnt(3)
	v_add_f32_e32 v5, v5, v13
	s_waitcnt lgkmcnt(2)
; template <int NR> __device__ __forceinline__ void wave_sumN(float (&s)[NR]) {
; #pragma unroll
;     for (int o = 1; o < 64; o <<= 1) {
;         float t[NR];
; #pragma unroll
;         for (int r = 0; r < NR; ++r) t[r] = __shfl_xor(s[r], o);
; #pragma unroll
;         for (int r = 0; r < NR; ++r) s[r] += t[r];
;     }
; }
; template <bool X_F32> __device__ __forceinline__ void phase_norm_mod(const Ctx& C, const void* xin, const float* modl, int shift_idx, int scale_idx) {
;     ...
;             f32x4 a[4], g[4];
; #pragma unroll
;             for (int j = 0; j < 2; ++j)
; #pragma unroll
;                 for (int q = 0; q < 2; ++q) { a[2 * j + q] = *(const f32x4*)(modl + (size_t)b * NMOD + shift_idx * DM + 512 * j + 8 * lane + 4 * q);
;                     g[2 * j + q] = *(const f32x4*)(modl + (size_t)b * NMOD + scale_idx * DM + 512 * j + 8 * lane + 4 * q) + 1.0f; }
	v_add_f32_e32 v6, v6, v14
	s_waitcnt lgkmcnt(1)
	v_add_f32_e32 v7, v7, v15
	ds_bpermute_b32 v9, v181, v1
	ds_bpermute_b32 v10, v181, v2
	ds_bpermute_b32 v11, v181, v3
	ds_bpermute_b32 v12, v181, v4
	ds_bpermute_b32 v13, v181, v5
	ds_bpermute_b32 v14, v181, v6
	ds_bpermute_b32 v15, v181, v7
	s_waitcnt lgkmcnt(7)
	v_add_f32_e32 v0, v0, v8
	s_waitcnt lgkmcnt(6)
	v_add_f32_e32 v1, v1, v9
	ds_bpermute_b32 v8, v182, v0
	s_waitcnt lgkmcnt(6)
	v_add_f32_e32 v2, v2, v10
	s_waitcnt lgkmcnt(5)
	v_add_f32_e32 v3, v3, v11
	s_waitcnt lgkmcnt(4)
	v_add_f32_e32 v4, v4, v12
	s_waitcnt lgkmcnt(3)
	v_add_f32_e32 v5, v5, v13
	s_waitcnt lgkmcnt(2)
	v_add_f32_e32 v6, v6, v14
	s_waitcnt lgkmcnt(1)
	v_add_f32_e32 v7, v7, v15
	ds_bpermute_b32 v9, v182, v1
	ds_bpermute_b32 v10, v182, v2
	ds_bpermute_b32 v11, v182, v3
	ds_bpermute_b32 v12, v182, v4
	ds_bpermute_b32 v13, v182, v5
	ds_bpermute_b32 v14, v182, v6
	ds_bpermute_b32 v15, v182, v7
	s_waitcnt lgkmcnt(7)
	v_add_f32_e32 v0, v0, v8
	s_waitcnt lgkmcnt(6)
	v_add_f32_e32 v1, v1, v9
	ds_bpermute_b32 v8, v183, v0
	s_waitcnt lgkmcnt(6)
	v_add_f32_e32 v2, v2, v10
	s_waitcnt lgkmcnt(5)
	v_add_f32_e32 v3, v3, v11
	s_waitcnt lgkmcnt(4)
	v_add_f32_e32 v4, v4, v12
	s_waitcnt lgkmcnt(3)
	v_add_f32_e32 v5, v5, v13
	s_waitcnt lgkmcnt(2)
	v_add_f32_e32 v6, v6, v14
	s_waitcnt lgkmcnt(1)
	v_add_f32_e32 v7, v7, v15
	ds_bpermute_b32 v9, v183, v1
	ds_bpermute_b32 v10, v183, v2
	ds_bpermute_b32 v11, v183, v3
	ds_bpermute_b32 v12, v183, v4
	ds_bpermute_b32 v13, v183, v5
	ds_bpermute_b32 v14, v183, v6
	ds_bpermute_b32 v15, v183, v7
	s_waitcnt lgkmcnt(7)
	v_add_f32_e32 v0, v0, v8
	s_waitcnt lgkmcnt(6)
	v_add_f32_e32 v1, v1, v9
	ds_bpermute_b32 v8, v184, v0
	s_waitcnt lgkmcnt(6)
	v_add_f32_e32 v2, v2, v10
	s_waitcnt lgkmcnt(5)
	v_add_f32_e32 v3, v3, v11
	s_waitcnt lgkmcnt(4)
	v_add_f32_e32 v4, v4, v12
	s_waitcnt lgkmcnt(3)
	v_add_f32_e32 v5, v5, v13
	s_waitcnt lgkmcnt(2)
	v_add_f32_e32 v6, v6, v14
	s_waitcnt lgkmcnt(1)
	v_add_f32_e32 v7, v7, v15
	ds_bpermute_b32 v9, v184, v1
	ds_bpermute_b32 v10, v184, v2
	ds_bpermute_b32 v11, v184, v3
	ds_bpermute_b32 v12, v184, v4
	ds_bpermute_b32 v13, v184, v5
	ds_bpermute_b32 v14, v184, v6
	ds_bpermute_b32 v15, v184, v7
	s_waitcnt lgkmcnt(7)
	v_add_f32_e32 v0, v0, v8
	s_waitcnt lgkmcnt(6)
	v_add_f32_e32 v1, v1, v9
	ds_bpermute_b32 v8, v185, v0
	s_waitcnt lgkmcnt(6)
	v_add_f32_e32 v2, v2, v10
	s_waitcnt lgkmcnt(5)
	v_add_f32_e32 v3, v3, v11
	s_waitcnt lgkmcnt(4)
	v_add_f32_e32 v4, v4, v12
	s_waitcnt lgkmcnt(3)
	v_add_f32_e32 v5, v5, v13
	s_waitcnt lgkmcnt(2)
	v_add_f32_e32 v6, v6, v14
	s_waitcnt lgkmcnt(1)
	v_add_f32_e32 v7, v7, v15
	ds_bpermute_b32 v9, v185, v1
	ds_bpermute_b32 v10, v185, v2
	ds_bpermute_b32 v11, v185, v3
	ds_bpermute_b32 v12, v185, v4
	ds_bpermute_b32 v13, v185, v5
	ds_bpermute_b32 v14, v185, v6
	ds_bpermute_b32 v15, v185, v7
	v_lshl_add_u64 v[104:105], v[18:19], 2, s[2:3]
	s_waitcnt lgkmcnt(7)
	v_add_f32_e32 v80, v0, v8
	v_add_co_u32_e32 v0, vcc, s19, v104
	s_waitcnt lgkmcnt(6)
	v_add_f32_e32 v192, v1, v9
	v_addc_co_u32_e32 v1, vcc, 0, v105, vcc
	s_waitcnt lgkmcnt(5)
	v_add_f32_e32 v191, v2, v10
	s_waitcnt lgkmcnt(4)
	v_add_f32_e32 v190, v3, v11
	s_waitcnt lgkmcnt(3)
	v_add_f32_e32 v189, v4, v12
	s_waitcnt lgkmcnt(2)
	v_add_f32_e32 v188, v5, v13
	s_waitcnt lgkmcnt(1)
	v_add_f32_e32 v187, v6, v14
	s_waitcnt lgkmcnt(0)
	v_add_f32_e32 v186, v7, v15
	v_lshl_add_u64 v[106:107], v[104:105], 0, s[90:91]
	global_load_dwordx4 v[4:7], v[104:105], off offset:16
	global_load_dwordx4 v[12:15], v[104:105], off
	s_nop 0
	global_load_dwordx4 v[0:3], v[0:1], off
	s_nop 0
	global_load_dwordx4 v[8:11], v[106:107], off offset:16
	v_fmamk_f32 v80, v80, 0x3a800000, v214
	v_cmp_gt_f32_e32 vcc, s51, v80
	v_mul_f32_e32 v193, 0x4f800000, v80
	v_mov_b32_e32 v201, v160
	v_cndmask_b32_e32 v80, v80, v193, vcc
	v_sqrt_f32_e32 v193, v80
	v_mov_b32_e32 v203, v178
	v_mov_b32_e32 v160, v157
	v_mov_b32_e32 v178, v177
	v_mov_b32_e32 v200, v156
	v_mov_b32_e32 v202, v176
	s_waitcnt vmcnt(1)
	v_pk_add_f32 v[116:117], v[2:3], 1.0 op_sel_hi:[1,0]
	v_pk_add_f32 v[118:119], v[0:1], 1.0 op_sel_hi:[1,0]
	s_waitcnt vmcnt(0)
	v_pk_add_f32 v[112:113], v[10:11], 1.0 op_sel_hi:[1,0]
	v_pk_add_f32 v[114:115], v[8:9], 1.0 op_sel_hi:[1,0]
	global_load_dwordx4 v[0:3], v[104:105], off offset:2064
	global_load_dwordx4 v[8:11], v[104:105], off offset:2048
	global_load_dwordx4 v[194:197], v[106:107], off offset:2064
	s_nop 0
	global_load_dwordx4 v[104:107], v[106:107], off offset:2048
	s_waitcnt vmcnt(0)
; __device__ __forceinline__ unsigned pk2(float lo, float hi) { return pg8::cvt_pk_bf16(lo, hi); }
; __device__ __forceinline__ void unpack8(const u32x4 w, f32x4& a, f32x4& c) { a = (f32x4){bf_lo(w.x), bf_hi(w.x), bf_lo(w.y), bf_hi(w.y)}; c = (f32x4){bf_lo(w.z), bf_hi(w.z), bf_lo(w.w), bf_hi(w.w)}; }
; template <bool X_F32> __device__ __forceinline__ void phase_norm_mod(const Ctx& C, const void* xin, const float* modl, int shift_idx, int scale_idx) {
;     ...
; #pragma unroll
;             for (int r = 0; r < NR; ++r) { const float rs = 1.0f / sqrtf(s[r] * (1.f / DM) + EPS);
; #pragma unroll
;                 for (int j = 0; j < 2; ++j) { f32x4 t0, t1; unpack8(raw[r][j], t0, t1);
;                     const f32x4 y0 = t0 * rs * g[2 * j] + a[2 * j], y1 = t1 * rs * g[2 * j + 1] + a[2 * j + 1];
;                     u32x4 w; w.x = pk2(y0.x, y0.y); w.y = pk2(y0.z, y0.w); w.z = pk2(y1.x, y1.y); w.w = pk2(y1.z, y1.w);
;                     ((u32x4*)(H + (size_t)(m0 + r) * DM + 512 * j))[lane] = w; } }
	v_pk_add_f32 v[108:109], v[106:107], 1.0 op_sel_hi:[1,0]
	v_pk_add_f32 v[106:107], v[194:195], 1.0 op_sel_hi:[1,0]
	v_add_u32_e32 v194, -1, v193
	v_fma_f32 v195, -v194, v193, v80
	v_cmp_ge_f32_e64 s[36:37], 0, v195
	v_add_u32_e32 v195, 1, v193
	v_pk_add_f32 v[110:111], v[104:105], 1.0 op_sel_hi:[1,0]
	v_cndmask_b32_e64 v194, v193, v194, s[36:37]
	v_fma_f32 v193, -v195, v193, v80
	v_cmp_lt_f32_e64 s[36:37], 0, v193
	v_pk_add_f32 v[104:105], v[196:197], 1.0 op_sel_hi:[1,0]
	s_nop 0
	v_cndmask_b32_e64 v193, v194, v195, s[36:37]
	v_mul_f32_e32 v194, 0x37800000, v193
	v_cndmask_b32_e32 v193, v193, v194, vcc
	v_cmp_class_f32_e32 vcc, v80, v215
	s_nop 1
	v_cndmask_b32_e32 v80, v193, v80, vcc
	v_div_scale_f32 v193, s[2:3], v80, v80, 1.0
	v_rcp_f32_e32 v194, v193
	s_nop 0
	v_fma_f32 v195, -v193, v194, 1.0
	v_fmac_f32_e32 v194, v195, v194
	v_div_scale_f32 v195, vcc, 1.0, v80, 1.0
	v_mul_f32_e32 v196, v195, v194
	v_fma_f32 v197, -v193, v196, v195
	v_fmac_f32_e32 v196, v197, v194
	v_fma_f32 v193, -v193, v196, v195
	v_div_fmas_f32 v193, v193, v194, v196
	v_div_fixup_f32 v80, v193, v80, 1.0
	v_mov_b32_e32 v195, v154
	v_mov_b32_e32 v197, v174
	v_mov_b32_e32 v154, v153
	v_mov_b32_e32 v174, v159
	v_mov_b32_e32 v194, v152
	v_mov_b32_e32 v196, v158
	v_pk_mul_f32 v[152:153], v[80:81], v[154:155] op_sel_hi:[0,1]
	v_pk_mul_f32 v[154:155], v[80:81], v[174:175] op_sel_hi:[0,1]
	v_pk_mul_f32 v[156:157], v[80:81], v[160:161] op_sel_hi:[0,1]
	v_pk_mul_f32 v[158:159], v[80:81], v[178:179] op_sel_hi:[0,1]
	v_pk_fma_f32 v[154:155], v[154:155], v[108:109], v[10:11]
	v_pk_fma_f32 v[152:153], v[152:153], v[110:111], v[8:9]
	v_pk_fma_f32 v[158:159], v[158:159], v[104:105], v[2:3]
	v_pk_fma_f32 v[156:157], v[156:157], v[106:107], v[0:1]
	v_pk_mul_f32 v[194:195], v[80:81], v[194:195] op_sel_hi:[0,1]
	v_pk_mul_f32 v[196:197], v[80:81], v[196:197] op_sel_hi:[0,1]
	v_pk_mul_f32 v[200:201], v[80:81], v[200:201] op_sel_hi:[0,1]
	v_pk_mul_f32 v[202:203], v[80:81], v[202:203] op_sel_hi:[0,1]
	v_cvt_pk_bf16_f32 v152, v152, v153
	v_cvt_pk_bf16_f32 v153, v154, v155
	v_cvt_pk_bf16_f32 v154, v156, v157
	v_cvt_pk_bf16_f32 v155, v158, v159
	v_fmamk_f32 v80, v192, 0x3a800000, v214
	flat_store_dwordx4 v[198:199], v[152:155] offset:1024
	v_cmp_gt_f32_e32 vcc, s51, v80
	v_mov_b32_e32 v159, v144
	v_mul_f32_e32 v152, 0x4f800000, v80
	v_cndmask_b32_e32 v80, v80, v152, vcc
	v_sqrt_f32_e32 v152, v80
	v_mov_b32_e32 v161, v150
	v_mov_b32_e32 v144, v141
	v_mov_b32_e32 v150, v149
	v_add_u32_e32 v153, -1, v152
	v_fma_f32 v154, -v153, v152, v80
	v_cmp_ge_f32_e64 s[36:37], 0, v154
	v_add_u32_e32 v154, 1, v152
	v_mov_b32_e32 v158, v140
	v_cndmask_b32_e64 v153, v152, v153, s[36:37]
	v_fma_f32 v152, -v154, v152, v80
	v_cmp_lt_f32_e64 s[36:37], 0, v152
	v_mov_b32_e32 v160, v148
	v_pk_fma_f32 v[196:197], v[196:197], v[116:117], v[14:15]
	v_cndmask_b32_e64 v152, v153, v154, s[36:37]
	v_mul_f32_e32 v153, 0x37800000, v152
	v_cndmask_b32_e32 v152, v152, v153, vcc
	v_cmp_class_f32_e32 vcc, v80, v215
	v_pk_fma_f32 v[194:195], v[194:195], v[118:119], v[12:13]
	v_pk_fma_f32 v[202:203], v[202:203], v[112:113], v[6:7]
	v_cndmask_b32_e32 v80, v152, v80, vcc
	v_div_scale_f32 v152, s[2:3], v80, v80, 1.0
	v_rcp_f32_e32 v153, v152
	v_pk_fma_f32 v[200:201], v[200:201], v[114:115], v[4:5]
	v_cvt_pk_bf16_f32 v194, v194, v195
	v_cvt_pk_bf16_f32 v195, v196, v197
	v_fma_f32 v154, -v152, v153, 1.0
	v_fmac_f32_e32 v153, v154, v153
	v_div_scale_f32 v154, vcc, 1.0, v80, 1.0
	v_mul_f32_e32 v155, v154, v153
	v_fma_f32 v156, -v152, v155, v154
	v_fmac_f32_e32 v155, v156, v153
	v_fma_f32 v152, -v152, v155, v154
	v_div_fmas_f32 v152, v152, v153, v155
	v_div_fixup_f32 v80, v152, v80, 1.0
	v_mov_b32_e32 v153, v138
	v_mov_b32_e32 v155, v146
	v_mov_b32_e32 v138, v137
	v_mov_b32_e32 v146, v143
	v_mov_b32_e32 v152, v136
	v_mov_b32_e32 v154, v142
	v_pk_mul_f32 v[136:137], v[80:81], v[138:139] op_sel_hi:[0,1]
	v_pk_mul_f32 v[138:139], v[80:81], v[146:147] op_sel_hi:[0,1]
	v_pk_mul_f32 v[140:141], v[80:81], v[144:145] op_sel_hi:[0,1]
	v_pk_mul_f32 v[142:143], v[80:81], v[150:151] op_sel_hi:[0,1]
	v_pk_fma_f32 v[138:139], v[138:139], v[108:109], v[10:11]
	v_pk_fma_f32 v[136:137], v[136:137], v[110:111], v[8:9]
	v_pk_fma_f32 v[142:143], v[142:143], v[104:105], v[2:3]
	v_pk_fma_f32 v[140:141], v[140:141], v[106:107], v[0:1]
	v_lshl_add_u64 v[156:157], v[20:21], 0, s[14:15]
	v_pk_mul_f32 v[152:153], v[80:81], v[152:153] op_sel_hi:[0,1]
	v_pk_mul_f32 v[154:155], v[80:81], v[154:155] op_sel_hi:[0,1]
	v_pk_mul_f32 v[158:159], v[80:81], v[158:159] op_sel_hi:[0,1]
	v_pk_mul_f32 v[160:161], v[80:81], v[160:161] op_sel_hi:[0,1]
	v_cvt_pk_bf16_f32 v136, v136, v137
	v_cvt_pk_bf16_f32 v137, v138, v139
	v_cvt_pk_bf16_f32 v138, v140, v141
	v_cvt_pk_bf16_f32 v139, v142, v143
	v_fmamk_f32 v80, v191, 0x3a800000, v214
	flat_store_dwordx4 v[156:157], v[136:139] offset:1024
	v_cmp_gt_f32_e32 vcc, s51, v80
	v_mov_b32_e32 v143, v128
	v_mul_f32_e32 v136, 0x4f800000, v80
	v_cndmask_b32_e32 v80, v80, v136, vcc
	v_sqrt_f32_e32 v136, v80
	v_mov_b32_e32 v145, v134
	v_mov_b32_e32 v128, v125
	v_mov_b32_e32 v134, v133
	v_add_u32_e32 v137, -1, v136
	v_fma_f32 v138, -v137, v136, v80
	v_cmp_ge_f32_e64 s[36:37], 0, v138
	v_add_u32_e32 v138, 1, v136
	v_mov_b32_e32 v142, v124
	v_cndmask_b32_e64 v137, v136, v137, s[36:37]
	v_fma_f32 v136, -v138, v136, v80
	v_cmp_lt_f32_e64 s[36:37], 0, v136
	v_mov_b32_e32 v144, v132
	v_pk_fma_f32 v[154:155], v[116:117], v[154:155], v[14:15]
	v_cndmask_b32_e64 v136, v137, v138, s[36:37]
	v_mul_f32_e32 v137, 0x37800000, v136
	v_cndmask_b32_e32 v136, v136, v137, vcc
	v_cmp_class_f32_e32 vcc, v80, v215
	v_pk_fma_f32 v[152:153], v[118:119], v[152:153], v[12:13]
; __device__ __forceinline__ unsigned pk2(float lo, float hi) { return pg8::cvt_pk_bf16(lo, hi); }
; __device__ __forceinline__ void unpack8(const u32x4 w, f32x4& a, f32x4& c) { a = (f32x4){bf_lo(w.x), bf_hi(w.x), bf_lo(w.y), bf_hi(w.y)}; c = (f32x4){bf_lo(w.z), bf_hi(w.z), bf_lo(w.w), bf_hi(w.w)}; }
; template <bool X_F32> __device__ __forceinline__ void phase_norm_mod(const Ctx& C, const void* xin, const float* modl, int shift_idx, int scale_idx) {
;     ...
; #pragma unroll
;             for (int r = 0; r < NR; ++r) { const float rs = 1.0f / sqrtf(s[r] * (1.f / DM) + EPS);
; #pragma unroll
;                 for (int j = 0; j < 2; ++j) { f32x4 t0, t1; unpack8(raw[r][j], t0, t1);
;                     const f32x4 y0 = t0 * rs * g[2 * j] + a[2 * j], y1 = t1 * rs * g[2 * j + 1] + a[2 * j + 1];
;                     u32x4 w; w.x = pk2(y0.x, y0.y); w.y = pk2(y0.z, y0.w); w.z = pk2(y1.x, y1.y); w.w = pk2(y1.z, y1.w);
;                     ((u32x4*)(H + (size_t)(m0 + r) * DM + 512 * j))[lane] = w; } }
	v_pk_fma_f32 v[160:161], v[160:161], v[112:113], v[6:7]
	v_cndmask_b32_e32 v80, v136, v80, vcc
	v_div_scale_f32 v136, s[2:3], v80, v80, 1.0
	v_rcp_f32_e32 v137, v136
	v_pk_fma_f32 v[158:159], v[158:159], v[114:115], v[4:5]
	v_cvt_pk_bf16_f32 v196, v200, v201
	v_cvt_pk_bf16_f32 v197, v202, v203
	v_fma_f32 v138, -v136, v137, 1.0
	v_fmac_f32_e32 v137, v138, v137
	v_div_scale_f32 v138, vcc, 1.0, v80, 1.0
	v_mul_f32_e32 v139, v138, v137
	v_fma_f32 v140, -v136, v139, v138
	v_fmac_f32_e32 v139, v140, v137
	v_fma_f32 v136, -v136, v139, v138
	v_div_fmas_f32 v136, v136, v137, v139
	v_div_fixup_f32 v80, v136, v80, 1.0
	v_mov_b32_e32 v137, v122
	v_mov_b32_e32 v139, v130
	v_mov_b32_e32 v122, v121
	v_mov_b32_e32 v130, v127
	v_mov_b32_e32 v136, v120
	v_mov_b32_e32 v138, v126
	v_pk_mul_f32 v[120:121], v[80:81], v[122:123] op_sel_hi:[0,1]
	v_pk_mul_f32 v[122:123], v[80:81], v[130:131] op_sel_hi:[0,1]
	v_pk_mul_f32 v[124:125], v[80:81], v[128:129] op_sel_hi:[0,1]
	v_pk_mul_f32 v[126:127], v[80:81], v[134:135] op_sel_hi:[0,1]
	v_pk_fma_f32 v[122:123], v[122:123], v[108:109], v[10:11]
	v_pk_fma_f32 v[120:121], v[120:121], v[110:111], v[8:9]
	v_pk_fma_f32 v[126:127], v[126:127], v[104:105], v[2:3]
	v_pk_fma_f32 v[124:125], v[124:125], v[106:107], v[0:1]
	v_lshl_add_u64 v[140:141], v[20:21], 0, s[4:5]
	v_pk_mul_f32 v[136:137], v[80:81], v[136:137] op_sel_hi:[0,1]
	v_pk_mul_f32 v[138:139], v[80:81], v[138:139] op_sel_hi:[0,1]
	v_pk_mul_f32 v[142:143], v[80:81], v[142:143] op_sel_hi:[0,1]
	v_pk_mul_f32 v[144:145], v[80:81], v[144:145] op_sel_hi:[0,1]
	v_cvt_pk_bf16_f32 v120, v120, v121
	v_cvt_pk_bf16_f32 v121, v122, v123
	v_cvt_pk_bf16_f32 v122, v124, v125
	v_cvt_pk_bf16_f32 v123, v126, v127
	v_fmamk_f32 v80, v190, 0x3a800000, v214
	flat_store_dwordx4 v[140:141], v[120:123] offset:1024
	v_cmp_gt_f32_e32 vcc, s51, v80
	v_mov_b32_e32 v127, v96
	v_mul_f32_e32 v120, 0x4f800000, v80
	v_cndmask_b32_e32 v80, v80, v120, vcc
	v_sqrt_f32_e32 v120, v80
	v_mov_b32_e32 v129, v102
	v_mov_b32_e32 v96, v93
	v_mov_b32_e32 v102, v101
	v_add_u32_e32 v121, -1, v120
	v_fma_f32 v122, -v121, v120, v80
	v_cmp_ge_f32_e64 s[36:37], 0, v122
	v_add_u32_e32 v122, 1, v120
	v_mov_b32_e32 v126, v92
	v_cndmask_b32_e64 v121, v120, v121, s[36:37]
	v_fma_f32 v120, -v122, v120, v80
	v_cmp_lt_f32_e64 s[36:37], 0, v120
	v_mov_b32_e32 v128, v100
	v_pk_fma_f32 v[138:139], v[116:117], v[138:139], v[14:15]
	v_cndmask_b32_e64 v120, v121, v122, s[36:37]
	v_mul_f32_e32 v121, 0x37800000, v120
	v_cndmask_b32_e32 v120, v120, v121, vcc
	v_cmp_class_f32_e32 vcc, v80, v215
	v_pk_fma_f32 v[136:137], v[118:119], v[136:137], v[12:13]
	v_pk_fma_f32 v[144:145], v[144:145], v[112:113], v[6:7]
	v_cndmask_b32_e32 v80, v120, v80, vcc
	v_div_scale_f32 v120, s[2:3], v80, v80, 1.0
	v_rcp_f32_e32 v121, v120
	v_pk_fma_f32 v[142:143], v[142:143], v[114:115], v[4:5]
	v_cvt_pk_bf16_f32 v152, v152, v153
	v_cvt_pk_bf16_f32 v153, v154, v155
	v_fma_f32 v122, -v120, v121, 1.0
	v_fmac_f32_e32 v121, v122, v121
	v_div_scale_f32 v122, vcc, 1.0, v80, 1.0
	v_mul_f32_e32 v123, v122, v121
	v_fma_f32 v124, -v120, v123, v122
	v_fmac_f32_e32 v123, v124, v121
	v_fma_f32 v120, -v120, v123, v122
	v_div_fmas_f32 v120, v120, v121, v123
	v_div_fixup_f32 v80, v120, v80, 1.0
	v_mov_b32_e32 v121, v90
	v_mov_b32_e32 v123, v98
	v_mov_b32_e32 v90, v89
	v_mov_b32_e32 v98, v95
	v_mov_b32_e32 v120, v88
	v_mov_b32_e32 v122, v94
	v_pk_mul_f32 v[88:89], v[80:81], v[90:91] op_sel_hi:[0,1]
	v_pk_mul_f32 v[90:91], v[80:81], v[98:99] op_sel_hi:[0,1]
	v_pk_mul_f32 v[92:93], v[80:81], v[96:97] op_sel_hi:[0,1]
	v_pk_mul_f32 v[94:95], v[80:81], v[102:103] op_sel_hi:[0,1]
	v_pk_fma_f32 v[90:91], v[90:91], v[108:109], v[10:11]
	v_pk_fma_f32 v[88:89], v[88:89], v[110:111], v[8:9]
	v_pk_fma_f32 v[94:95], v[94:95], v[104:105], v[2:3]
	v_pk_fma_f32 v[92:93], v[92:93], v[106:107], v[0:1]
	v_lshl_add_u64 v[124:125], v[20:21], 0, s[46:47]
	v_pk_mul_f32 v[120:121], v[80:81], v[120:121] op_sel_hi:[0,1]
	v_pk_mul_f32 v[122:123], v[80:81], v[122:123] op_sel_hi:[0,1]
	v_pk_mul_f32 v[126:127], v[80:81], v[126:127] op_sel_hi:[0,1]
	v_pk_mul_f32 v[128:129], v[80:81], v[128:129] op_sel_hi:[0,1]
	v_cvt_pk_bf16_f32 v88, v88, v89
	v_cvt_pk_bf16_f32 v89, v90, v91
	v_cvt_pk_bf16_f32 v90, v92, v93
	v_cvt_pk_bf16_f32 v91, v94, v95
	v_fmamk_f32 v80, v189, 0x3a800000, v214
	flat_store_dwordx4 v[124:125], v[88:91] offset:1024
	v_cmp_gt_f32_e32 vcc, s51, v80
	v_mov_b32_e32 v95, v78
	v_mul_f32_e32 v88, 0x4f800000, v80
	v_cndmask_b32_e32 v80, v80, v88, vcc
	v_sqrt_f32_e32 v88, v80
	v_mov_b32_e32 v97, v86
	v_mov_b32_e32 v78, v75
	v_mov_b32_e32 v86, v85
	v_add_u32_e32 v89, -1, v88
	v_fma_f32 v90, -v89, v88, v80
	v_cmp_ge_f32_e64 s[36:37], 0, v90
	v_add_u32_e32 v90, 1, v88
	v_mov_b32_e32 v94, v74
	v_cndmask_b32_e64 v89, v88, v89, s[36:37]
	v_fma_f32 v88, -v90, v88, v80
	v_cmp_lt_f32_e64 s[36:37], 0, v88
	v_pk_fma_f32 v[122:123], v[116:117], v[122:123], v[14:15]
	v_pk_fma_f32 v[120:121], v[118:119], v[120:121], v[12:13]
	v_cndmask_b32_e64 v88, v89, v90, s[36:37]
	v_mul_f32_e32 v89, 0x37800000, v88
	v_cndmask_b32_e32 v88, v88, v89, vcc
	v_cmp_class_f32_e32 vcc, v80, v215
	v_mov_b32_e32 v96, v84
	v_pk_fma_f32 v[128:129], v[112:113], v[128:129], v[6:7]
	v_cndmask_b32_e32 v80, v88, v80, vcc
	v_div_scale_f32 v88, s[2:3], v80, v80, 1.0
	v_rcp_f32_e32 v89, v88
	v_pk_fma_f32 v[126:127], v[114:115], v[126:127], v[4:5]
	v_cvt_pk_bf16_f32 v154, v158, v159
	v_cvt_pk_bf16_f32 v155, v160, v161
	v_fma_f32 v90, -v88, v89, 1.0
	v_fmac_f32_e32 v89, v90, v89
	v_div_scale_f32 v90, vcc, 1.0, v80, 1.0
	v_mul_f32_e32 v91, v90, v89
	v_fma_f32 v92, -v88, v91, v90
	v_fmac_f32_e32 v91, v92, v89
	v_fma_f32 v88, -v88, v91, v90
; __device__ __forceinline__ unsigned pk2(float lo, float hi) { return pg8::cvt_pk_bf16(lo, hi); }
; __device__ __forceinline__ void unpack8(const u32x4 w, f32x4& a, f32x4& c) { a = (f32x4){bf_lo(w.x), bf_hi(w.x), bf_lo(w.y), bf_hi(w.y)}; c = (f32x4){bf_lo(w.z), bf_hi(w.z), bf_lo(w.w), bf_hi(w.w)}; }
; template <bool X_F32> __device__ __forceinline__ void phase_norm_mod(const Ctx& C, const void* xin, const float* modl, int shift_idx, int scale_idx) {
;     ...
; #pragma unroll
;             for (int r = 0; r < NR; ++r) { const float rs = 1.0f / sqrtf(s[r] * (1.f / DM) + EPS);
; #pragma unroll
;                 for (int j = 0; j < 2; ++j) { f32x4 t0, t1; unpack8(raw[r][j], t0, t1);
;                     const f32x4 y0 = t0 * rs * g[2 * j] + a[2 * j], y1 = t1 * rs * g[2 * j + 1] + a[2 * j + 1];
;                     u32x4 w; w.x = pk2(y0.x, y0.y); w.y = pk2(y0.z, y0.w); w.z = pk2(y1.x, y1.y); w.w = pk2(y1.z, y1.w);
;                     ((u32x4*)(H + (size_t)(m0 + r) * DM + 512 * j))[lane] = w; } }
	v_div_fmas_f32 v88, v88, v89, v91
	v_div_fixup_f32 v80, v88, v80, 1.0
	v_mov_b32_e32 v89, v72
	v_mov_b32_e32 v91, v82
	v_mov_b32_e32 v72, v71
	v_mov_b32_e32 v82, v77
	v_mov_b32_e32 v88, v70
	v_mov_b32_e32 v90, v76
	v_pk_mul_f32 v[70:71], v[80:81], v[72:73] op_sel_hi:[0,1]
	v_pk_mul_f32 v[72:73], v[80:81], v[82:83] op_sel_hi:[0,1]
	v_pk_mul_f32 v[74:75], v[80:81], v[78:79] op_sel_hi:[0,1]
	v_pk_mul_f32 v[76:77], v[80:81], v[86:87] op_sel_hi:[0,1]
	v_pk_fma_f32 v[72:73], v[72:73], v[108:109], v[10:11]
	v_pk_fma_f32 v[70:71], v[70:71], v[110:111], v[8:9]
	v_pk_fma_f32 v[76:77], v[76:77], v[104:105], v[2:3]
	v_pk_fma_f32 v[74:75], v[74:75], v[106:107], v[0:1]
	v_lshl_add_u64 v[92:93], v[20:21], 0, s[44:45]
	v_cvt_pk_bf16_f32 v70, v70, v71
	v_cvt_pk_bf16_f32 v71, v72, v73
	v_cvt_pk_bf16_f32 v72, v74, v75
	v_cvt_pk_bf16_f32 v73, v76, v77
	flat_store_dwordx4 v[92:93], v[70:73] offset:1024
	v_mov_b32_e32 v79, v62
	v_mov_b32_e32 v83, v68
	v_fmamk_f32 v70, v188, 0x3a800000, v214
	v_cmp_gt_f32_e32 vcc, s51, v70
	v_mul_f32_e32 v71, 0x4f800000, v70
	v_mov_b32_e32 v62, v59
	v_cndmask_b32_e32 v70, v70, v71, vcc
	v_sqrt_f32_e32 v71, v70
	v_mov_b32_e32 v68, v67
	v_mov_b32_e32 v78, v58
	v_lshl_add_u64 v[76:77], v[20:21], 0, s[42:43]
	v_add_u32_e32 v72, -1, v71
	v_fma_f32 v73, -v72, v71, v70
	v_cmp_ge_f32_e64 s[36:37], 0, v73
	v_add_u32_e32 v73, 1, v71
	v_pk_mul_f32 v[88:89], v[80:81], v[88:89] op_sel_hi:[0,1]
	v_cndmask_b32_e64 v72, v71, v72, s[36:37]
	v_fma_f32 v71, -v73, v71, v70
	v_cmp_lt_f32_e64 s[36:37], 0, v71
	v_pk_mul_f32 v[90:91], v[80:81], v[90:91] op_sel_hi:[0,1]
	v_pk_fma_f32 v[90:91], v[116:117], v[90:91], v[14:15]
	v_cndmask_b32_e64 v71, v72, v73, s[36:37]
	v_mul_f32_e32 v72, 0x37800000, v71
	v_cndmask_b32_e32 v71, v71, v72, vcc
	v_cmp_class_f32_e32 vcc, v70, v215
	v_pk_fma_f32 v[88:89], v[118:119], v[88:89], v[12:13]
	v_mov_b32_e32 v82, v66
	v_cndmask_b32_e32 v70, v71, v70, vcc
	v_div_scale_f32 v71, s[2:3], v70, v70, 1.0
	v_rcp_f32_e32 v72, v71
	v_pk_mul_f32 v[96:97], v[80:81], v[96:97] op_sel_hi:[0,1]
	v_pk_mul_f32 v[94:95], v[80:81], v[94:95] op_sel_hi:[0,1]
	v_pk_fma_f32 v[96:97], v[112:113], v[96:97], v[6:7]
	v_fma_f32 v73, -v71, v72, 1.0
	v_fmac_f32_e32 v72, v73, v72
	v_div_scale_f32 v73, vcc, 1.0, v70, 1.0
	v_mul_f32_e32 v74, v73, v72
	v_fma_f32 v75, -v71, v74, v73
	v_fmac_f32_e32 v74, v75, v72
	v_fma_f32 v71, -v71, v74, v73
	v_div_fmas_f32 v71, v71, v72, v74
	v_div_fixup_f32 v70, v71, v70, 1.0
	v_mov_b32_e32 v73, v56
	v_mov_b32_e32 v75, v64
	v_mov_b32_e32 v56, v55
	v_mov_b32_e32 v64, v61
	v_mov_b32_e32 v72, v54
	v_mov_b32_e32 v74, v60
	v_pk_mul_f32 v[54:55], v[70:71], v[56:57] op_sel_hi:[0,1]
	v_pk_mul_f32 v[56:57], v[70:71], v[64:65] op_sel_hi:[0,1]
	v_pk_mul_f32 v[58:59], v[70:71], v[62:63] op_sel_hi:[0,1]
	v_pk_mul_f32 v[60:61], v[70:71], v[68:69] op_sel_hi:[0,1]
	v_pk_fma_f32 v[56:57], v[108:109], v[56:57], v[10:11]
	v_pk_fma_f32 v[54:55], v[110:111], v[54:55], v[8:9]
	v_pk_fma_f32 v[60:61], v[60:61], v[104:105], v[2:3]
	v_pk_fma_f32 v[58:59], v[58:59], v[106:107], v[0:1]
	v_cvt_pk_bf16_f32 v54, v54, v55
	v_cvt_pk_bf16_f32 v55, v56, v57
	v_cvt_pk_bf16_f32 v56, v58, v59
	v_cvt_pk_bf16_f32 v57, v60, v61
	flat_store_dwordx4 v[76:77], v[54:57] offset:1024
	v_mov_b32_e32 v63, v46
	v_mov_b32_e32 v65, v52
	v_fmamk_f32 v54, v187, 0x3a800000, v214
	v_cmp_gt_f32_e32 vcc, s51, v54
	v_mul_f32_e32 v55, 0x4f800000, v54
	v_mov_b32_e32 v46, v43
	v_cndmask_b32_e32 v54, v54, v55, vcc
	v_sqrt_f32_e32 v55, v54
	v_mov_b32_e32 v52, v51
	v_mov_b32_e32 v62, v42
	v_lshl_add_u64 v[60:61], v[20:21], 0, s[40:41]
	v_add_u32_e32 v56, -1, v55
	v_fma_f32 v57, -v56, v55, v54
	v_cmp_ge_f32_e64 s[36:37], 0, v57
	v_add_u32_e32 v57, 1, v55
	v_pk_mul_f32 v[72:73], v[70:71], v[72:73] op_sel_hi:[0,1]
	v_cndmask_b32_e64 v56, v55, v56, s[36:37]
	v_fma_f32 v55, -v57, v55, v54
	v_cmp_lt_f32_e64 s[36:37], 0, v55
	v_pk_mul_f32 v[74:75], v[70:71], v[74:75] op_sel_hi:[0,1]
	v_pk_fma_f32 v[74:75], v[116:117], v[74:75], v[14:15]
	v_cndmask_b32_e64 v55, v56, v57, s[36:37]
	v_mul_f32_e32 v56, 0x37800000, v55
	v_cndmask_b32_e32 v55, v55, v56, vcc
	v_cmp_class_f32_e32 vcc, v54, v215
	v_pk_fma_f32 v[72:73], v[118:119], v[72:73], v[12:13]
	v_mov_b32_e32 v64, v50
	v_cndmask_b32_e32 v54, v55, v54, vcc
	v_div_scale_f32 v55, s[2:3], v54, v54, 1.0
	v_rcp_f32_e32 v56, v55
	v_pk_mul_f32 v[82:83], v[70:71], v[82:83] op_sel_hi:[0,1]
	v_pk_mul_f32 v[78:79], v[70:71], v[78:79] op_sel_hi:[0,1]
	v_pk_fma_f32 v[82:83], v[112:113], v[82:83], v[6:7]
	v_fma_f32 v57, -v55, v56, 1.0
	v_fmac_f32_e32 v56, v57, v56
	v_div_scale_f32 v57, vcc, 1.0, v54, 1.0
	v_mul_f32_e32 v58, v57, v56
	v_fma_f32 v59, -v55, v58, v57
	v_fmac_f32_e32 v58, v59, v56
	v_fma_f32 v55, -v55, v58, v57
	v_div_fmas_f32 v55, v55, v56, v58
	v_div_fixup_f32 v54, v55, v54, 1.0
	v_mov_b32_e32 v57, v40
	v_mov_b32_e32 v59, v48
	v_mov_b32_e32 v40, v39
; __device__ __forceinline__ unsigned pk2(float lo, float hi) { return pg8::cvt_pk_bf16(lo, hi); }
; __device__ __forceinline__ void unpack8(const u32x4 w, f32x4& a, f32x4& c) { a = (f32x4){bf_lo(w.x), bf_hi(w.x), bf_lo(w.y), bf_hi(w.y)}; c = (f32x4){bf_lo(w.z), bf_hi(w.z), bf_lo(w.w), bf_hi(w.w)}; }
; template <bool X_F32> __device__ __forceinline__ void phase_norm_mod(const Ctx& C, const void* xin, const float* modl, int shift_idx, int scale_idx) {
;     ...
; #pragma unroll
;             for (int r = 0; r < NR; ++r) { const float rs = 1.0f / sqrtf(s[r] * (1.f / DM) + EPS);
; #pragma unroll
;                 for (int j = 0; j < 2; ++j) { f32x4 t0, t1; unpack8(raw[r][j], t0, t1);
;                     const f32x4 y0 = t0 * rs * g[2 * j] + a[2 * j], y1 = t1 * rs * g[2 * j + 1] + a[2 * j + 1];
;                     u32x4 w; w.x = pk2(y0.x, y0.y); w.y = pk2(y0.z, y0.w); w.z = pk2(y1.x, y1.y); w.w = pk2(y1.z, y1.w);
;                     ((u32x4*)(H + (size_t)(m0 + r) * DM + 512 * j))[lane] = w; } }
;         }
	v_mov_b32_e32 v48, v45
	v_mov_b32_e32 v56, v38
	v_mov_b32_e32 v58, v44
	v_pk_mul_f32 v[38:39], v[54:55], v[40:41] op_sel_hi:[0,1]
	v_pk_mul_f32 v[40:41], v[54:55], v[48:49] op_sel_hi:[0,1]
	v_pk_mul_f32 v[42:43], v[54:55], v[46:47] op_sel_hi:[0,1]
	v_pk_mul_f32 v[44:45], v[54:55], v[52:53] op_sel_hi:[0,1]
	v_pk_fma_f32 v[40:41], v[108:109], v[40:41], v[10:11]
	v_pk_fma_f32 v[38:39], v[110:111], v[38:39], v[8:9]
	v_pk_fma_f32 v[44:45], v[44:45], v[104:105], v[2:3]
	v_pk_fma_f32 v[42:43], v[42:43], v[106:107], v[0:1]
	v_cvt_pk_bf16_f32 v38, v38, v39
	v_cvt_pk_bf16_f32 v39, v40, v41
	v_cvt_pk_bf16_f32 v40, v42, v43
	v_cvt_pk_bf16_f32 v41, v44, v45
	flat_store_dwordx4 v[60:61], v[38:41] offset:1024
	v_mov_b32_e32 v44, v28
	v_mov_b32_e32 v45, v32
	v_fmamk_f32 v38, v186, 0x3a800000, v214
	v_cmp_gt_f32_e32 vcc, s51, v38
	v_mul_f32_e32 v39, 0x4f800000, v38
	v_pk_mul_f32 v[56:57], v[54:55], v[56:57] op_sel_hi:[0,1]
	v_cndmask_b32_e32 v38, v38, v39, vcc
	v_sqrt_f32_e32 v39, v38
	v_pk_mul_f32 v[58:59], v[54:55], v[58:59] op_sel_hi:[0,1]
	v_pk_fma_f32 v[58:59], v[116:117], v[58:59], v[14:15]
	v_pk_fma_f32 v[56:57], v[118:119], v[56:57], v[12:13]
	v_add_u32_e32 v40, -1, v39
	v_fma_f32 v41, -v40, v39, v38
	v_cmp_ge_f32_e64 s[36:37], 0, v41
	v_add_u32_e32 v41, 1, v39
	v_pk_mul_f32 v[64:65], v[54:55], v[64:65] op_sel_hi:[0,1]
	v_cndmask_b32_e64 v40, v39, v40, s[36:37]
	v_fma_f32 v39, -v41, v39, v38
	v_cmp_lt_f32_e64 s[36:37], 0, v39
	v_pk_mul_f32 v[62:63], v[54:55], v[62:63] op_sel_hi:[0,1]
	v_pk_fma_f32 v[64:65], v[112:113], v[64:65], v[6:7]
	v_cndmask_b32_e64 v39, v40, v41, s[36:37]
	v_mul_f32_e32 v40, 0x37800000, v39
	v_cndmask_b32_e32 v39, v39, v40, vcc
	v_cmp_class_f32_e32 vcc, v38, v215
	v_pk_fma_f32 v[94:95], v[114:115], v[94:95], v[4:5]
	v_pk_fma_f32 v[78:79], v[114:115], v[78:79], v[4:5]
	v_cndmask_b32_e32 v38, v39, v38, vcc
	v_div_scale_f32 v39, s[2:3], v38, v38, 1.0
	v_rcp_f32_e32 v40, v39
	v_pk_fma_f32 v[62:63], v[114:115], v[62:63], v[4:5]
	v_mov_b32_e32 v32, v29
	s_add_i32 s2, s12, s13
	v_fma_f32 v41, -v39, v40, 1.0
	v_fmac_f32_e32 v40, v41, v40
	v_div_scale_f32 v41, vcc, 1.0, v38, 1.0
	v_mul_f32_e32 v42, v41, v40
	v_fma_f32 v43, -v39, v42, v41
	v_fmac_f32_e32 v42, v43, v40
	v_fma_f32 v39, -v39, v42, v41
	v_div_fmas_f32 v39, v39, v40, v42
	v_div_fixup_f32 v38, v39, v38, 1.0
	v_mov_b32_e32 v42, v22
	v_mov_b32_e32 v43, v24
	v_pk_mul_f32 v[42:43], v[38:39], v[42:43] op_sel_hi:[0,1]
	v_pk_mul_f32 v[44:45], v[38:39], v[44:45] op_sel_hi:[0,1]
	v_pk_fma_f32 v[14:15], v[116:117], v[44:45], v[14:15]
	v_pk_fma_f32 v[12:13], v[118:119], v[42:43], v[12:13]
	v_mov_b32_e32 v42, v26
	v_mov_b32_e32 v43, v30
	v_mov_b32_e32 v44, v34
	v_mov_b32_e32 v45, v36
	v_pk_mul_f32 v[42:43], v[38:39], v[42:43] op_sel_hi:[0,1]
	v_pk_mul_f32 v[44:45], v[38:39], v[44:45] op_sel_hi:[0,1]
	v_pk_fma_f32 v[44:45], v[112:113], v[44:45], v[6:7]
	v_pk_fma_f32 v[6:7], v[114:115], v[42:43], v[4:5]
	v_lshl_add_u64 v[40:41], v[20:21], 0, s[38:39]
	v_cvt_pk_bf16_f32 v4, v12, v13
	v_cvt_pk_bf16_f32 v5, v14, v15
	v_cvt_pk_bf16_f32 v6, v6, v7
	v_cvt_pk_bf16_f32 v7, v44, v45
	v_mov_b32_e32 v24, v23
	flat_store_dwordx4 v[40:41], v[4:7]
	v_mov_b32_e32 v30, v27
	v_mov_b32_e32 v36, v35
	v_pk_mul_f32 v[4:5], v[38:39], v[24:25] op_sel_hi:[0,1]
	v_pk_mul_f32 v[6:7], v[38:39], v[32:33] op_sel_hi:[0,1]
	v_pk_fma_f32 v[6:7], v[108:109], v[6:7], v[10:11]
	v_pk_fma_f32 v[4:5], v[110:111], v[4:5], v[8:9]
	v_pk_mul_f32 v[8:9], v[38:39], v[30:31] op_sel_hi:[0,1]
	v_pk_mul_f32 v[10:11], v[38:39], v[36:37] op_sel_hi:[0,1]
	v_pk_fma_f32 v[10:11], v[104:105], v[10:11], v[2:3]
	v_pk_fma_f32 v[2:3], v[106:107], v[8:9], v[0:1]
	v_cvt_pk_bf16_f32 v136, v136, v137
	v_cvt_pk_bf16_f32 v137, v138, v139
	v_cvt_pk_bf16_f32 v138, v142, v143
	v_cvt_pk_bf16_f32 v139, v144, v145
	v_cvt_pk_bf16_f32 v120, v120, v121
	v_cvt_pk_bf16_f32 v121, v122, v123
	v_cvt_pk_bf16_f32 v122, v126, v127
	v_cvt_pk_bf16_f32 v123, v128, v129
	v_cvt_pk_bf16_f32 v88, v88, v89
	v_cvt_pk_bf16_f32 v89, v90, v91
	v_cvt_pk_bf16_f32 v90, v94, v95
	v_cvt_pk_bf16_f32 v91, v96, v97
	v_cvt_pk_bf16_f32 v72, v72, v73
	v_cvt_pk_bf16_f32 v73, v74, v75
	v_cvt_pk_bf16_f32 v74, v78, v79
	v_cvt_pk_bf16_f32 v75, v82, v83
	v_cvt_pk_bf16_f32 v56, v56, v57
	v_cvt_pk_bf16_f32 v57, v58, v59
	v_cvt_pk_bf16_f32 v58, v62, v63
	v_cvt_pk_bf16_f32 v59, v64, v65
	v_cvt_pk_bf16_f32 v0, v4, v5
	v_cvt_pk_bf16_f32 v1, v6, v7
	v_cvt_pk_bf16_f32 v2, v2, v3
	v_cvt_pk_bf16_f32 v3, v10, v11
	s_cmpk_lt_i32 s2, 0x1000
	flat_store_dwordx4 v[198:199], v[194:197]
	flat_store_dwordx4 v[156:157], v[152:155]
	flat_store_dwordx4 v[140:141], v[136:139]
	flat_store_dwordx4 v[124:125], v[120:123]
	flat_store_dwordx4 v[92:93], v[88:91]
	flat_store_dwordx4 v[76:77], v[72:75]
	flat_store_dwordx4 v[60:61], v[56:59]
	flat_store_dwordx4 v[40:41], v[0:3] offset:1024
	s_cbranch_scc1 .LBB0_129

; template <bool X_F32> __device__ __forceinline__ void phase_norm_mod(const Ctx& C, const void* xin, const float* modl, int shift_idx, int scale_idx) {
;     ...
;         for (int r0_ = (gw % (NGW >> 3)) * NRW; r0_ < T / 8; r0_ += (NGW >> 3) * NRW) { const int m0 = (gw / (NGW >> 3)) * (T / 8) + r0_;
;             const int b = m0 >> 12;
;             f32x4 v[NRW][4]; float s[NRW];
; #pragma unroll
;             for (int r = 0; r < NRW; ++r) { s[r] = 0.f;
; #pragma unroll
;                 for (int j = 0; j < 2; ++j) { const f32x4* xr = (const f32x4*)((const float*)xin + (size_t)(m0 + r) * DM + 512 * j + 8 * lane); v[r][2 * j] = xr[0]; v[r][2 * j + 1] = xr[1];
; #pragma unroll
;                     for (int q = 0; q < 2; ++q) { const f32x4 t = v[r][2 * j + q]; s[r] += (t.x * t.x + t.y * t.y) + (t.z * t.z + t.w * t.w); } } }
;             wave_sumN<NRW>(s);
.LBB0_134:
	s_add_i32 s20, s10, s48
	s_ashr_i32 s21, s20, 31
	s_lshl_b64 s[36:37], s[20:21], 12
	v_lshl_add_u64 v[0:1], v[70:71], 0, s[36:37]
	global_load_dwordx4 v[60:63], v[0:1], off nt
	global_load_dwordx4 v[52:55], v[0:1], off offset:16 nt
	global_load_dwordx4 v[48:51], v[0:1], off offset:2064 nt
	global_load_dwordx4 v[56:59], v[0:1], off offset:2048 nt
	s_add_i32 s12, s20, 1
	s_add_i32 s4, s20, 2
	s_add_i32 s14, s20, 3
	s_ashr_i32 s13, s12, 31
	s_ashr_i32 s5, s4, 31
	s_ashr_i32 s15, s14, 31
	s_lshl_b64 s[36:37], s[12:13], 12
	s_lshl_b64 s[38:39], s[4:5], 12
	s_lshl_b64 s[40:41], s[14:15], 12
	v_lshl_add_u64 v[8:9], v[70:71], 0, s[36:37]
	v_lshl_add_u64 v[10:11], v[70:71], 0, s[38:39]
	v_lshl_add_u64 v[12:13], v[70:71], 0, s[40:41]
	global_load_dwordx4 v[36:39], v[8:9], off nt
	global_load_dwordx4 v[32:35], v[8:9], off offset:16 nt
	global_load_dwordx4 v[20:23], v[10:11], off nt
	global_load_dwordx4 v[16:19], v[10:11], off offset:16 nt
	global_load_dwordx4 v[4:7], v[12:13], off nt
	global_load_dwordx4 v[0:3], v[12:13], off offset:16 nt
	global_load_dwordx4 v[40:43], v[8:9], off offset:2064 nt
	global_load_dwordx4 v[44:47], v[8:9], off offset:2048 nt
	global_load_dwordx4 v[24:27], v[10:11], off offset:2064 nt
	global_load_dwordx4 v[28:31], v[10:11], off offset:2048 nt
	s_nop 0
	global_load_dwordx4 v[8:11], v[12:13], off offset:2064 nt
	s_nop 0
	global_load_dwordx4 v[12:15], v[12:13], off offset:2048 nt
	s_ashr_i32 s3, s20, 12
	s_mul_hi_i32 s42, s3, 0x6000
	s_mulk_i32 s3, 0x6000
	s_add_u32 s36, s78, s3
	s_addc_u32 s37, s1, s42
	v_lshl_add_u64 v[100:101], v[68:69], 2, s[36:37]
	v_add_co_u32_e32 v64, vcc, s49, v100
	v_lshl_add_u64 v[76:77], v[100:101], 0, s[90:91]
	s_nop 0
	v_addc_co_u32_e32 v65, vcc, 0, v101, vcc
	global_load_dwordx4 v[82:85], v[64:65], off
	s_lshl_b64 s[4:5], s[4:5], 11
	s_lshl_b64 s[20:21], s[20:21], 11
	s_lshl_b64 s[12:13], s[12:13], 11
	v_lshl_add_u64 v[74:75], v[72:73], 0, s[20:21]
	s_add_i32 s19, s19, s2
	s_lshl_b64 s[14:15], s[14:15], 11
	s_add_i32 s48, s48, s2
	s_add_i32 s3, s10, s19
	s_cmpk_gt_i32 s3, 0xfff
	s_waitcnt vmcnt(0)
	v_pk_mul_f32 v[64:65], v[62:63], v[62:63]
	v_pk_mul_f32 v[66:67], v[60:61], v[60:61]
	v_pk_mul_f32 v[78:79], v[54:55], v[54:55]
	v_pk_mul_f32 v[86:87], v[52:53], v[52:53]
	v_mul_f32_e32 v88, v57, v57
	v_mul_f32_e32 v90, v59, v59
	v_mul_f32_e32 v123, v50, v50
	v_mul_f32_e32 v124, v51, v51
	v_pk_mov_b32 v[92:93], v[66:67], v[64:65] op_sel:[1,0]
	v_mov_b32_e32 v67, v65
	v_pk_mov_b32 v[64:65], v[86:87], v[78:79] op_sel:[1,0]
	v_mov_b32_e32 v87, v79
	v_pk_fma_f32 v[78:79], v[56:57], v[56:57], v[88:89] op_sel_hi:[1,1,0]
	v_pk_fma_f32 v[90:91], v[58:59], v[58:59], v[90:91] op_sel_hi:[1,1,0]
	v_mov_b32_e32 v79, v123
	v_mov_b32_e32 v91, v124
	v_pk_mul_f32 v[88:89], v[38:39], v[38:39]
	v_pk_mul_f32 v[94:95], v[36:37], v[36:37]
	v_pk_add_f32 v[116:117], v[64:65], v[86:87]
	v_pk_add_f32 v[64:65], v[78:79], v[90:91]
	v_mul_f32_e32 v78, v45, v45
	v_pk_mul_f32 v[96:97], v[34:35], v[34:35]
	v_pk_mul_f32 v[98:99], v[32:33], v[32:33]
	v_pk_mul_f32 v[102:103], v[22:23], v[22:23]
	v_pk_mul_f32 v[104:105], v[20:21], v[20:21]
	v_pk_mul_f32 v[106:107], v[18:19], v[18:19]
	v_pk_mul_f32 v[108:109], v[16:17], v[16:17]
	v_pk_mul_f32 v[110:111], v[6:7], v[6:7]
	v_pk_mul_f32 v[112:113], v[4:5], v[4:5]
	v_pk_mul_f32 v[114:115], v[2:3], v[2:3]
	v_pk_add_f32 v[66:67], v[92:93], v[66:67]
	v_pk_mul_f32 v[92:93], v[0:1], v[0:1]
	v_pk_mov_b32 v[124:125], v[94:95], v[88:89] op_sel:[1,0]
	v_mov_b32_e32 v95, v89
	v_mul_f32_e32 v91, v42, v42
	v_mul_f32_e32 v90, v47, v47
	v_pk_fma_f32 v[78:79], v[44:45], v[44:45], v[78:79] op_sel_hi:[1,1,0]
	v_pk_mov_b32 v[126:127], v[98:99], v[96:97] op_sel:[1,0]
	v_mov_b32_e32 v99, v97
	v_pk_mov_b32 v[96:97], v[104:105], v[102:103] op_sel:[1,0]
	v_mov_b32_e32 v105, v103
	v_pk_mov_b32 v[102:103], v[108:109], v[106:107] op_sel:[1,0]
	v_mov_b32_e32 v109, v107
	v_pk_mov_b32 v[128:129], v[112:113], v[110:111] op_sel:[1,0]
	v_mov_b32_e32 v113, v111
	v_pk_mov_b32 v[130:131], v[92:93], v[114:115] op_sel:[1,0]
	v_mov_b32_e32 v93, v115
	v_pk_add_f32 v[106:107], v[124:125], v[94:95]
	v_mul_f32_e32 v95, v43, v43
	v_mov_b32_e32 v79, v91
	v_mul_f32_e32 v94, v29, v29
	v_pk_fma_f32 v[90:91], v[46:47], v[46:47], v[90:91] op_sel_hi:[1,1,0]
	v_pk_add_f32 v[96:97], v[96:97], v[104:105]
	v_mul_f32_e32 v104, v26, v26
	v_pk_add_f32 v[110:111], v[102:103], v[108:109]
	v_pk_add_f32 v[108:109], v[128:129], v[112:113]
	v_mov_b32_e32 v91, v95
	v_pk_fma_f32 v[94:95], v[28:29], v[28:29], v[94:95] op_sel_hi:[1,1,0]
	v_pk_add_f32 v[112:113], v[130:131], v[92:93]
	v_mul_f32_e32 v92, v13, v13
	v_mul_f32_e32 v102, v31, v31
	v_mov_b32_e32 v95, v104
	v_pk_fma_f32 v[104:105], v[12:13], v[12:13], v[92:93] op_sel_hi:[1,1,0]
	v_mul_f32_e32 v92, v15, v15
	v_mul_f32_e32 v114, v27, v27
	v_mul_f32_e32 v115, v10, v10
	v_mul_f32_e32 v124, v11, v11
	v_pk_fma_f32 v[102:103], v[30:31], v[30:31], v[102:103] op_sel_hi:[1,1,0]
	v_pk_fma_f32 v[128:129], v[14:15], v[14:15], v[92:93] op_sel_hi:[1,1,0]
	v_mul_f32_e32 v92, v49, v49
	v_pk_add_f32 v[116:117], v[116:117], v[116:117] op_sel:[0,1] op_sel_hi:[1,0]
	global_load_dwordx4 v[86:89], v[76:77], off offset:16
	v_pk_add_f32 v[98:99], v[126:127], v[98:99]
	v_mov_b32_e32 v103, v114
	v_mov_b32_e32 v105, v115
	v_mov_b32_e32 v129, v124
	v_pk_add_f32 v[114:115], v[66:67], v[66:67] op_sel:[0,1] op_sel_hi:[1,0]
	v_mov_b32_e32 v117, v92
	v_pk_add_f32 v[66:67], v[78:79], v[90:91]
	global_load_dwordx4 v[90:93], v[76:77], off offset:2048
	global_load_dwordx4 v[124:127], v[76:77], off offset:2064
	v_mul_f32_e32 v123, v48, v48
	v_mov_b32_e32 v115, v123
	v_pk_add_f32 v[114:115], v[114:115], v[116:117]
	v_mul_f32_e32 v116, v40, v40
	v_pk_add_f32 v[106:107], v[106:107], v[106:107] op_sel:[0,1] op_sel_hi:[1,0]
	v_pk_add_f32 v[76:77], v[84:85], 1.0 op_sel_hi:[1,0]
	v_pk_add_f32 v[78:79], v[82:83], 1.0 op_sel_hi:[1,0]
	v_mul_f32_e32 v123, v41, v41
	v_mov_b32_e32 v107, v116
	v_pk_add_f32 v[116:117], v[98:99], v[98:99] op_sel:[0,1] op_sel_hi:[1,0]
	v_mul_f32_e32 v98, v25, v25
	v_pk_add_f32 v[110:111], v[110:111], v[110:111] op_sel:[0,1] op_sel_hi:[1,0]
	v_mov_b32_e32 v117, v123
	v_mov_b32_e32 v111, v98
	v_pk_add_f32 v[108:109], v[108:109], v[108:109] op_sel:[0,1] op_sel_hi:[1,0]
	v_pk_add_f32 v[112:113], v[112:113], v[112:113] op_sel:[0,1] op_sel_hi:[1,0]
	v_pk_add_f32 v[102:103], v[94:95], v[102:103]
	v_pk_add_f32 v[64:65], v[114:115], v[64:65]
	v_pk_add_f32 v[106:107], v[106:107], v[116:117]
	v_pk_add_f32 v[104:105], v[104:105], v[128:129]
	v_lshl_add_u64 v[98:99], v[72:73], 0, s[4:5]
	v_lshl_add_u64 v[94:95], v[72:73], 0, s[12:13]
	s_waitcnt vmcnt(0)
; template <bool X_F32> __device__ __forceinline__ void phase_norm_mod(const Ctx& C, const void* xin, const float* modl, int shift_idx, int scale_idx) {
;     ...
;             wave_sumN<NRW>(s);
;             f32x4 a[4], g[4];
; #pragma unroll
;             for (int j = 0; j < 2; ++j)
; #pragma unroll
;                 for (int q = 0; q < 2; ++q) { a[2 * j + q] = *(const f32x4*)(modl + (size_t)b * NMOD + shift_idx * DM + 512 * j + 8 * lane + 4 * q);
;                     g[2 * j + q] = *(const f32x4*)(modl + (size_t)b * NMOD + scale_idx * DM + 512 * j + 8 * lane + 4 * q) + 1.0f; }
; #pragma unroll
;             for (int r = 0; r < NRW; ++r) { const float rs = 1.0f / sqrtf(s[r] * (1.f / DM) + EPS);
	v_pk_add_f32 v[82:83], v[88:89], 1.0 op_sel_hi:[1,0]
	v_pk_add_f32 v[84:85], v[86:87], 1.0 op_sel_hi:[1,0]
	v_pk_add_f32 v[86:87], v[92:93], 1.0 op_sel_hi:[1,0]
	v_pk_add_f32 v[88:89], v[90:91], 1.0 op_sel_hi:[1,0]
	v_pk_add_f32 v[90:91], v[126:127], 1.0 op_sel_hi:[1,0]
	v_pk_add_f32 v[92:93], v[124:125], 1.0 op_sel_hi:[1,0]
	v_mul_f32_e32 v126, v24, v24
	v_pk_add_f32 v[124:125], v[96:97], v[96:97] op_sel:[0,1] op_sel_hi:[1,0]
	v_mul_f32_e32 v96, v8, v8
	v_mov_b32_e32 v125, v126
	v_mul_f32_e32 v97, v9, v9
	v_mov_b32_e32 v109, v96
	v_mov_b32_e32 v113, v97
	v_pk_add_f32 v[110:111], v[124:125], v[110:111]
	v_pk_add_f32 v[108:109], v[108:109], v[112:113]
	v_add_f32_e32 v112, v64, v65
	v_pk_add_f32 v[64:65], v[106:107], v[66:67]
	v_pk_add_f32 v[66:67], v[110:111], v[102:103]
	v_pk_add_f32 v[102:103], v[108:109], v[104:105]
	v_add_f32_e32 v64, v64, v65
	v_add_f32_e32 v65, v66, v67
	ds_bpermute_b32 v67, v80, v112
	v_add_f32_e32 v66, v102, v103
	ds_bpermute_b32 v102, v80, v64
	ds_bpermute_b32 v103, v80, v65
	ds_bpermute_b32 v104, v80, v66
	s_waitcnt lgkmcnt(0)
	v_add_f32_e32 v67, v112, v67
	v_lshl_add_u64 v[96:97], v[72:73], 0, s[14:15]
	v_add_f32_e32 v64, v64, v102
	ds_bpermute_b32 v102, v118, v67
	v_add_f32_e32 v65, v65, v103
	v_add_f32_e32 v66, v66, v104
	ds_bpermute_b32 v103, v118, v64
	ds_bpermute_b32 v104, v118, v65
	ds_bpermute_b32 v105, v118, v66
	s_waitcnt lgkmcnt(3)
	v_add_f32_e32 v67, v67, v102
	ds_bpermute_b32 v102, v119, v67
	s_waitcnt lgkmcnt(3)
	v_add_f32_e32 v64, v64, v103
	s_waitcnt lgkmcnt(2)
	v_add_f32_e32 v65, v65, v104
	s_waitcnt lgkmcnt(1)
	v_add_f32_e32 v66, v66, v105
	ds_bpermute_b32 v103, v119, v64
	ds_bpermute_b32 v104, v119, v65
	ds_bpermute_b32 v105, v119, v66
	s_waitcnt lgkmcnt(3)
	v_add_f32_e32 v67, v67, v102
	ds_bpermute_b32 v102, v120, v67
	s_waitcnt lgkmcnt(3)
	v_add_f32_e32 v64, v64, v103
	s_waitcnt lgkmcnt(2)
	v_add_f32_e32 v65, v65, v104
	s_waitcnt lgkmcnt(1)
	v_add_f32_e32 v66, v66, v105
	ds_bpermute_b32 v103, v120, v64
	ds_bpermute_b32 v104, v120, v65
	ds_bpermute_b32 v105, v120, v66
	s_waitcnt lgkmcnt(3)
	v_add_f32_e32 v67, v67, v102
	ds_bpermute_b32 v102, v121, v67
	s_waitcnt lgkmcnt(3)
	v_add_f32_e32 v64, v64, v103
	s_waitcnt lgkmcnt(2)
	v_add_f32_e32 v65, v65, v104
	s_waitcnt lgkmcnt(1)
	v_add_f32_e32 v66, v66, v105
	ds_bpermute_b32 v103, v121, v64
	ds_bpermute_b32 v104, v121, v65
	ds_bpermute_b32 v105, v121, v66
	s_waitcnt lgkmcnt(3)
	v_add_f32_e32 v67, v67, v102
	ds_bpermute_b32 v102, v122, v67
	s_waitcnt lgkmcnt(3)
	v_add_f32_e32 v64, v64, v103
	s_waitcnt lgkmcnt(2)
	v_add_f32_e32 v65, v65, v104
	s_waitcnt lgkmcnt(1)
	v_add_f32_e32 v66, v66, v105
	ds_bpermute_b32 v103, v122, v64
	ds_bpermute_b32 v104, v122, v65
	ds_bpermute_b32 v105, v122, v66
	s_waitcnt lgkmcnt(3)
	v_add_f32_e32 v67, v67, v102
	v_fmamk_f32 v67, v67, 0x3a800000, v214
	s_waitcnt lgkmcnt(2)
	v_add_f32_e32 v64, v64, v103
	v_mul_f32_e32 v102, 0x4f800000, v67
	v_cmp_gt_f32_e32 vcc, s50, v67
	s_waitcnt lgkmcnt(1)
	v_add_f32_e32 v65, v65, v104
	s_waitcnt lgkmcnt(0)
	v_add_f32_e32 v66, v66, v105
	v_fmamk_f32 v64, v64, 0x3a800000, v214
	v_cndmask_b32_e32 v67, v67, v102, vcc
	v_fmamk_f32 v65, v65, 0x3a800000, v214
	v_fmamk_f32 v66, v66, 0x3a800000, v214
	v_mul_f32_e32 v102, 0x4f800000, v64
	v_cmp_gt_f32_e64 s[36:37], s50, v64
	v_sqrt_f32_e32 v105, v67
	v_mul_f32_e32 v103, 0x4f800000, v65
	v_cmp_gt_f32_e64 s[38:39], s50, v65
	v_mul_f32_e32 v104, 0x4f800000, v66
	v_cmp_gt_f32_e64 s[40:41], s50, v66
	v_cndmask_b32_e64 v64, v64, v102, s[36:37]
	v_cndmask_b32_e64 v65, v65, v103, s[38:39]
	v_cndmask_b32_e64 v66, v66, v104, s[40:41]
	v_sqrt_f32_e32 v102, v64
	v_sqrt_f32_e32 v103, v65
	v_sqrt_f32_e32 v104, v66
	v_add_u32_e32 v106, -1, v105
	v_add_u32_e32 v107, 1, v105
	v_fma_f32 v108, -v106, v105, v67
	v_fma_f32 v109, -v107, v105, v67
	v_add_u32_e32 v110, -1, v102
	v_cmp_ge_f32_e64 s[42:43], 0, v108
	v_add_u32_e32 v111, 1, v102
	v_add_u32_e32 v112, -1, v103
	v_add_u32_e32 v114, -1, v104
	v_cndmask_b32_e64 v105, v105, v106, s[42:43]
	v_cmp_lt_f32_e64 s[42:43], 0, v109
	v_fma_f32 v106, -v110, v102, v64
	v_add_u32_e32 v113, 1, v103
	v_add_u32_e32 v115, 1, v104
	v_fma_f32 v108, -v111, v102, v64
	v_fma_f32 v109, -v112, v103, v65
	v_fma_f32 v117, -v114, v104, v66
	v_cndmask_b32_e64 v105, v105, v107, s[42:43]
	v_cmp_ge_f32_e64 s[42:43], 0, v106
	v_fma_f32 v116, -v113, v103, v65
	v_fma_f32 v107, -v115, v104, v66
	v_cndmask_b32_e64 v102, v102, v110, s[42:43]
	v_cmp_lt_f32_e64 s[42:43], 0, v108
	v_cmp_ge_f32_e64 s[44:45], 0, v109
	v_cmp_ge_f32_e64 s[46:47], 0, v117
	v_mul_f32_e32 v106, 0x37800000, v105
	v_cndmask_b32_e64 v103, v103, v112, s[44:45]
	v_cmp_lt_f32_e64 s[44:45], 0, v116
	v_cndmask_b32_e64 v104, v104, v114, s[46:47]
	v_cmp_lt_f32_e64 s[46:47], 0, v107
	v_cndmask_b32_e64 v107, v102, v111, s[42:43]
	v_cndmask_b32_e32 v102, v105, v106, vcc
	v_cmp_class_f32_e32 vcc, v67, v215
	v_cndmask_b32_e64 v103, v103, v113, s[44:45]
	v_mul_f32_e32 v105, 0x37800000, v107
	v_cndmask_b32_e32 v102, v102, v67, vcc
	v_cndmask_b32_e64 v104, v104, v115, s[46:47]
	v_mul_f32_e32 v106, 0x37800000, v103
	v_cndmask_b32_e64 v67, v107, v105, s[36:37]
	v_cmp_class_f32_e32 vcc, v64, v215
	v_div_scale_f32 v109, s[4:5], v102, v102, 1.0
	v_mul_f32_e32 v108, 0x37800000, v104
	v_cndmask_b32_e64 v103, v103, v106, s[38:39]
	v_cmp_class_f32_e64 s[36:37], v65, v215
	v_cndmask_b32_e32 v106, v67, v64, vcc
	v_rcp_f32_e32 v64, v109
	v_cndmask_b32_e64 v104, v104, v108, s[40:41]
	v_cmp_class_f32_e64 s[38:39], v66, v215
	v_cndmask_b32_e64 v115, v103, v65, s[36:37]
	v_div_scale_f32 v65, s[4:5], v106, v106, 1.0
	v_cndmask_b32_e64 v114, v104, v66, s[38:39]
	v_div_scale_f32 v103, s[4:5], v115, v115, 1.0
; __device__ __forceinline__ unsigned pk2(float lo, float hi) { return pg8::cvt_pk_bf16(lo, hi); }
; template <bool X_F32> __device__ __forceinline__ void phase_norm_mod(const Ctx& C, const void* xin, const float* modl, int shift_idx, int scale_idx) {
;     ...
; #pragma unroll
;             for (int r = 0; r < NRW; ++r) { const float rs = 1.0f / sqrtf(s[r] * (1.f / DM) + EPS);
; #pragma unroll
;                 for (int j = 0; j < 2; ++j) { const f32x4 y0 = v[r][2 * j] * rs * g[2 * j] + a[2 * j], y1 = v[r][2 * j + 1] * rs * g[2 * j + 1] + a[2 * j + 1];
;                     u32x4 w; w.x = pk2(y0.x, y0.y); w.y = pk2(y0.z, y0.w); w.z = pk2(y1.x, y1.y); w.w = pk2(y1.z, y1.w);
;                     ((u32x4*)(H + (size_t)(m0 + r) * DM + 512 * j))[lane] = w; } }
;         }
	v_rcp_f32_e32 v107, v65
	v_div_scale_f32 v105, s[4:5], v114, v114, 1.0
	v_rcp_f32_e32 v124, v103
	v_rcp_f32_e32 v116, v105
	v_fma_f32 v67, -v109, v64, 1.0
	v_div_scale_f32 v111, s[42:43], 1.0, v102, 1.0
	v_fmac_f32_e32 v64, v67, v64
	v_fma_f32 v67, -v65, v107, 1.0
	v_mul_f32_e32 v113, v111, v64
	v_div_scale_f32 v66, s[40:41], 1.0, v106, 1.0
	v_fma_f32 v108, -v103, v124, 1.0
	v_fmac_f32_e32 v107, v67, v107
	v_fma_f32 v67, -v109, v113, v111
	v_div_scale_f32 v104, s[38:39], 1.0, v115, 1.0
	v_fma_f32 v112, -v105, v116, 1.0
	v_fmac_f32_e32 v124, v108, v124
	v_mul_f32_e32 v108, v66, v107
	v_fmac_f32_e32 v113, v67, v64
	v_div_scale_f32 v110, s[36:37], 1.0, v114, 1.0
	v_fmac_f32_e32 v116, v112, v116
	v_mul_f32_e32 v125, v104, v124
	v_fma_f32 v67, -v109, v113, v111
	v_fma_f32 v109, -v65, v108, v66
	v_mul_f32_e32 v117, v110, v116
	v_fmac_f32_e32 v108, v109, v107
	v_fma_f32 v109, -v103, v125, v104
	v_fmac_f32_e32 v125, v109, v124
	v_fma_f32 v109, -v105, v117, v110
	s_mov_b64 vcc, s[42:43]
	v_fmac_f32_e32 v117, v109, v116
	v_div_fmas_f32 v111, v67, v64, v113
	v_fma_f32 v109, -v65, v108, v66
	s_mov_b64 vcc, s[40:41]
	v_div_fmas_f32 v107, v109, v107, v108
	v_fma_f32 v127, -v103, v125, v104
	v_div_fixup_f32 v104, v111, v102, 1.0
	v_div_fixup_f32 v126, v107, v106, 1.0
	global_load_dwordx4 v[64:67], v[100:101], off offset:16
	v_fma_f32 v123, -v105, v117, v110
	v_pk_mul_f32 v[60:61], v[60:61], v[104:105] op_sel_hi:[1,0]
	v_pk_mul_f32 v[62:63], v[62:63], v[104:105] op_sel_hi:[1,0]
	v_pk_mul_f32 v[52:53], v[52:53], v[104:105] op_sel_hi:[1,0]
	v_pk_mul_f32 v[102:103], v[54:55], v[104:105] op_sel_hi:[1,0]
	v_pk_mul_f32 v[54:55], v[56:57], v[104:105] op_sel_hi:[1,0]
	v_pk_mul_f32 v[58:59], v[58:59], v[104:105] op_sel_hi:[1,0]
	v_pk_mul_f32 v[56:57], v[48:49], v[104:105] op_sel_hi:[1,0]
	v_pk_mul_f32 v[104:105], v[50:51], v[104:105] op_sel_hi:[1,0]
	global_load_dwordx4 v[48:51], v[100:101], off
	v_pk_mul_f32 v[106:107], v[36:37], v[126:127] op_sel_hi:[1,0]
	v_pk_mul_f32 v[110:111], v[38:39], v[126:127] op_sel_hi:[1,0]
	v_pk_mul_f32 v[108:109], v[32:33], v[126:127] op_sel_hi:[1,0]
	v_pk_mul_f32 v[112:113], v[34:35], v[126:127] op_sel_hi:[1,0]
	global_load_dwordx4 v[32:35], v[100:101], off offset:2048
	global_load_dwordx4 v[36:39], v[100:101], off offset:2064
	s_mov_b64 vcc, s[38:39]
	v_div_fmas_f32 v124, v127, v124, v125
	s_mov_b64 vcc, s[36:37]
	v_pk_mul_f32 v[44:45], v[44:45], v[126:127] op_sel_hi:[1,0]
	v_pk_mul_f32 v[46:47], v[46:47], v[126:127] op_sel_hi:[1,0]
	v_pk_mul_f32 v[40:41], v[40:41], v[126:127] op_sel_hi:[1,0]
	v_pk_mul_f32 v[42:43], v[42:43], v[126:127] op_sel_hi:[1,0]
	v_div_fixup_f32 v124, v124, v115, 1.0
	v_div_fmas_f32 v115, v123, v116, v117
	v_pk_mul_f32 v[28:29], v[28:29], v[124:125] op_sel_hi:[1,0]
	v_pk_mul_f32 v[30:31], v[30:31], v[124:125] op_sel_hi:[1,0]
	v_pk_mul_f32 v[24:25], v[24:25], v[124:125] op_sel_hi:[1,0]
	v_pk_mul_f32 v[26:27], v[26:27], v[124:125] op_sel_hi:[1,0]
	s_waitcnt vmcnt(3)
	v_pk_fma_f32 v[100:101], v[82:83], v[102:103], v[66:67]
	v_pk_fma_f32 v[102:103], v[84:85], v[52:53], v[64:65]
	s_waitcnt vmcnt(2)
	v_pk_fma_f32 v[62:63], v[76:77], v[62:63], v[50:51]
	v_pk_fma_f32 v[60:61], v[78:79], v[60:61], v[48:49]
	v_cvt_pk_bf16_f32 v53, v62, v63
	v_cvt_pk_bf16_f32 v52, v60, v61
	v_pk_fma_f32 v[60:61], v[76:77], v[110:111], v[50:51]
	s_waitcnt vmcnt(1)
	v_pk_fma_f32 v[58:59], v[58:59], v[86:87], v[34:35]
	v_pk_fma_f32 v[126:127], v[54:55], v[88:89], v[32:33]
	s_waitcnt vmcnt(0)
	v_pk_fma_f32 v[104:105], v[104:105], v[90:91], v[38:39]
	v_pk_fma_f32 v[128:129], v[56:57], v[92:93], v[36:37]
	v_cvt_pk_bf16_f32 v54, v102, v103
	v_cvt_pk_bf16_f32 v55, v100, v101
	v_cvt_pk_bf16_f32 v56, v126, v127
	v_cvt_pk_bf16_f32 v57, v58, v59
	v_cvt_pk_bf16_f32 v58, v128, v129
	v_cvt_pk_bf16_f32 v59, v104, v105
	v_pk_fma_f32 v[62:63], v[78:79], v[106:107], v[48:49]
	v_pk_fma_f32 v[100:101], v[82:83], v[112:113], v[66:67]
	v_pk_fma_f32 v[102:103], v[84:85], v[108:109], v[64:65]
	v_pk_fma_f32 v[46:47], v[46:47], v[86:87], v[34:35]
	v_pk_fma_f32 v[44:45], v[44:45], v[88:89], v[32:33]
	v_pk_fma_f32 v[42:43], v[42:43], v[90:91], v[38:39]
	v_pk_fma_f32 v[40:41], v[40:41], v[92:93], v[36:37]
	v_pk_mul_f32 v[104:105], v[20:21], v[124:125] op_sel_hi:[1,0]
	v_pk_mul_f32 v[106:107], v[22:23], v[124:125] op_sel_hi:[1,0]
	v_pk_mul_f32 v[108:109], v[16:17], v[124:125] op_sel_hi:[1,0]
	v_pk_mul_f32 v[110:111], v[18:19], v[124:125] op_sel_hi:[1,0]
	v_div_fixup_f32 v112, v115, v114, 1.0
	flat_store_dwordx4 v[74:75], v[52:55]
	flat_store_dwordx4 v[74:75], v[56:59] offset:1024
	v_cvt_pk_bf16_f32 v16, v62, v63
	v_cvt_pk_bf16_f32 v17, v60, v61
	v_cvt_pk_bf16_f32 v18, v102, v103
	v_cvt_pk_bf16_f32 v19, v100, v101
	v_cvt_pk_bf16_f32 v20, v44, v45
	v_cvt_pk_bf16_f32 v21, v46, v47
	v_cvt_pk_bf16_f32 v22, v40, v41
	v_cvt_pk_bf16_f32 v23, v42, v43
	v_pk_fma_f32 v[40:41], v[76:77], v[106:107], v[50:51]
	v_pk_fma_f32 v[42:43], v[78:79], v[104:105], v[48:49]
	v_pk_fma_f32 v[44:45], v[82:83], v[110:111], v[66:67]
	v_pk_fma_f32 v[46:47], v[84:85], v[108:109], v[64:65]
	v_pk_mul_f32 v[52:53], v[4:5], v[112:113] op_sel_hi:[1,0]
	v_pk_mul_f32 v[54:55], v[6:7], v[112:113] op_sel_hi:[1,0]
	v_pk_mul_f32 v[56:57], v[0:1], v[112:113] op_sel_hi:[1,0]
	v_pk_mul_f32 v[58:59], v[2:3], v[112:113] op_sel_hi:[1,0]
	v_pk_fma_f32 v[30:31], v[86:87], v[30:31], v[34:35]
	v_pk_fma_f32 v[28:29], v[88:89], v[28:29], v[32:33]
	v_pk_fma_f32 v[26:27], v[26:27], v[90:91], v[38:39]
	v_pk_fma_f32 v[24:25], v[24:25], v[92:93], v[36:37]
	v_pk_mul_f32 v[12:13], v[12:13], v[112:113] op_sel_hi:[1,0]
	v_pk_mul_f32 v[14:15], v[14:15], v[112:113] op_sel_hi:[1,0]
	v_pk_mul_f32 v[8:9], v[8:9], v[112:113] op_sel_hi:[1,0]
	v_pk_mul_f32 v[10:11], v[10:11], v[112:113] op_sel_hi:[1,0]
	flat_store_dwordx4 v[94:95], v[16:19]
	flat_store_dwordx4 v[94:95], v[20:23] offset:1024
	v_cvt_pk_bf16_f32 v0, v42, v43
	v_cvt_pk_bf16_f32 v1, v40, v41
	v_cvt_pk_bf16_f32 v2, v46, v47
	v_cvt_pk_bf16_f32 v3, v44, v45
	v_pk_fma_f32 v[16:17], v[76:77], v[54:55], v[50:51]
	v_pk_fma_f32 v[18:19], v[78:79], v[52:53], v[48:49]
	v_pk_fma_f32 v[20:21], v[82:83], v[58:59], v[66:67]
	v_pk_fma_f32 v[22:23], v[84:85], v[56:57], v[64:65]
	v_cvt_pk_bf16_f32 v4, v28, v29
	v_cvt_pk_bf16_f32 v5, v30, v31
	v_cvt_pk_bf16_f32 v6, v24, v25
	v_cvt_pk_bf16_f32 v7, v26, v27
	v_pk_fma_f32 v[14:15], v[86:87], v[14:15], v[34:35]
	v_pk_fma_f32 v[12:13], v[88:89], v[12:13], v[32:33]
	v_pk_fma_f32 v[10:11], v[10:11], v[90:91], v[38:39]
	v_pk_fma_f32 v[8:9], v[8:9], v[92:93], v[36:37]
	flat_store_dwordx4 v[98:99], v[0:3]
	flat_store_dwordx4 v[98:99], v[4:7] offset:1024
	s_nop 0
	v_cvt_pk_bf16_f32 v0, v18, v19
	v_cvt_pk_bf16_f32 v1, v16, v17
	v_cvt_pk_bf16_f32 v2, v22, v23
	v_cvt_pk_bf16_f32 v3, v20, v21
	v_cvt_pk_bf16_f32 v4, v12, v13
	v_cvt_pk_bf16_f32 v5, v14, v15
	v_cvt_pk_bf16_f32 v6, v8, v9
	v_cvt_pk_bf16_f32 v7, v10, v11
	flat_store_dwordx4 v[96:97], v[0:3]
	flat_store_dwordx4 v[96:97], v[4:7] offset:1024
	s_cbranch_scc0 .LBB0_134

; __device__ __forceinline__ void unpack8(const u32x4 w, f32x4& a, f32x4& c) { a = (f32x4){bf_lo(w.x), bf_hi(w.x), bf_lo(w.y), bf_hi(w.y)}; c = (f32x4){bf_lo(w.z), bf_hi(w.z), bf_lo(w.w), bf_hi(w.w)}; }
; template <bool X_F32> __device__ __forceinline__ void phase_norm_mod(const Ctx& C, const void* xin, const float* modl, int shift_idx, int scale_idx) {
;     ...
;         for (int r0_ = (gw % (NGW >> 3)) * NR; r0_ < T / 8; r0_ += (NGW >> 3) * NR) { const int m0 = (gw / (NGW >> 3)) * (T / 8) + r0_;
;             const int b = m0 >> 12;
;             u32x4 raw[NR][2]; float s[NR];
; #pragma unroll
;             for (int r = 0; r < NR; ++r)
; #pragma unroll
;                 for (int j = 0; j < 2; ++j) raw[r][j] = ((const u32x4*)((const bf16*)xin + (size_t)(m0 + r) * DM + 512 * j))[lane];
; #pragma unroll
;             for (int r = 0; r < NR; ++r) { s[r] = 0.f;
; #pragma unroll
;                 for (int j = 0; j < 2; ++j) { f32x4 t0, t1; unpack8(raw[r][j], t0, t1);
;                     s[r] += ((t0.x * t0.x + t0.y * t0.y) + (t0.z * t0.z + t0.w * t0.w)) + ((t1.x * t1.x + t1.y * t1.y) + (t1.z * t1.z + t1.w * t1.w)); } }
.LBB0_499:
	s_add_i32 s12, s20, s50
	s_ashr_i32 s13, s12, 31
	s_lshl_b64 s[48:49], s[12:13], 11
	v_lshl_add_u64 v[4:5], v[16:17], 0, s[48:49]
	global_load_dwordx4 v[0:3], v[4:5], off nt
	s_nop 0
	global_load_dwordx4 v[4:7], v[4:5], off offset:1024 nt
	s_add_i32 s2, s12, 1
	s_ashr_i32 s3, s2, 31
	s_lshl_b64 s[14:15], s[2:3], 11
	v_lshl_add_u64 v[12:13], v[16:17], 0, s[14:15]
	global_load_dwordx4 v[8:11], v[12:13], off nt
	s_nop 0
	global_load_dwordx4 v[12:15], v[12:13], off offset:1024 nt
	s_add_i32 s2, s12, 2
	s_ashr_i32 s3, s2, 31
	s_lshl_b64 s[4:5], s[2:3], 11
	v_lshl_add_u64 v[26:27], v[16:17], 0, s[4:5]
	global_load_dwordx4 v[22:25], v[26:27], off nt
	s_nop 0
	global_load_dwordx4 v[26:29], v[26:27], off offset:1024 nt
	s_add_i32 s2, s12, 3
	s_ashr_i32 s3, s2, 31
	s_lshl_b64 s[46:47], s[2:3], 11
	v_lshl_add_u64 v[34:35], v[16:17], 0, s[46:47]
	global_load_dwordx4 v[30:33], v[34:35], off nt
	s_nop 0
	global_load_dwordx4 v[34:37], v[34:35], off offset:1024 nt
	s_add_i32 s2, s12, 4
	s_ashr_i32 s3, s2, 31
	s_lshl_b64 s[44:45], s[2:3], 11
	v_lshl_add_u64 v[42:43], v[16:17], 0, s[44:45]
	global_load_dwordx4 v[38:41], v[42:43], off nt
	s_nop 0
	global_load_dwordx4 v[42:45], v[42:43], off offset:1024 nt
	s_add_i32 s2, s12, 5
	s_ashr_i32 s3, s2, 31
	s_lshl_b64 s[42:43], s[2:3], 11
	v_lshl_add_u64 v[50:51], v[16:17], 0, s[42:43]
	global_load_dwordx4 v[46:49], v[50:51], off nt
	s_nop 0
	global_load_dwordx4 v[50:53], v[50:51], off offset:1024 nt
	s_add_i32 s2, s12, 6
	s_ashr_i32 s3, s2, 31
	s_lshl_b64 s[40:41], s[2:3], 11
	v_lshl_add_u64 v[54:55], v[16:17], 0, s[40:41]
	global_load_dwordx4 v[120:123], v[54:55], off nt
	global_load_dwordx4 v[124:127], v[54:55], off offset:1024 nt
	s_add_i32 s2, s12, 7
	s_ashr_i32 s3, s2, 31
	s_lshl_b64 s[38:39], s[2:3], 11
	v_lshl_add_u64 v[54:55], v[16:17], 0, s[38:39]
	global_load_dwordx4 v[128:131], v[54:55], off nt
	global_load_dwordx4 v[132:135], v[54:55], off offset:1024 nt
	s_ashr_i32 s2, s12, 12
	s_mul_hi_i32 s3, s2, 0x6000
	s_mulk_i32 s2, 0x6000
	s_add_u32 s2, s78, s2
	s_addc_u32 s3, s51, s3
	v_lshl_add_u64 v[198:199], v[20:21], 0, s[48:49]
	s_add_i32 s21, s21, s10
	s_add_i32 s50, s50, s10
	s_waitcnt vmcnt(0)
	v_and_b32_e32 v154, 0xffff0000, v0
	v_and_b32_e32 v155, 0xffff0000, v4
	v_and_b32_e32 v175, 0xffff0000, v5
	v_and_b32_e32 v174, 0xffff0000, v1
	v_lshlrev_b32_e32 v153, 16, v4
	v_lshlrev_b32_e32 v152, 16, v0
	v_lshlrev_b32_e32 v159, 16, v5
	v_lshlrev_b32_e32 v158, 16, v1
	v_lshlrev_b32_e32 v156, 16, v2
	v_and_b32_e32 v160, 0xffff0000, v2
	v_lshlrev_b32_e32 v176, 16, v3
	v_and_b32_e32 v178, 0xffff0000, v3
	v_pk_mul_f32 v[0:1], v[154:155], v[154:155]
	v_pk_mul_f32 v[2:3], v[174:175], v[174:175]
	v_and_b32_e32 v161, 0xffff0000, v6
	v_and_b32_e32 v179, 0xffff0000, v7
	v_pk_fma_f32 v[0:1], v[152:153], v[152:153], v[0:1]
	v_pk_fma_f32 v[2:3], v[158:159], v[158:159], v[2:3]
	v_lshlrev_b32_e32 v157, 16, v6
	v_lshlrev_b32_e32 v177, 16, v7
	v_pk_add_f32 v[0:1], v[0:1], v[2:3]
	v_pk_mul_f32 v[2:3], v[160:161], v[160:161]
	v_pk_mul_f32 v[4:5], v[178:179], v[178:179]
	v_pk_fma_f32 v[2:3], v[156:157], v[156:157], v[2:3]
	v_pk_fma_f32 v[4:5], v[176:177], v[176:177], v[4:5]
	v_and_b32_e32 v139, 0xffff0000, v12
	v_pk_add_f32 v[2:3], v[2:3], v[4:5]
	v_and_b32_e32 v138, 0xffff0000, v8
	v_pk_add_f32 v[0:1], v[0:1], v[2:3]
	v_and_b32_e32 v147, 0xffff0000, v13
	v_and_b32_e32 v146, 0xffff0000, v9
	v_add_f32_e32 v6, v0, v1
	v_lshlrev_b32_e32 v137, 16, v12
	v_lshlrev_b32_e32 v136, 16, v8
	v_lshlrev_b32_e32 v143, 16, v13
	v_lshlrev_b32_e32 v142, 16, v9
	v_pk_mul_f32 v[0:1], v[138:139], v[138:139]
	v_pk_mul_f32 v[2:3], v[146:147], v[146:147]
	v_and_b32_e32 v145, 0xffff0000, v14
	v_and_b32_e32 v144, 0xffff0000, v10
	v_and_b32_e32 v151, 0xffff0000, v15
	v_and_b32_e32 v150, 0xffff0000, v11
	v_pk_fma_f32 v[0:1], v[136:137], v[136:137], v[0:1]
	v_pk_fma_f32 v[2:3], v[142:143], v[142:143], v[2:3]
	v_lshlrev_b32_e32 v141, 16, v14
	v_lshlrev_b32_e32 v140, 16, v10
	v_lshlrev_b32_e32 v149, 16, v15
	v_lshlrev_b32_e32 v148, 16, v11
	v_pk_add_f32 v[0:1], v[0:1], v[2:3]
	v_pk_mul_f32 v[2:3], v[144:145], v[144:145]
	v_pk_mul_f32 v[4:5], v[150:151], v[150:151]
	v_pk_fma_f32 v[2:3], v[140:141], v[140:141], v[2:3]
	v_pk_fma_f32 v[4:5], v[148:149], v[148:149], v[4:5]
	v_and_b32_e32 v107, 0xffff0000, v26
	v_pk_add_f32 v[2:3], v[2:3], v[4:5]
	v_and_b32_e32 v106, 0xffff0000, v22
	v_pk_add_f32 v[0:1], v[0:1], v[2:3]
	v_and_b32_e32 v115, 0xffff0000, v27
	v_and_b32_e32 v114, 0xffff0000, v23
	v_add_f32_e32 v7, v0, v1
	v_lshlrev_b32_e32 v105, 16, v26
	v_lshlrev_b32_e32 v104, 16, v22
	v_lshlrev_b32_e32 v111, 16, v27
	v_lshlrev_b32_e32 v110, 16, v23
	v_pk_mul_f32 v[0:1], v[106:107], v[106:107]
	v_pk_mul_f32 v[2:3], v[114:115], v[114:115]
	v_and_b32_e32 v113, 0xffff0000, v28
	v_and_b32_e32 v112, 0xffff0000, v24
	v_and_b32_e32 v119, 0xffff0000, v29
	v_and_b32_e32 v118, 0xffff0000, v25
	v_pk_fma_f32 v[0:1], v[104:105], v[104:105], v[0:1]
	v_pk_fma_f32 v[2:3], v[110:111], v[110:111], v[2:3]
	v_lshlrev_b32_e32 v109, 16, v28
	v_lshlrev_b32_e32 v108, 16, v24
	v_lshlrev_b32_e32 v117, 16, v29
	v_lshlrev_b32_e32 v116, 16, v25
	v_pk_add_f32 v[0:1], v[0:1], v[2:3]
	v_pk_mul_f32 v[2:3], v[112:113], v[112:113]
	v_pk_mul_f32 v[4:5], v[118:119], v[118:119]
	v_pk_fma_f32 v[2:3], v[108:109], v[108:109], v[2:3]
	v_pk_fma_f32 v[4:5], v[116:117], v[116:117], v[4:5]
	v_and_b32_e32 v91, 0xffff0000, v34
	v_pk_add_f32 v[2:3], v[2:3], v[4:5]
	v_and_b32_e32 v90, 0xffff0000, v30
	v_pk_add_f32 v[0:1], v[0:1], v[2:3]
	v_and_b32_e32 v99, 0xffff0000, v35
	v_and_b32_e32 v98, 0xffff0000, v31
	v_add_f32_e32 v8, v0, v1
	v_lshlrev_b32_e32 v89, 16, v34
	v_lshlrev_b32_e32 v88, 16, v30
; __device__ __forceinline__ void unpack8(const u32x4 w, f32x4& a, f32x4& c) { a = (f32x4){bf_lo(w.x), bf_hi(w.x), bf_lo(w.y), bf_hi(w.y)}; c = (f32x4){bf_lo(w.z), bf_hi(w.z), bf_lo(w.w), bf_hi(w.w)}; }
; template <bool X_F32> __device__ __forceinline__ void phase_norm_mod(const Ctx& C, const void* xin, const float* modl, int shift_idx, int scale_idx) {
;     ...
;             for (int r = 0; r < NR; ++r) { s[r] = 0.f;
; #pragma unroll
;                 for (int j = 0; j < 2; ++j) { f32x4 t0, t1; unpack8(raw[r][j], t0, t1);
;                     s[r] += ((t0.x * t0.x + t0.y * t0.y) + (t0.z * t0.z + t0.w * t0.w)) + ((t1.x * t1.x + t1.y * t1.y) + (t1.z * t1.z + t1.w * t1.w)); } }
;             wave_sumN<NR>(s);
	v_lshlrev_b32_e32 v95, 16, v35
	v_lshlrev_b32_e32 v94, 16, v31
	v_pk_mul_f32 v[0:1], v[90:91], v[90:91]
	v_pk_mul_f32 v[2:3], v[98:99], v[98:99]
	v_and_b32_e32 v97, 0xffff0000, v36
	v_and_b32_e32 v96, 0xffff0000, v32
	v_and_b32_e32 v103, 0xffff0000, v37
	v_and_b32_e32 v102, 0xffff0000, v33
	v_pk_fma_f32 v[0:1], v[88:89], v[88:89], v[0:1]
	v_pk_fma_f32 v[2:3], v[94:95], v[94:95], v[2:3]
	v_lshlrev_b32_e32 v93, 16, v36
	v_lshlrev_b32_e32 v92, 16, v32
	v_lshlrev_b32_e32 v101, 16, v37
	v_lshlrev_b32_e32 v100, 16, v33
	v_pk_add_f32 v[0:1], v[0:1], v[2:3]
	v_pk_mul_f32 v[2:3], v[96:97], v[96:97]
	v_pk_mul_f32 v[4:5], v[102:103], v[102:103]
	v_pk_fma_f32 v[2:3], v[92:93], v[92:93], v[2:3]
	v_pk_fma_f32 v[4:5], v[100:101], v[100:101], v[4:5]
	v_and_b32_e32 v73, 0xffff0000, v42
	v_pk_add_f32 v[2:3], v[2:3], v[4:5]
	v_and_b32_e32 v72, 0xffff0000, v38
	v_pk_add_f32 v[0:1], v[0:1], v[2:3]
	v_and_b32_e32 v83, 0xffff0000, v43
	v_and_b32_e32 v82, 0xffff0000, v39
	v_add_f32_e32 v9, v0, v1
	v_lshlrev_b32_e32 v71, 16, v42
	v_lshlrev_b32_e32 v70, 16, v38
	v_lshlrev_b32_e32 v77, 16, v43
	v_lshlrev_b32_e32 v76, 16, v39
	v_pk_mul_f32 v[0:1], v[72:73], v[72:73]
	v_pk_mul_f32 v[2:3], v[82:83], v[82:83]
	v_and_b32_e32 v79, 0xffff0000, v44
	v_and_b32_e32 v78, 0xffff0000, v40
	v_and_b32_e32 v87, 0xffff0000, v45
	v_and_b32_e32 v86, 0xffff0000, v41
	v_pk_fma_f32 v[0:1], v[70:71], v[70:71], v[0:1]
	v_pk_fma_f32 v[2:3], v[76:77], v[76:77], v[2:3]
	v_lshlrev_b32_e32 v75, 16, v44
	v_lshlrev_b32_e32 v74, 16, v40
	v_lshlrev_b32_e32 v85, 16, v45
	v_lshlrev_b32_e32 v84, 16, v41
	v_pk_add_f32 v[0:1], v[0:1], v[2:3]
	v_pk_mul_f32 v[2:3], v[78:79], v[78:79]
	v_pk_mul_f32 v[4:5], v[86:87], v[86:87]
	v_pk_fma_f32 v[2:3], v[74:75], v[74:75], v[2:3]
	v_pk_fma_f32 v[4:5], v[84:85], v[84:85], v[4:5]
	v_and_b32_e32 v57, 0xffff0000, v50
	v_pk_add_f32 v[2:3], v[2:3], v[4:5]
	v_and_b32_e32 v56, 0xffff0000, v46
	v_pk_add_f32 v[0:1], v[0:1], v[2:3]
	v_and_b32_e32 v65, 0xffff0000, v51
	v_and_b32_e32 v64, 0xffff0000, v47
	v_add_f32_e32 v10, v0, v1
	v_lshlrev_b32_e32 v55, 16, v50
	v_lshlrev_b32_e32 v54, 16, v46
	v_lshlrev_b32_e32 v61, 16, v51
	v_lshlrev_b32_e32 v60, 16, v47
	v_pk_mul_f32 v[0:1], v[56:57], v[56:57]
	v_pk_mul_f32 v[2:3], v[64:65], v[64:65]
	v_and_b32_e32 v63, 0xffff0000, v52
	v_and_b32_e32 v62, 0xffff0000, v48
	v_and_b32_e32 v69, 0xffff0000, v53
	v_and_b32_e32 v68, 0xffff0000, v49
	v_pk_fma_f32 v[0:1], v[54:55], v[54:55], v[0:1]
	v_pk_fma_f32 v[2:3], v[60:61], v[60:61], v[2:3]
	v_lshlrev_b32_e32 v59, 16, v52
	v_lshlrev_b32_e32 v58, 16, v48
	v_lshlrev_b32_e32 v67, 16, v53
	v_lshlrev_b32_e32 v66, 16, v49
	v_pk_add_f32 v[0:1], v[0:1], v[2:3]
	v_pk_mul_f32 v[2:3], v[62:63], v[62:63]
	v_pk_mul_f32 v[4:5], v[68:69], v[68:69]
	v_pk_fma_f32 v[2:3], v[58:59], v[58:59], v[2:3]
	v_pk_fma_f32 v[4:5], v[66:67], v[66:67], v[4:5]
	v_and_b32_e32 v41, 0xffff0000, v124
	v_pk_add_f32 v[2:3], v[2:3], v[4:5]
	v_and_b32_e32 v40, 0xffff0000, v120
	v_pk_add_f32 v[0:1], v[0:1], v[2:3]
	v_and_b32_e32 v49, 0xffff0000, v125
	v_and_b32_e32 v48, 0xffff0000, v121
	v_add_f32_e32 v11, v0, v1
	v_lshlrev_b32_e32 v39, 16, v124
	v_lshlrev_b32_e32 v38, 16, v120
	v_lshlrev_b32_e32 v45, 16, v125
	v_lshlrev_b32_e32 v44, 16, v121
	v_pk_mul_f32 v[0:1], v[40:41], v[40:41]
	v_pk_mul_f32 v[2:3], v[48:49], v[48:49]
	v_and_b32_e32 v47, 0xffff0000, v126
	v_and_b32_e32 v46, 0xffff0000, v122
	v_and_b32_e32 v53, 0xffff0000, v127
	v_and_b32_e32 v52, 0xffff0000, v123
	v_pk_fma_f32 v[0:1], v[38:39], v[38:39], v[0:1]
	v_pk_fma_f32 v[2:3], v[44:45], v[44:45], v[2:3]
	v_lshlrev_b32_e32 v43, 16, v126
	v_lshlrev_b32_e32 v42, 16, v122
	v_lshlrev_b32_e32 v51, 16, v127
	v_lshlrev_b32_e32 v50, 16, v123
	v_pk_add_f32 v[0:1], v[0:1], v[2:3]
	v_pk_mul_f32 v[2:3], v[46:47], v[46:47]
	v_pk_mul_f32 v[4:5], v[52:53], v[52:53]
	v_pk_fma_f32 v[2:3], v[42:43], v[42:43], v[2:3]
	v_pk_fma_f32 v[4:5], v[50:51], v[50:51], v[4:5]
	v_and_b32_e32 v25, 0xffff0000, v132
	v_pk_add_f32 v[2:3], v[2:3], v[4:5]
	v_and_b32_e32 v24, 0xffff0000, v128
	v_pk_add_f32 v[0:1], v[0:1], v[2:3]
	v_and_b32_e32 v33, 0xffff0000, v133
	v_and_b32_e32 v32, 0xffff0000, v129
	v_add_f32_e32 v12, v0, v1
	v_lshlrev_b32_e32 v23, 16, v132
	v_lshlrev_b32_e32 v22, 16, v128
	v_lshlrev_b32_e32 v29, 16, v133
	v_lshlrev_b32_e32 v28, 16, v129
	v_pk_mul_f32 v[0:1], v[24:25], v[24:25]
	v_pk_mul_f32 v[2:3], v[32:33], v[32:33]
	v_and_b32_e32 v31, 0xffff0000, v134
	v_and_b32_e32 v30, 0xffff0000, v130
	v_and_b32_e32 v37, 0xffff0000, v135
	v_and_b32_e32 v36, 0xffff0000, v131
	v_pk_fma_f32 v[0:1], v[22:23], v[22:23], v[0:1]
	v_pk_fma_f32 v[2:3], v[28:29], v[28:29], v[2:3]
	v_lshlrev_b32_e32 v27, 16, v134
	v_lshlrev_b32_e32 v26, 16, v130
	v_lshlrev_b32_e32 v35, 16, v135
	v_lshlrev_b32_e32 v34, 16, v131
	v_pk_add_f32 v[0:1], v[0:1], v[2:3]
	v_pk_mul_f32 v[2:3], v[30:31], v[30:31]
	v_pk_mul_f32 v[4:5], v[36:37], v[36:37]
	v_pk_fma_f32 v[2:3], v[26:27], v[26:27], v[2:3]
	v_pk_fma_f32 v[4:5], v[34:35], v[34:35], v[4:5]
	ds_bpermute_b32 v13, v180, v11
	v_pk_add_f32 v[2:3], v[2:3], v[4:5]
	ds_bpermute_b32 v4, v180, v9
	v_pk_add_f32 v[0:1], v[0:1], v[2:3]
	ds_bpermute_b32 v3, v180, v8
	v_add_f32_e32 v0, v0, v1
	ds_bpermute_b32 v1, v180, v6
	ds_bpermute_b32 v15, v180, v0
	ds_bpermute_b32 v2, v180, v7
	ds_bpermute_b32 v5, v180, v10
	ds_bpermute_b32 v14, v180, v12
	s_waitcnt lgkmcnt(0)
	v_add_f32_e32 v1, v6, v1
	s_waitcnt lgkmcnt(3)
	v_add_f32_e32 v0, v0, v15
	v_add_f32_e32 v3, v8, v3
	ds_bpermute_b32 v8, v181, v1
	ds_bpermute_b32 v15, v181, v0
	s_waitcnt lgkmcnt(4)
	v_add_f32_e32 v2, v7, v2
	v_add_f32_e32 v4, v9, v4
	s_waitcnt lgkmcnt(3)
	v_add_f32_e32 v5, v10, v5
	v_add_f32_e32 v6, v11, v13
	s_waitcnt lgkmcnt(2)
; template <int NR> __device__ __forceinline__ void wave_sumN(float (&s)[NR]) {
; #pragma unroll
;     for (int o = 1; o < 64; o <<= 1) {
;         float t[NR];
; #pragma unroll
;         for (int r = 0; r < NR; ++r) t[r] = __shfl_xor(s[r], o);
; #pragma unroll
;         for (int r = 0; r < NR; ++r) s[r] += t[r];
;     }
; }
; template <bool X_F32> __device__ __forceinline__ void phase_norm_mod(const Ctx& C, const void* xin, const float* modl, int shift_idx, int scale_idx) {
;     ...
;             f32x4 a[4], g[4];
; #pragma unroll
;             for (int j = 0; j < 2; ++j)
; #pragma unroll
;                 for (int q = 0; q < 2; ++q) { a[2 * j + q] = *(const f32x4*)(modl + (size_t)b * NMOD + shift_idx * DM + 512 * j + 8 * lane + 4 * q);
;                     g[2 * j + q] = *(const f32x4*)(modl + (size_t)b * NMOD + scale_idx * DM + 512 * j + 8 * lane + 4 * q) + 1.0f; }
	v_add_f32_e32 v7, v12, v14
	ds_bpermute_b32 v9, v181, v2
	ds_bpermute_b32 v10, v181, v3
	ds_bpermute_b32 v11, v181, v4
	ds_bpermute_b32 v12, v181, v5
	ds_bpermute_b32 v13, v181, v6
	ds_bpermute_b32 v14, v181, v7
	s_waitcnt lgkmcnt(7)
	v_add_f32_e32 v1, v1, v8
	s_waitcnt lgkmcnt(6)
	v_add_f32_e32 v0, v0, v15
	ds_bpermute_b32 v8, v182, v1
	ds_bpermute_b32 v15, v182, v0
	s_waitcnt lgkmcnt(7)
	v_add_f32_e32 v2, v2, v9
	s_waitcnt lgkmcnt(6)
	v_add_f32_e32 v3, v3, v10
	s_waitcnt lgkmcnt(5)
	v_add_f32_e32 v4, v4, v11
	s_waitcnt lgkmcnt(4)
	v_add_f32_e32 v5, v5, v12
	s_waitcnt lgkmcnt(3)
	v_add_f32_e32 v6, v6, v13
	s_waitcnt lgkmcnt(2)
	v_add_f32_e32 v7, v7, v14
	ds_bpermute_b32 v9, v182, v2
	ds_bpermute_b32 v10, v182, v3
	ds_bpermute_b32 v11, v182, v4
	ds_bpermute_b32 v12, v182, v5
	ds_bpermute_b32 v13, v182, v6
	ds_bpermute_b32 v14, v182, v7
	s_waitcnt lgkmcnt(7)
	v_add_f32_e32 v1, v1, v8
	s_waitcnt lgkmcnt(6)
	v_add_f32_e32 v0, v0, v15
	ds_bpermute_b32 v8, v183, v1
	ds_bpermute_b32 v15, v183, v0
	s_waitcnt lgkmcnt(7)
	v_add_f32_e32 v2, v2, v9
	s_waitcnt lgkmcnt(6)
	v_add_f32_e32 v3, v3, v10
	s_waitcnt lgkmcnt(5)
	v_add_f32_e32 v4, v4, v11
	s_waitcnt lgkmcnt(4)
	v_add_f32_e32 v5, v5, v12
	s_waitcnt lgkmcnt(3)
	v_add_f32_e32 v6, v6, v13
	s_waitcnt lgkmcnt(2)
	v_add_f32_e32 v7, v7, v14
	ds_bpermute_b32 v9, v183, v2
	ds_bpermute_b32 v10, v183, v3
	ds_bpermute_b32 v11, v183, v4
	ds_bpermute_b32 v12, v183, v5
	ds_bpermute_b32 v13, v183, v6
	ds_bpermute_b32 v14, v183, v7
	s_waitcnt lgkmcnt(7)
	v_add_f32_e32 v1, v1, v8
	s_waitcnt lgkmcnt(6)
	v_add_f32_e32 v0, v0, v15
	ds_bpermute_b32 v8, v184, v1
	ds_bpermute_b32 v15, v184, v0
	s_waitcnt lgkmcnt(7)
	v_add_f32_e32 v2, v2, v9
	s_waitcnt lgkmcnt(6)
	v_add_f32_e32 v3, v3, v10
	s_waitcnt lgkmcnt(5)
	v_add_f32_e32 v4, v4, v11
	s_waitcnt lgkmcnt(4)
	v_add_f32_e32 v5, v5, v12
	s_waitcnt lgkmcnt(3)
	v_add_f32_e32 v6, v6, v13
	s_waitcnt lgkmcnt(2)
	v_add_f32_e32 v7, v7, v14
	ds_bpermute_b32 v9, v184, v2
	ds_bpermute_b32 v10, v184, v3
	ds_bpermute_b32 v11, v184, v4
	ds_bpermute_b32 v12, v184, v5
	ds_bpermute_b32 v13, v184, v6
	ds_bpermute_b32 v14, v184, v7
	s_waitcnt lgkmcnt(7)
	v_add_f32_e32 v1, v1, v8
	s_waitcnt lgkmcnt(6)
	v_add_f32_e32 v0, v0, v15
	ds_bpermute_b32 v8, v185, v1
	ds_bpermute_b32 v15, v185, v0
	s_waitcnt lgkmcnt(7)
	v_add_f32_e32 v2, v2, v9
	s_waitcnt lgkmcnt(6)
	v_add_f32_e32 v3, v3, v10
	s_waitcnt lgkmcnt(5)
	v_add_f32_e32 v4, v4, v11
	s_waitcnt lgkmcnt(4)
	v_add_f32_e32 v5, v5, v12
	s_waitcnt lgkmcnt(3)
	v_add_f32_e32 v6, v6, v13
	s_waitcnt lgkmcnt(2)
	v_add_f32_e32 v7, v7, v14
	ds_bpermute_b32 v9, v185, v2
	ds_bpermute_b32 v10, v185, v3
	ds_bpermute_b32 v11, v185, v4
	ds_bpermute_b32 v12, v185, v5
	ds_bpermute_b32 v13, v185, v6
	ds_bpermute_b32 v14, v185, v7
	s_waitcnt lgkmcnt(7)
	v_add_f32_e32 v80, v1, v8
	s_waitcnt lgkmcnt(6)
	v_add_f32_e32 v186, v0, v15
	v_lshl_add_u64 v[0:1], v[18:19], 2, s[2:3]
	s_mov_b64 s[2:3], 0x3000
	v_lshl_add_u64 v[120:121], v[0:1], 0, s[2:3]
	s_mov_b64 s[2:3], 0x4000
	v_lshl_add_u64 v[122:123], v[0:1], 0, s[2:3]
	s_movk_i32 s2, 0x4000
	v_add_co_u32_e32 v0, vcc, s2, v0
	s_waitcnt lgkmcnt(5)
	v_add_f32_e32 v192, v2, v9
	v_addc_co_u32_e32 v1, vcc, 0, v1, vcc
	s_waitcnt lgkmcnt(4)
	v_add_f32_e32 v191, v3, v10
	s_waitcnt lgkmcnt(3)
	v_add_f32_e32 v190, v4, v11
	s_waitcnt lgkmcnt(2)
	v_add_f32_e32 v189, v5, v12
	s_waitcnt lgkmcnt(1)
	v_add_f32_e32 v188, v6, v13
	s_waitcnt lgkmcnt(0)
	v_add_f32_e32 v187, v7, v14
	global_load_dwordx4 v[12:15], v[0:1], off offset:-4096
	global_load_dwordx4 v[8:11], v[120:121], off offset:16
	s_nop 0
	global_load_dwordx4 v[0:3], v[0:1], off
	s_nop 0
	global_load_dwordx4 v[4:7], v[122:123], off offset:16
	v_fmamk_f32 v80, v80, 0x3a800000, v214
	v_cmp_gt_f32_e32 vcc, s19, v80
	v_mul_f32_e32 v193, 0x4f800000, v80
	v_mov_b32_e32 v201, v160
	v_cndmask_b32_e32 v80, v80, v193, vcc
	v_sqrt_f32_e32 v193, v80
	v_mov_b32_e32 v203, v178
	v_mov_b32_e32 v160, v157
	v_mov_b32_e32 v178, v177
	v_mov_b32_e32 v200, v156
	v_mov_b32_e32 v202, v176
	s_waitcnt vmcnt(1)
	v_pk_add_f32 v[132:133], v[2:3], 1.0 op_sel_hi:[1,0]
	v_pk_add_f32 v[134:135], v[0:1], 1.0 op_sel_hi:[1,0]
	s_waitcnt vmcnt(0)
	v_pk_add_f32 v[128:129], v[6:7], 1.0 op_sel_hi:[1,0]
	v_pk_add_f32 v[130:131], v[4:5], 1.0 op_sel_hi:[1,0]
	global_load_dwordx4 v[0:3], v[120:121], off offset:2064
	global_load_dwordx4 v[4:7], v[120:121], off offset:2048
	global_load_dwordx4 v[194:197], v[122:123], off offset:2064
	s_nop 0
	global_load_dwordx4 v[120:123], v[122:123], off offset:2048
	s_waitcnt vmcnt(0)
; __device__ __forceinline__ unsigned pk2(float lo, float hi) { return pg8::cvt_pk_bf16(lo, hi); }
; __device__ __forceinline__ void unpack8(const u32x4 w, f32x4& a, f32x4& c) { a = (f32x4){bf_lo(w.x), bf_hi(w.x), bf_lo(w.y), bf_hi(w.y)}; c = (f32x4){bf_lo(w.z), bf_hi(w.z), bf_lo(w.w), bf_hi(w.w)}; }
; template <bool X_F32> __device__ __forceinline__ void phase_norm_mod(const Ctx& C, const void* xin, const float* modl, int shift_idx, int scale_idx) {
;     ...
; #pragma unroll
;             for (int r = 0; r < NR; ++r) { const float rs = 1.0f / sqrtf(s[r] * (1.f / DM) + EPS);
; #pragma unroll
;                 for (int j = 0; j < 2; ++j) { f32x4 t0, t1; unpack8(raw[r][j], t0, t1);
;                     const f32x4 y0 = t0 * rs * g[2 * j] + a[2 * j], y1 = t1 * rs * g[2 * j + 1] + a[2 * j + 1];
;                     u32x4 w; w.x = pk2(y0.x, y0.y); w.y = pk2(y0.z, y0.w); w.z = pk2(y1.x, y1.y); w.w = pk2(y1.z, y1.w);
;                     ((u32x4*)(H + (size_t)(m0 + r) * DM + 512 * j))[lane] = w; } }
	v_pk_add_f32 v[124:125], v[122:123], 1.0 op_sel_hi:[1,0]
	v_pk_add_f32 v[122:123], v[194:195], 1.0 op_sel_hi:[1,0]
	v_add_u32_e32 v194, -1, v193
	v_fma_f32 v195, -v194, v193, v80
	v_cmp_ge_f32_e64 s[36:37], 0, v195
	v_add_u32_e32 v195, 1, v193
	v_pk_add_f32 v[126:127], v[120:121], 1.0 op_sel_hi:[1,0]
	v_cndmask_b32_e64 v194, v193, v194, s[36:37]
	v_fma_f32 v193, -v195, v193, v80
	v_cmp_lt_f32_e64 s[36:37], 0, v193
	v_pk_add_f32 v[120:121], v[196:197], 1.0 op_sel_hi:[1,0]
	s_nop 0
	v_cndmask_b32_e64 v193, v194, v195, s[36:37]
	v_mul_f32_e32 v194, 0x37800000, v193
	v_cndmask_b32_e32 v193, v193, v194, vcc
	v_cmp_class_f32_e32 vcc, v80, v215
	s_nop 1
	v_cndmask_b32_e32 v80, v193, v80, vcc
	v_div_scale_f32 v193, s[2:3], v80, v80, 1.0
	v_rcp_f32_e32 v194, v193
	s_nop 0
	v_fma_f32 v195, -v193, v194, 1.0
	v_fmac_f32_e32 v194, v195, v194
	v_div_scale_f32 v195, vcc, 1.0, v80, 1.0
	v_mul_f32_e32 v196, v195, v194
	v_fma_f32 v197, -v193, v196, v195
	v_fmac_f32_e32 v196, v197, v194
	v_fma_f32 v193, -v193, v196, v195
	v_div_fmas_f32 v193, v193, v194, v196
	v_div_fixup_f32 v80, v193, v80, 1.0
	v_mov_b32_e32 v195, v154
	v_mov_b32_e32 v197, v174
	v_mov_b32_e32 v154, v153
	v_mov_b32_e32 v174, v159
	v_mov_b32_e32 v194, v152
	v_mov_b32_e32 v196, v158
	v_pk_mul_f32 v[152:153], v[80:81], v[154:155] op_sel_hi:[0,1]
	v_pk_mul_f32 v[154:155], v[80:81], v[174:175] op_sel_hi:[0,1]
	v_pk_mul_f32 v[156:157], v[80:81], v[160:161] op_sel_hi:[0,1]
	v_pk_mul_f32 v[158:159], v[80:81], v[178:179] op_sel_hi:[0,1]
	v_pk_fma_f32 v[154:155], v[154:155], v[124:125], v[6:7]
	v_pk_fma_f32 v[152:153], v[152:153], v[126:127], v[4:5]
	v_pk_fma_f32 v[158:159], v[158:159], v[120:121], v[2:3]
	v_pk_fma_f32 v[156:157], v[156:157], v[122:123], v[0:1]
	v_pk_mul_f32 v[194:195], v[80:81], v[194:195] op_sel_hi:[0,1]
	v_pk_mul_f32 v[196:197], v[80:81], v[196:197] op_sel_hi:[0,1]
	v_pk_mul_f32 v[200:201], v[80:81], v[200:201] op_sel_hi:[0,1]
	v_pk_mul_f32 v[202:203], v[80:81], v[202:203] op_sel_hi:[0,1]
	v_cvt_pk_bf16_f32 v152, v152, v153
	v_cvt_pk_bf16_f32 v153, v154, v155
	v_cvt_pk_bf16_f32 v154, v156, v157
	v_cvt_pk_bf16_f32 v155, v158, v159
	v_fmamk_f32 v80, v192, 0x3a800000, v214
	flat_store_dwordx4 v[198:199], v[152:155] offset:1024
	v_cmp_gt_f32_e32 vcc, s19, v80
	v_mov_b32_e32 v159, v144
	v_mul_f32_e32 v152, 0x4f800000, v80
	v_cndmask_b32_e32 v80, v80, v152, vcc
	v_sqrt_f32_e32 v152, v80
	v_mov_b32_e32 v161, v150
	v_mov_b32_e32 v144, v141
	v_mov_b32_e32 v150, v149
	v_add_u32_e32 v153, -1, v152
	v_fma_f32 v154, -v153, v152, v80
	v_cmp_ge_f32_e64 s[36:37], 0, v154
	v_add_u32_e32 v154, 1, v152
	v_mov_b32_e32 v158, v140
	v_cndmask_b32_e64 v153, v152, v153, s[36:37]
	v_fma_f32 v152, -v154, v152, v80
	v_cmp_lt_f32_e64 s[36:37], 0, v152
	v_mov_b32_e32 v160, v148
	v_pk_fma_f32 v[196:197], v[196:197], v[132:133], v[14:15]
	v_cndmask_b32_e64 v152, v153, v154, s[36:37]
	v_mul_f32_e32 v153, 0x37800000, v152
	v_cndmask_b32_e32 v152, v152, v153, vcc
	v_cmp_class_f32_e32 vcc, v80, v215
	v_pk_fma_f32 v[194:195], v[194:195], v[134:135], v[12:13]
	v_pk_fma_f32 v[202:203], v[202:203], v[128:129], v[10:11]
	v_cndmask_b32_e32 v80, v152, v80, vcc
	v_div_scale_f32 v152, s[2:3], v80, v80, 1.0
	v_rcp_f32_e32 v153, v152
	v_pk_fma_f32 v[200:201], v[200:201], v[130:131], v[8:9]
	v_cvt_pk_bf16_f32 v194, v194, v195
	v_cvt_pk_bf16_f32 v195, v196, v197
	v_fma_f32 v154, -v152, v153, 1.0
	v_fmac_f32_e32 v153, v154, v153
	v_div_scale_f32 v154, vcc, 1.0, v80, 1.0
	v_mul_f32_e32 v155, v154, v153
	v_fma_f32 v156, -v152, v155, v154
	v_fmac_f32_e32 v155, v156, v153
	v_fma_f32 v152, -v152, v155, v154
	v_div_fmas_f32 v152, v152, v153, v155
	v_div_fixup_f32 v80, v152, v80, 1.0
	v_mov_b32_e32 v153, v138
	v_mov_b32_e32 v155, v146
	v_mov_b32_e32 v138, v137
	v_mov_b32_e32 v146, v143
	v_mov_b32_e32 v152, v136
	v_mov_b32_e32 v154, v142
	v_pk_mul_f32 v[136:137], v[80:81], v[138:139] op_sel_hi:[0,1]
	v_pk_mul_f32 v[138:139], v[80:81], v[146:147] op_sel_hi:[0,1]
	v_pk_mul_f32 v[140:141], v[80:81], v[144:145] op_sel_hi:[0,1]
	v_pk_mul_f32 v[142:143], v[80:81], v[150:151] op_sel_hi:[0,1]
	v_pk_fma_f32 v[138:139], v[138:139], v[124:125], v[6:7]
	v_pk_fma_f32 v[136:137], v[136:137], v[126:127], v[4:5]
	v_pk_fma_f32 v[142:143], v[142:143], v[120:121], v[2:3]
	v_pk_fma_f32 v[140:141], v[140:141], v[122:123], v[0:1]
	v_lshl_add_u64 v[156:157], v[20:21], 0, s[14:15]
	v_pk_mul_f32 v[152:153], v[80:81], v[152:153] op_sel_hi:[0,1]
	v_pk_mul_f32 v[154:155], v[80:81], v[154:155] op_sel_hi:[0,1]
	v_pk_mul_f32 v[158:159], v[80:81], v[158:159] op_sel_hi:[0,1]
	v_pk_mul_f32 v[160:161], v[80:81], v[160:161] op_sel_hi:[0,1]
	v_cvt_pk_bf16_f32 v136, v136, v137
	v_cvt_pk_bf16_f32 v137, v138, v139
	v_cvt_pk_bf16_f32 v138, v140, v141
	v_cvt_pk_bf16_f32 v139, v142, v143
	v_fmamk_f32 v80, v191, 0x3a800000, v214
	flat_store_dwordx4 v[156:157], v[136:139] offset:1024
	v_cmp_gt_f32_e32 vcc, s19, v80
	v_mov_b32_e32 v143, v112
	v_mul_f32_e32 v136, 0x4f800000, v80
	v_cndmask_b32_e32 v80, v80, v136, vcc
	v_sqrt_f32_e32 v136, v80
	v_mov_b32_e32 v145, v118
	v_mov_b32_e32 v112, v109
	v_mov_b32_e32 v118, v117
	v_add_u32_e32 v137, -1, v136
	v_fma_f32 v138, -v137, v136, v80
	v_cmp_ge_f32_e64 s[36:37], 0, v138
	v_add_u32_e32 v138, 1, v136
	v_mov_b32_e32 v142, v108
	v_cndmask_b32_e64 v137, v136, v137, s[36:37]
	v_fma_f32 v136, -v138, v136, v80
	v_cmp_lt_f32_e64 s[36:37], 0, v136
	v_mov_b32_e32 v144, v116
	v_pk_fma_f32 v[154:155], v[132:133], v[154:155], v[14:15]
	v_cndmask_b32_e64 v136, v137, v138, s[36:37]
	v_mul_f32_e32 v137, 0x37800000, v136
	v_cndmask_b32_e32 v136, v136, v137, vcc
	v_cmp_class_f32_e32 vcc, v80, v215
	v_pk_fma_f32 v[152:153], v[134:135], v[152:153], v[12:13]
; __device__ __forceinline__ unsigned pk2(float lo, float hi) { return pg8::cvt_pk_bf16(lo, hi); }
; __device__ __forceinline__ void unpack8(const u32x4 w, f32x4& a, f32x4& c) { a = (f32x4){bf_lo(w.x), bf_hi(w.x), bf_lo(w.y), bf_hi(w.y)}; c = (f32x4){bf_lo(w.z), bf_hi(w.z), bf_lo(w.w), bf_hi(w.w)}; }
; template <bool X_F32> __device__ __forceinline__ void phase_norm_mod(const Ctx& C, const void* xin, const float* modl, int shift_idx, int scale_idx) {
;     ...
; #pragma unroll
;             for (int r = 0; r < NR; ++r) { const float rs = 1.0f / sqrtf(s[r] * (1.f / DM) + EPS);
; #pragma unroll
;                 for (int j = 0; j < 2; ++j) { f32x4 t0, t1; unpack8(raw[r][j], t0, t1);
;                     const f32x4 y0 = t0 * rs * g[2 * j] + a[2 * j], y1 = t1 * rs * g[2 * j + 1] + a[2 * j + 1];
;                     u32x4 w; w.x = pk2(y0.x, y0.y); w.y = pk2(y0.z, y0.w); w.z = pk2(y1.x, y1.y); w.w = pk2(y1.z, y1.w);
;                     ((u32x4*)(H + (size_t)(m0 + r) * DM + 512 * j))[lane] = w; } }
	v_pk_fma_f32 v[160:161], v[160:161], v[128:129], v[10:11]
	v_cndmask_b32_e32 v80, v136, v80, vcc
	v_div_scale_f32 v136, s[2:3], v80, v80, 1.0
	v_rcp_f32_e32 v137, v136
	v_pk_fma_f32 v[158:159], v[158:159], v[130:131], v[8:9]
	v_cvt_pk_bf16_f32 v196, v200, v201
	v_cvt_pk_bf16_f32 v197, v202, v203
	v_fma_f32 v138, -v136, v137, 1.0
	v_fmac_f32_e32 v137, v138, v137
	v_div_scale_f32 v138, vcc, 1.0, v80, 1.0
	v_mul_f32_e32 v139, v138, v137
	v_fma_f32 v140, -v136, v139, v138
	v_fmac_f32_e32 v139, v140, v137
	v_fma_f32 v136, -v136, v139, v138
	v_div_fmas_f32 v136, v136, v137, v139
	v_div_fixup_f32 v80, v136, v80, 1.0
	v_mov_b32_e32 v137, v106
	v_mov_b32_e32 v139, v114
	v_mov_b32_e32 v106, v105
	v_mov_b32_e32 v114, v111
	v_mov_b32_e32 v136, v104
	v_mov_b32_e32 v138, v110
	v_pk_mul_f32 v[104:105], v[80:81], v[106:107] op_sel_hi:[0,1]
	v_pk_mul_f32 v[106:107], v[80:81], v[114:115] op_sel_hi:[0,1]
	v_pk_mul_f32 v[108:109], v[80:81], v[112:113] op_sel_hi:[0,1]
	v_pk_mul_f32 v[110:111], v[80:81], v[118:119] op_sel_hi:[0,1]
	v_pk_fma_f32 v[106:107], v[106:107], v[124:125], v[6:7]
	v_pk_fma_f32 v[104:105], v[104:105], v[126:127], v[4:5]
	v_pk_fma_f32 v[110:111], v[110:111], v[120:121], v[2:3]
	v_pk_fma_f32 v[108:109], v[108:109], v[122:123], v[0:1]
	v_lshl_add_u64 v[140:141], v[20:21], 0, s[4:5]
	v_pk_mul_f32 v[136:137], v[80:81], v[136:137] op_sel_hi:[0,1]
	v_pk_mul_f32 v[138:139], v[80:81], v[138:139] op_sel_hi:[0,1]
	v_pk_mul_f32 v[142:143], v[80:81], v[142:143] op_sel_hi:[0,1]
	v_pk_mul_f32 v[144:145], v[80:81], v[144:145] op_sel_hi:[0,1]
	v_cvt_pk_bf16_f32 v104, v104, v105
	v_cvt_pk_bf16_f32 v105, v106, v107
	v_cvt_pk_bf16_f32 v106, v108, v109
	v_cvt_pk_bf16_f32 v107, v110, v111
	v_fmamk_f32 v80, v190, 0x3a800000, v214
	flat_store_dwordx4 v[140:141], v[104:107] offset:1024
	v_cmp_gt_f32_e32 vcc, s19, v80
	v_mov_b32_e32 v111, v96
	v_mul_f32_e32 v104, 0x4f800000, v80
	v_cndmask_b32_e32 v80, v80, v104, vcc
	v_sqrt_f32_e32 v104, v80
	v_mov_b32_e32 v113, v102
	v_mov_b32_e32 v96, v93
	v_mov_b32_e32 v102, v101
	v_add_u32_e32 v105, -1, v104
	v_fma_f32 v106, -v105, v104, v80
	v_cmp_ge_f32_e64 s[36:37], 0, v106
	v_add_u32_e32 v106, 1, v104
	v_mov_b32_e32 v110, v92
	v_cndmask_b32_e64 v105, v104, v105, s[36:37]
	v_fma_f32 v104, -v106, v104, v80
	v_cmp_lt_f32_e64 s[36:37], 0, v104
	v_mov_b32_e32 v112, v100
	v_pk_fma_f32 v[138:139], v[132:133], v[138:139], v[14:15]
	v_cndmask_b32_e64 v104, v105, v106, s[36:37]
	v_mul_f32_e32 v105, 0x37800000, v104
	v_cndmask_b32_e32 v104, v104, v105, vcc
	v_cmp_class_f32_e32 vcc, v80, v215
	v_pk_fma_f32 v[136:137], v[134:135], v[136:137], v[12:13]
	v_pk_fma_f32 v[144:145], v[144:145], v[128:129], v[10:11]
	v_cndmask_b32_e32 v80, v104, v80, vcc
	v_div_scale_f32 v104, s[2:3], v80, v80, 1.0
	v_rcp_f32_e32 v105, v104
	v_pk_fma_f32 v[142:143], v[142:143], v[130:131], v[8:9]
	v_cvt_pk_bf16_f32 v152, v152, v153
	v_cvt_pk_bf16_f32 v153, v154, v155
	v_fma_f32 v106, -v104, v105, 1.0
	v_fmac_f32_e32 v105, v106, v105
	v_div_scale_f32 v106, vcc, 1.0, v80, 1.0
	v_mul_f32_e32 v107, v106, v105
	v_fma_f32 v108, -v104, v107, v106
	v_fmac_f32_e32 v107, v108, v105
	v_fma_f32 v104, -v104, v107, v106
	v_div_fmas_f32 v104, v104, v105, v107
	v_div_fixup_f32 v80, v104, v80, 1.0
	v_mov_b32_e32 v105, v90
	v_mov_b32_e32 v107, v98
	v_mov_b32_e32 v90, v89
	v_mov_b32_e32 v98, v95
	v_mov_b32_e32 v104, v88
	v_mov_b32_e32 v106, v94
	v_pk_mul_f32 v[88:89], v[80:81], v[90:91] op_sel_hi:[0,1]
	v_pk_mul_f32 v[90:91], v[80:81], v[98:99] op_sel_hi:[0,1]
	v_pk_mul_f32 v[92:93], v[80:81], v[96:97] op_sel_hi:[0,1]
	v_pk_mul_f32 v[94:95], v[80:81], v[102:103] op_sel_hi:[0,1]
	v_pk_fma_f32 v[90:91], v[90:91], v[124:125], v[6:7]
	v_pk_fma_f32 v[88:89], v[88:89], v[126:127], v[4:5]
	v_pk_fma_f32 v[94:95], v[94:95], v[120:121], v[2:3]
	v_pk_fma_f32 v[92:93], v[92:93], v[122:123], v[0:1]
	v_lshl_add_u64 v[108:109], v[20:21], 0, s[46:47]
	v_pk_mul_f32 v[104:105], v[80:81], v[104:105] op_sel_hi:[0,1]
	v_pk_mul_f32 v[106:107], v[80:81], v[106:107] op_sel_hi:[0,1]
	v_pk_mul_f32 v[110:111], v[80:81], v[110:111] op_sel_hi:[0,1]
	v_pk_mul_f32 v[112:113], v[80:81], v[112:113] op_sel_hi:[0,1]
	v_cvt_pk_bf16_f32 v88, v88, v89
	v_cvt_pk_bf16_f32 v89, v90, v91
	v_cvt_pk_bf16_f32 v90, v92, v93
	v_cvt_pk_bf16_f32 v91, v94, v95
	v_fmamk_f32 v80, v189, 0x3a800000, v214
	flat_store_dwordx4 v[108:109], v[88:91] offset:1024
	v_cmp_gt_f32_e32 vcc, s19, v80
	v_mov_b32_e32 v95, v78
	v_mul_f32_e32 v88, 0x4f800000, v80
	v_cndmask_b32_e32 v80, v80, v88, vcc
	v_sqrt_f32_e32 v88, v80
	v_mov_b32_e32 v97, v86
	v_mov_b32_e32 v78, v75
	v_mov_b32_e32 v86, v85
	v_add_u32_e32 v89, -1, v88
	v_fma_f32 v90, -v89, v88, v80
	v_cmp_ge_f32_e64 s[36:37], 0, v90
	v_add_u32_e32 v90, 1, v88
	v_mov_b32_e32 v94, v74
	v_cndmask_b32_e64 v89, v88, v89, s[36:37]
	v_fma_f32 v88, -v90, v88, v80
	v_cmp_lt_f32_e64 s[36:37], 0, v88
	v_pk_fma_f32 v[106:107], v[132:133], v[106:107], v[14:15]
	v_pk_fma_f32 v[104:105], v[134:135], v[104:105], v[12:13]
	v_cndmask_b32_e64 v88, v89, v90, s[36:37]
	v_mul_f32_e32 v89, 0x37800000, v88
	v_cndmask_b32_e32 v88, v88, v89, vcc
	v_cmp_class_f32_e32 vcc, v80, v215
	v_mov_b32_e32 v96, v84
	v_pk_fma_f32 v[112:113], v[128:129], v[112:113], v[10:11]
	v_cndmask_b32_e32 v80, v88, v80, vcc
	v_div_scale_f32 v88, s[2:3], v80, v80, 1.0
	v_rcp_f32_e32 v89, v88
	v_pk_fma_f32 v[110:111], v[130:131], v[110:111], v[8:9]
	v_cvt_pk_bf16_f32 v154, v158, v159
	v_cvt_pk_bf16_f32 v155, v160, v161
	v_fma_f32 v90, -v88, v89, 1.0
	v_fmac_f32_e32 v89, v90, v89
	v_div_scale_f32 v90, vcc, 1.0, v80, 1.0
	v_mul_f32_e32 v91, v90, v89
	v_fma_f32 v92, -v88, v91, v90
	v_fmac_f32_e32 v91, v92, v89
	v_fma_f32 v88, -v88, v91, v90
; __device__ __forceinline__ unsigned pk2(float lo, float hi) { return pg8::cvt_pk_bf16(lo, hi); }
; __device__ __forceinline__ void unpack8(const u32x4 w, f32x4& a, f32x4& c) { a = (f32x4){bf_lo(w.x), bf_hi(w.x), bf_lo(w.y), bf_hi(w.y)}; c = (f32x4){bf_lo(w.z), bf_hi(w.z), bf_lo(w.w), bf_hi(w.w)}; }
; template <bool X_F32> __device__ __forceinline__ void phase_norm_mod(const Ctx& C, const void* xin, const float* modl, int shift_idx, int scale_idx) {
;     ...
; #pragma unroll
;             for (int r = 0; r < NR; ++r) { const float rs = 1.0f / sqrtf(s[r] * (1.f / DM) + EPS);
; #pragma unroll
;                 for (int j = 0; j < 2; ++j) { f32x4 t0, t1; unpack8(raw[r][j], t0, t1);
;                     const f32x4 y0 = t0 * rs * g[2 * j] + a[2 * j], y1 = t1 * rs * g[2 * j + 1] + a[2 * j + 1];
;                     u32x4 w; w.x = pk2(y0.x, y0.y); w.y = pk2(y0.z, y0.w); w.z = pk2(y1.x, y1.y); w.w = pk2(y1.z, y1.w);
;                     ((u32x4*)(H + (size_t)(m0 + r) * DM + 512 * j))[lane] = w; } }
	v_div_fmas_f32 v88, v88, v89, v91
	v_div_fixup_f32 v80, v88, v80, 1.0
	v_mov_b32_e32 v89, v72
	v_mov_b32_e32 v91, v82
	v_mov_b32_e32 v72, v71
	v_mov_b32_e32 v82, v77
	v_mov_b32_e32 v88, v70
	v_mov_b32_e32 v90, v76
	v_pk_mul_f32 v[70:71], v[80:81], v[72:73] op_sel_hi:[0,1]
	v_pk_mul_f32 v[72:73], v[80:81], v[82:83] op_sel_hi:[0,1]
	v_pk_mul_f32 v[74:75], v[80:81], v[78:79] op_sel_hi:[0,1]
	v_pk_mul_f32 v[76:77], v[80:81], v[86:87] op_sel_hi:[0,1]
	v_pk_fma_f32 v[72:73], v[72:73], v[124:125], v[6:7]
	v_pk_fma_f32 v[70:71], v[70:71], v[126:127], v[4:5]
	v_pk_fma_f32 v[76:77], v[76:77], v[120:121], v[2:3]
	v_pk_fma_f32 v[74:75], v[74:75], v[122:123], v[0:1]
	v_lshl_add_u64 v[92:93], v[20:21], 0, s[44:45]
	v_cvt_pk_bf16_f32 v70, v70, v71
	v_cvt_pk_bf16_f32 v71, v72, v73
	v_cvt_pk_bf16_f32 v72, v74, v75
	v_cvt_pk_bf16_f32 v73, v76, v77
	flat_store_dwordx4 v[92:93], v[70:73] offset:1024
	v_mov_b32_e32 v79, v62
	v_mov_b32_e32 v83, v68
	v_fmamk_f32 v70, v188, 0x3a800000, v214
	v_cmp_gt_f32_e32 vcc, s19, v70
	v_mul_f32_e32 v71, 0x4f800000, v70
	v_mov_b32_e32 v62, v59
	v_cndmask_b32_e32 v70, v70, v71, vcc
	v_sqrt_f32_e32 v71, v70
	v_mov_b32_e32 v68, v67
	v_mov_b32_e32 v78, v58
	v_lshl_add_u64 v[76:77], v[20:21], 0, s[42:43]
	v_add_u32_e32 v72, -1, v71
	v_fma_f32 v73, -v72, v71, v70
	v_cmp_ge_f32_e64 s[36:37], 0, v73
	v_add_u32_e32 v73, 1, v71
	v_pk_mul_f32 v[88:89], v[80:81], v[88:89] op_sel_hi:[0,1]
	v_cndmask_b32_e64 v72, v71, v72, s[36:37]
	v_fma_f32 v71, -v73, v71, v70
	v_cmp_lt_f32_e64 s[36:37], 0, v71
	v_pk_mul_f32 v[90:91], v[80:81], v[90:91] op_sel_hi:[0,1]
	v_pk_fma_f32 v[90:91], v[132:133], v[90:91], v[14:15]
	v_cndmask_b32_e64 v71, v72, v73, s[36:37]
	v_mul_f32_e32 v72, 0x37800000, v71
	v_cndmask_b32_e32 v71, v71, v72, vcc
	v_cmp_class_f32_e32 vcc, v70, v215
	v_pk_fma_f32 v[88:89], v[134:135], v[88:89], v[12:13]
	v_mov_b32_e32 v82, v66
	v_cndmask_b32_e32 v70, v71, v70, vcc
	v_div_scale_f32 v71, s[2:3], v70, v70, 1.0
	v_rcp_f32_e32 v72, v71
	v_pk_mul_f32 v[96:97], v[80:81], v[96:97] op_sel_hi:[0,1]
	v_pk_mul_f32 v[94:95], v[80:81], v[94:95] op_sel_hi:[0,1]
	v_pk_fma_f32 v[96:97], v[128:129], v[96:97], v[10:11]
	v_fma_f32 v73, -v71, v72, 1.0
	v_fmac_f32_e32 v72, v73, v72
	v_div_scale_f32 v73, vcc, 1.0, v70, 1.0
	v_mul_f32_e32 v74, v73, v72
	v_fma_f32 v75, -v71, v74, v73
	v_fmac_f32_e32 v74, v75, v72
	v_fma_f32 v71, -v71, v74, v73
	v_div_fmas_f32 v71, v71, v72, v74
	v_div_fixup_f32 v70, v71, v70, 1.0
	v_mov_b32_e32 v73, v56
	v_mov_b32_e32 v75, v64
	v_mov_b32_e32 v56, v55
	v_mov_b32_e32 v64, v61
	v_mov_b32_e32 v72, v54
	v_mov_b32_e32 v74, v60
	v_pk_mul_f32 v[54:55], v[70:71], v[56:57] op_sel_hi:[0,1]
	v_pk_mul_f32 v[56:57], v[70:71], v[64:65] op_sel_hi:[0,1]
	v_pk_mul_f32 v[58:59], v[70:71], v[62:63] op_sel_hi:[0,1]
	v_pk_mul_f32 v[60:61], v[70:71], v[68:69] op_sel_hi:[0,1]
	v_pk_fma_f32 v[56:57], v[124:125], v[56:57], v[6:7]
	v_pk_fma_f32 v[54:55], v[126:127], v[54:55], v[4:5]
	v_pk_fma_f32 v[60:61], v[60:61], v[120:121], v[2:3]
	v_pk_fma_f32 v[58:59], v[58:59], v[122:123], v[0:1]
	v_cvt_pk_bf16_f32 v54, v54, v55
	v_cvt_pk_bf16_f32 v55, v56, v57
	v_cvt_pk_bf16_f32 v56, v58, v59
	v_cvt_pk_bf16_f32 v57, v60, v61
	flat_store_dwordx4 v[76:77], v[54:57] offset:1024
	v_mov_b32_e32 v63, v46
	v_mov_b32_e32 v65, v52
	v_fmamk_f32 v54, v187, 0x3a800000, v214
	v_cmp_gt_f32_e32 vcc, s19, v54
	v_mul_f32_e32 v55, 0x4f800000, v54
	v_mov_b32_e32 v46, v43
	v_cndmask_b32_e32 v54, v54, v55, vcc
	v_sqrt_f32_e32 v55, v54
	v_mov_b32_e32 v52, v51
	v_mov_b32_e32 v62, v42
	v_lshl_add_u64 v[60:61], v[20:21], 0, s[40:41]
	v_add_u32_e32 v56, -1, v55
	v_fma_f32 v57, -v56, v55, v54
	v_cmp_ge_f32_e64 s[36:37], 0, v57
	v_add_u32_e32 v57, 1, v55
	v_pk_mul_f32 v[72:73], v[70:71], v[72:73] op_sel_hi:[0,1]
	v_cndmask_b32_e64 v56, v55, v56, s[36:37]
	v_fma_f32 v55, -v57, v55, v54
	v_cmp_lt_f32_e64 s[36:37], 0, v55
	v_pk_mul_f32 v[74:75], v[70:71], v[74:75] op_sel_hi:[0,1]
	v_pk_fma_f32 v[74:75], v[132:133], v[74:75], v[14:15]
	v_cndmask_b32_e64 v55, v56, v57, s[36:37]
	v_mul_f32_e32 v56, 0x37800000, v55
	v_cndmask_b32_e32 v55, v55, v56, vcc
	v_cmp_class_f32_e32 vcc, v54, v215
	v_pk_fma_f32 v[72:73], v[134:135], v[72:73], v[12:13]
	v_mov_b32_e32 v64, v50
	v_cndmask_b32_e32 v54, v55, v54, vcc
	v_div_scale_f32 v55, s[2:3], v54, v54, 1.0
	v_rcp_f32_e32 v56, v55
	v_pk_mul_f32 v[82:83], v[70:71], v[82:83] op_sel_hi:[0,1]
	v_pk_mul_f32 v[78:79], v[70:71], v[78:79] op_sel_hi:[0,1]
	v_pk_fma_f32 v[82:83], v[128:129], v[82:83], v[10:11]
	v_fma_f32 v57, -v55, v56, 1.0
	v_fmac_f32_e32 v56, v57, v56
	v_div_scale_f32 v57, vcc, 1.0, v54, 1.0
	v_mul_f32_e32 v58, v57, v56
	v_fma_f32 v59, -v55, v58, v57
	v_fmac_f32_e32 v58, v59, v56
	v_fma_f32 v55, -v55, v58, v57
	v_div_fmas_f32 v55, v55, v56, v58
	v_div_fixup_f32 v54, v55, v54, 1.0
	v_mov_b32_e32 v57, v40
	v_mov_b32_e32 v59, v48
	v_mov_b32_e32 v40, v39
; __device__ __forceinline__ unsigned pk2(float lo, float hi) { return pg8::cvt_pk_bf16(lo, hi); }
; __device__ __forceinline__ void unpack8(const u32x4 w, f32x4& a, f32x4& c) { a = (f32x4){bf_lo(w.x), bf_hi(w.x), bf_lo(w.y), bf_hi(w.y)}; c = (f32x4){bf_lo(w.z), bf_hi(w.z), bf_lo(w.w), bf_hi(w.w)}; }
; template <bool X_F32> __device__ __forceinline__ void phase_norm_mod(const Ctx& C, const void* xin, const float* modl, int shift_idx, int scale_idx) {
;     ...
;             for (int r = 0; r < NR; ++r) { const float rs = 1.0f / sqrtf(s[r] * (1.f / DM) + EPS);
; #pragma unroll
;                 for (int j = 0; j < 2; ++j) { f32x4 t0, t1; unpack8(raw[r][j], t0, t1);
;                     const f32x4 y0 = t0 * rs * g[2 * j] + a[2 * j], y1 = t1 * rs * g[2 * j + 1] + a[2 * j + 1];
;                     u32x4 w; w.x = pk2(y0.x, y0.y); w.y = pk2(y0.z, y0.w); w.z = pk2(y1.x, y1.y); w.w = pk2(y1.z, y1.w);
;                     ((u32x4*)(H + (size_t)(m0 + r) * DM + 512 * j))[lane] = w; } }
	v_mov_b32_e32 v48, v45
	v_mov_b32_e32 v56, v38
	v_mov_b32_e32 v58, v44
	v_pk_mul_f32 v[38:39], v[54:55], v[40:41] op_sel_hi:[0,1]
	v_pk_mul_f32 v[40:41], v[54:55], v[48:49] op_sel_hi:[0,1]
	v_pk_mul_f32 v[42:43], v[54:55], v[46:47] op_sel_hi:[0,1]
	v_pk_mul_f32 v[44:45], v[54:55], v[52:53] op_sel_hi:[0,1]
	v_pk_fma_f32 v[40:41], v[124:125], v[40:41], v[6:7]
	v_pk_fma_f32 v[38:39], v[126:127], v[38:39], v[4:5]
	v_pk_fma_f32 v[44:45], v[44:45], v[120:121], v[2:3]
	v_pk_fma_f32 v[42:43], v[42:43], v[122:123], v[0:1]
	v_cvt_pk_bf16_f32 v38, v38, v39
	v_cvt_pk_bf16_f32 v39, v40, v41
	v_cvt_pk_bf16_f32 v40, v42, v43
	v_cvt_pk_bf16_f32 v41, v44, v45
	flat_store_dwordx4 v[60:61], v[38:41] offset:1024
	v_mov_b32_e32 v44, v28
	v_mov_b32_e32 v45, v32
	v_fmamk_f32 v38, v186, 0x3a800000, v214
	v_cmp_gt_f32_e32 vcc, s19, v38
	v_mul_f32_e32 v39, 0x4f800000, v38
	v_pk_mul_f32 v[56:57], v[54:55], v[56:57] op_sel_hi:[0,1]
	v_cndmask_b32_e32 v38, v38, v39, vcc
	v_sqrt_f32_e32 v39, v38
	v_pk_mul_f32 v[58:59], v[54:55], v[58:59] op_sel_hi:[0,1]
	v_pk_fma_f32 v[58:59], v[132:133], v[58:59], v[14:15]
	v_pk_fma_f32 v[56:57], v[134:135], v[56:57], v[12:13]
	v_add_u32_e32 v40, -1, v39
	v_fma_f32 v41, -v40, v39, v38
	v_cmp_ge_f32_e64 s[36:37], 0, v41
	v_add_u32_e32 v41, 1, v39
	v_pk_mul_f32 v[64:65], v[54:55], v[64:65] op_sel_hi:[0,1]
	v_cndmask_b32_e64 v40, v39, v40, s[36:37]
	v_fma_f32 v39, -v41, v39, v38
	v_cmp_lt_f32_e64 s[36:37], 0, v39
	v_pk_mul_f32 v[62:63], v[54:55], v[62:63] op_sel_hi:[0,1]
	v_pk_fma_f32 v[64:65], v[128:129], v[64:65], v[10:11]
	v_cndmask_b32_e64 v39, v40, v41, s[36:37]
	v_mul_f32_e32 v40, 0x37800000, v39
	v_cndmask_b32_e32 v39, v39, v40, vcc
	v_cmp_class_f32_e32 vcc, v38, v215
	v_pk_fma_f32 v[94:95], v[130:131], v[94:95], v[8:9]
	v_pk_fma_f32 v[78:79], v[130:131], v[78:79], v[8:9]
	v_cndmask_b32_e32 v38, v39, v38, vcc
	v_div_scale_f32 v39, s[2:3], v38, v38, 1.0
	v_rcp_f32_e32 v40, v39
	v_pk_fma_f32 v[62:63], v[130:131], v[62:63], v[8:9]
	v_mov_b32_e32 v32, v29
	s_add_i32 s2, s20, s21
	v_fma_f32 v41, -v39, v40, 1.0
	v_fmac_f32_e32 v40, v41, v40
	v_div_scale_f32 v41, vcc, 1.0, v38, 1.0
	v_mul_f32_e32 v42, v41, v40
	v_fma_f32 v43, -v39, v42, v41
	v_fmac_f32_e32 v42, v43, v40
	v_fma_f32 v39, -v39, v42, v41
	v_div_fmas_f32 v39, v39, v40, v42
	v_div_fixup_f32 v38, v39, v38, 1.0
	v_mov_b32_e32 v42, v22
	v_mov_b32_e32 v43, v24
	v_pk_mul_f32 v[42:43], v[38:39], v[42:43] op_sel_hi:[0,1]
	v_pk_mul_f32 v[44:45], v[38:39], v[44:45] op_sel_hi:[0,1]
	v_pk_fma_f32 v[14:15], v[132:133], v[44:45], v[14:15]
	v_pk_fma_f32 v[12:13], v[134:135], v[42:43], v[12:13]
	v_mov_b32_e32 v42, v26
	v_mov_b32_e32 v43, v30
	v_mov_b32_e32 v44, v34
	v_mov_b32_e32 v45, v36
	v_pk_mul_f32 v[42:43], v[38:39], v[42:43] op_sel_hi:[0,1]
	v_pk_mul_f32 v[44:45], v[38:39], v[44:45] op_sel_hi:[0,1]
	v_pk_fma_f32 v[44:45], v[128:129], v[44:45], v[10:11]
	v_pk_fma_f32 v[10:11], v[130:131], v[42:43], v[8:9]
	v_lshl_add_u64 v[40:41], v[20:21], 0, s[38:39]
	v_cvt_pk_bf16_f32 v8, v12, v13
	v_cvt_pk_bf16_f32 v9, v14, v15
	v_cvt_pk_bf16_f32 v10, v10, v11
	v_cvt_pk_bf16_f32 v11, v44, v45
	v_mov_b32_e32 v24, v23
	flat_store_dwordx4 v[40:41], v[8:11]
	v_mov_b32_e32 v30, v27
	v_mov_b32_e32 v36, v35
	v_pk_mul_f32 v[8:9], v[38:39], v[24:25] op_sel_hi:[0,1]
	v_pk_mul_f32 v[10:11], v[38:39], v[32:33] op_sel_hi:[0,1]
	v_pk_fma_f32 v[6:7], v[124:125], v[10:11], v[6:7]
	v_pk_fma_f32 v[4:5], v[126:127], v[8:9], v[4:5]
	v_pk_mul_f32 v[8:9], v[38:39], v[30:31] op_sel_hi:[0,1]
	v_pk_mul_f32 v[10:11], v[38:39], v[36:37] op_sel_hi:[0,1]
	v_pk_fma_f32 v[10:11], v[120:121], v[10:11], v[2:3]
	v_pk_fma_f32 v[2:3], v[122:123], v[8:9], v[0:1]
	v_cvt_pk_bf16_f32 v136, v136, v137
	v_cvt_pk_bf16_f32 v137, v138, v139
	v_cvt_pk_bf16_f32 v138, v142, v143
	v_cvt_pk_bf16_f32 v139, v144, v145
	v_cvt_pk_bf16_f32 v104, v104, v105
	v_cvt_pk_bf16_f32 v105, v106, v107
	v_cvt_pk_bf16_f32 v106, v110, v111
	v_cvt_pk_bf16_f32 v107, v112, v113
	v_cvt_pk_bf16_f32 v88, v88, v89
	v_cvt_pk_bf16_f32 v89, v90, v91
	v_cvt_pk_bf16_f32 v90, v94, v95
	v_cvt_pk_bf16_f32 v91, v96, v97
	v_cvt_pk_bf16_f32 v72, v72, v73
	v_cvt_pk_bf16_f32 v73, v74, v75
	v_cvt_pk_bf16_f32 v74, v78, v79
	v_cvt_pk_bf16_f32 v75, v82, v83
	v_cvt_pk_bf16_f32 v56, v56, v57
	v_cvt_pk_bf16_f32 v57, v58, v59
	v_cvt_pk_bf16_f32 v58, v62, v63
	v_cvt_pk_bf16_f32 v59, v64, v65
	v_cvt_pk_bf16_f32 v0, v4, v5
	v_cvt_pk_bf16_f32 v1, v6, v7
	v_cvt_pk_bf16_f32 v2, v2, v3
	v_cvt_pk_bf16_f32 v3, v10, v11
	s_cmpk_lt_i32 s2, 0x1000
	flat_store_dwordx4 v[198:199], v[194:197]
	flat_store_dwordx4 v[156:157], v[152:155]
	flat_store_dwordx4 v[140:141], v[136:139]
	flat_store_dwordx4 v[108:109], v[104:107]
	flat_store_dwordx4 v[92:93], v[88:91]
	flat_store_dwordx4 v[76:77], v[72:75]
	flat_store_dwordx4 v[60:61], v[56:59]
	flat_store_dwordx4 v[40:41], v[0:3] offset:1024
	s_cbranch_scc1 .LBB0_499

; __device__ __forceinline__ void unpack8(const u32x4 w, f32x4& a, f32x4& c) { a = (f32x4){bf_lo(w.x), bf_hi(w.x), bf_lo(w.y), bf_hi(w.y)}; c = (f32x4){bf_lo(w.z), bf_hi(w.z), bf_lo(w.w), bf_hi(w.w)}; }
; __device__ __forceinline__ void phase_final(const Ctx& C) {
;     ...
;     for (int r0_ = (gw % (NGW >> 3)) * NRW; r0_ < T / 8; r0_ += (NGW >> 3) * NRW) { const int m0 = (gw / (NGW >> 3)) * (T / 8) + r0_;
;         f32x4 v[NRW][4]; float s[NRW];
; #pragma unroll
;         for (int r = 0; r < NRW; ++r) { s[r] = 0.f;
; #pragma unroll
;             for (int j = 0; j < 2; ++j) { unpack8(((const u32x4*)(XR + (size_t)(m0 + r) * DM + 512 * j))[lane], v[r][2 * j], v[r][2 * j + 1]);
; #pragma unroll
;                 for (int q = 0; q < 2; ++q) { const f32x4 t = v[r][2 * j + q]; s[r] += (t.x * t.x + t.y * t.y) + (t.z * t.z + t.w * t.w); } } }
.LBB0_761:
	s_add_i32 s0, s13, s15
	s_ashr_i32 s1, s0, 31
	s_add_i32 s2, s0, 1
	s_lshl_b64 s[8:9], s[0:1], 11
	s_add_i32 s4, s0, 2
	s_add_i32 s6, s0, 3
	s_ashr_i32 s3, s2, 31
	v_lshl_add_u64 v[20:21], v[16:17], 0, s[8:9]
	s_ashr_i32 s5, s4, 31
	s_ashr_i32 s7, s6, 31
	s_lshl_b64 s[8:9], s[2:3], 11
	flat_load_dwordx4 v[28:31], v[20:21] nt
	flat_load_dwordx4 v[32:35], v[20:21] offset:1024 nt
	s_lshl_b64 s[10:11], s[4:5], 11
	s_lshl_b64 s[18:19], s[6:7], 11
	v_lshl_add_u64 v[52:53], v[16:17], 0, s[8:9]
	v_lshl_add_u64 v[54:55], v[16:17], 0, s[10:11]
	v_lshl_add_u64 v[56:57], v[16:17], 0, s[18:19]
	flat_load_dwordx4 v[36:39], v[52:53] nt
	flat_load_dwordx4 v[40:43], v[52:53] offset:1024 nt
	flat_load_dwordx4 v[44:47], v[54:55] nt
	flat_load_dwordx4 v[48:51], v[54:55] offset:1024 nt
	flat_load_dwordx4 v[84:87], v[56:57] nt
	flat_load_dwordx4 v[88:91], v[56:57] offset:1024 nt
	s_lshl_b64 s[0:1], s[0:1], 12
	v_lshl_add_u64 v[26:27], v[18:19], 0, s[0:1]
	s_lshl_b64 s[0:1], s[2:3], 12
	s_lshl_b64 s[2:3], s[4:5], 12
	s_lshl_b64 s[4:5], s[6:7], 12
	v_lshl_add_u64 v[24:25], v[18:19], 0, s[0:1]
	v_lshl_add_u64 v[22:23], v[18:19], 0, s[2:3]
	v_lshl_add_u64 v[20:21], v[18:19], 0, s[4:5]
	s_add_i32 s14, s14, s12
	s_add_i32 s15, s15, s12
	s_add_i32 s17, s13, s14
	s_cmpk_lt_i32 s17, 0x1000
	s_waitcnt vmcnt(0) lgkmcnt(0)
	v_lshlrev_b32_e32 v52, 16, v28
	v_lshlrev_b32_e32 v54, 16, v29
	v_and_b32_e32 v61, 0xffff0000, v31
	v_and_b32_e32 v60, 0xffff0000, v30
	v_lshlrev_b32_e32 v76, 16, v32
	v_lshlrev_b32_e32 v78, 16, v33
	v_and_b32_e32 v53, 0xffff0000, v28
	v_and_b32_e32 v55, 0xffff0000, v29
	v_lshlrev_b32_e32 v101, 16, v31
	v_lshlrev_b32_e32 v100, 16, v30
	v_and_b32_e32 v77, 0xffff0000, v32
	v_and_b32_e32 v79, 0xffff0000, v33
	v_mul_f32_e32 v102, v52, v52
	v_mul_f32_e32 v104, v54, v54
	v_pk_mul_f32 v[106:107], v[60:61], v[60:61]
	v_mul_f32_e32 v108, v76, v76
	v_mul_f32_e32 v110, v78, v78
	v_lshlrev_b32_e32 v62, 16, v36
	v_and_b32_e32 v63, 0xffff0000, v36
	v_lshlrev_b32_e32 v66, 16, v37
	v_and_b32_e32 v67, 0xffff0000, v37
	v_lshlrev_b32_e32 v114, 16, v38
	v_and_b32_e32 v75, 0xffff0000, v39
	v_and_b32_e32 v74, 0xffff0000, v38
	v_lshlrev_b32_e32 v80, 16, v40
	v_and_b32_e32 v81, 0xffff0000, v40
	v_lshlrev_b32_e32 v38, 16, v44
	v_lshlrev_b32_e32 v40, 16, v45
	v_lshlrev_b32_e32 v117, 16, v47
	v_lshlrev_b32_e32 v116, 16, v46
	v_and_b32_e32 v47, 0xffff0000, v47
	v_and_b32_e32 v46, 0xffff0000, v46
	v_and_b32_e32 v37, 0xffff0000, v87
	v_and_b32_e32 v36, 0xffff0000, v86
	v_lshlrev_b32_e32 v56, 16, v34
	v_and_b32_e32 v57, 0xffff0000, v34
	v_lshlrev_b32_e32 v58, 16, v35
	v_and_b32_e32 v59, 0xffff0000, v35
	v_lshlrev_b32_e32 v115, 16, v39
	v_lshlrev_b32_e32 v82, 16, v41
	v_and_b32_e32 v83, 0xffff0000, v41
	v_and_b32_e32 v39, 0xffff0000, v44
	v_and_b32_e32 v41, 0xffff0000, v45
	v_lshlrev_b32_e32 v64, 16, v48
	v_lshlrev_b32_e32 v70, 16, v49
	v_lshlrev_b32_e32 v28, 16, v84
	v_lshlrev_b32_e32 v30, 16, v85
	v_lshlrev_b32_e32 v119, 16, v87
	v_lshlrev_b32_e32 v118, 16, v86
	v_lshlrev_b32_e32 v32, 16, v90
	v_and_b32_e32 v33, 0xffff0000, v90
	v_lshlrev_b32_e32 v34, 16, v91
	v_and_b32_e32 v35, 0xffff0000, v91
	v_mov_b32_e32 v90, v100
	v_mov_b32_e32 v91, v60
	v_mov_b32_e32 v60, v101
	v_pk_fma_f32 v[102:103], v[52:53], v[52:53], v[102:103] op_sel_hi:[1,1,0]
	v_pk_fma_f32 v[104:105], v[54:55], v[54:55], v[104:105] op_sel_hi:[1,1,0]
	v_pk_fma_f32 v[100:101], v[100:101], v[100:101], v[106:107]
	v_pk_fma_f32 v[106:107], v[76:77], v[76:77], v[108:109] op_sel_hi:[1,1,0]
	v_pk_fma_f32 v[108:109], v[78:79], v[78:79], v[110:111] op_sel_hi:[1,1,0]
	v_mul_f32_e32 v110, v62, v62
	v_mul_f32_e32 v120, v66, v66
	v_pk_mul_f32 v[122:123], v[74:75], v[74:75]
	v_pk_mul_f32 v[126:127], v[46:47], v[46:47]
	v_pk_mul_f32 v[128:129], v[36:37], v[36:37]
	v_mul_f32_e32 v132, v38, v38
	v_mul_f32_e32 v134, v40, v40
	v_lshlrev_b32_e32 v68, 16, v42
	v_and_b32_e32 v69, 0xffff0000, v42
	v_lshlrev_b32_e32 v72, 16, v43
	v_and_b32_e32 v73, 0xffff0000, v43
	v_lshlrev_b32_e32 v42, 16, v50
	v_and_b32_e32 v43, 0xffff0000, v50
	v_lshlrev_b32_e32 v44, 16, v51
	v_and_b32_e32 v45, 0xffff0000, v51
	v_and_b32_e32 v65, 0xffff0000, v48
	v_and_b32_e32 v71, 0xffff0000, v49
	v_and_b32_e32 v29, 0xffff0000, v84
	v_and_b32_e32 v31, 0xffff0000, v85
	v_lshlrev_b32_e32 v48, 16, v88
	v_and_b32_e32 v49, 0xffff0000, v88
	v_lshlrev_b32_e32 v50, 16, v89
	v_and_b32_e32 v51, 0xffff0000, v89
	v_mul_f32_e32 v124, v80, v80
	v_mov_b32_e32 v88, v114
	v_mov_b32_e32 v89, v74
	v_mov_b32_e32 v74, v115
	v_mov_b32_e32 v86, v116
	v_mov_b32_e32 v87, v46
	v_mov_b32_e32 v46, v117
	v_mov_b32_e32 v84, v118
	v_mov_b32_e32 v85, v36
	v_mov_b32_e32 v36, v119
	v_mul_f32_e32 v130, v82, v82
	v_mul_f32_e32 v136, v28, v28
	v_mul_f32_e32 v138, v30, v30
	v_mul_f32_e32 v142, v64, v64
	v_mul_f32_e32 v144, v70, v70
	v_pk_add_f32 v[102:103], v[102:103], v[104:105]
	v_pk_fma_f32 v[104:105], v[114:115], v[114:115], v[122:123]
	v_pk_fma_f32 v[114:115], v[116:117], v[116:117], v[126:127]
	v_pk_fma_f32 v[116:117], v[118:119], v[118:119], v[128:129]
	v_mul_f32_e32 v106, v58, v58
	v_mul_f32_e32 v108, v59, v59
	v_pk_fma_f32 v[110:111], v[62:63], v[62:63], v[110:111] op_sel_hi:[1,1,0]
	v_pk_fma_f32 v[118:119], v[66:67], v[66:67], v[120:121] op_sel_hi:[1,1,0]
	v_pk_fma_f32 v[120:121], v[38:39], v[38:39], v[132:133] op_sel_hi:[1,1,0]
	v_pk_fma_f32 v[122:123], v[40:41], v[40:41], v[134:135] op_sel_hi:[1,1,0]
	v_pk_add_f32 v[100:101], v[100:101], v[100:101] op_sel_hi:[0,1]
	v_mul_f32_e32 v112, v56, v56
	v_mul_f32_e32 v148, v48, v48
	v_mul_f32_e32 v150, v50, v50
	v_pk_fma_f32 v[126:127], v[28:29], v[28:29], v[136:137] op_sel_hi:[1,1,0]
	v_pk_fma_f32 v[128:129], v[30:31], v[30:31], v[138:139] op_sel_hi:[1,1,0]
; template <int NR> __device__ __forceinline__ void wave_sumN(float (&s)[NR]) {
; #pragma unroll
;     for (int o = 1; o < 64; o <<= 1) {
;         float t[NR];
; #pragma unroll
;         for (int r = 0; r < NR; ++r) t[r] = __shfl_xor(s[r], o);
; #pragma unroll
;         for (int r = 0; r < NR; ++r) s[r] += t[r];
;     }
; }
; __device__ __forceinline__ void phase_final(const Ctx& C) {
;     ...
;                 for (int q = 0; q < 2; ++q) { const f32x4 t = v[r][2 * j + q]; s[r] += (t.x * t.x + t.y * t.y) + (t.z * t.z + t.w * t.w); } } }
;         wave_sumN<NRW>(s);
; #pragma unroll
;         for (int r = 0; r < NRW; ++r) { const float rs = 1.0f / sqrtf(s[r] * (1.f / DM) + EPS);
	v_pk_fma_f32 v[124:125], v[80:81], v[80:81], v[124:125] op_sel_hi:[1,1,0]
	v_pk_fma_f32 v[130:131], v[82:83], v[82:83], v[130:131] op_sel_hi:[1,1,0]
	v_pk_fma_f32 v[132:133], v[64:65], v[64:65], v[142:143] op_sel_hi:[1,1,0]
	v_pk_fma_f32 v[134:135], v[70:71], v[70:71], v[144:145] op_sel_hi:[1,1,0]
	v_mov_b32_e32 v113, v103
	v_pk_add_f32 v[102:103], v[106:107], v[108:109]
	v_pk_add_f32 v[106:107], v[110:111], v[118:119]
	v_pk_add_f32 v[108:109], v[120:121], v[122:123]
	v_mul_f32_e32 v100, v57, v57
	v_pk_add_f32 v[104:105], v[104:105], v[104:105] op_sel_hi:[0,1]
	v_pk_add_f32 v[114:115], v[114:115], v[114:115] op_sel_hi:[0,1]
	v_mul_f32_e32 v140, v68, v68
	v_mul_f32_e32 v146, v42, v42
	v_pk_fma_f32 v[136:137], v[48:49], v[48:49], v[148:149] op_sel_hi:[1,1,0]
	v_pk_fma_f32 v[138:139], v[50:51], v[50:51], v[150:151] op_sel_hi:[1,1,0]
	v_pk_add_f32 v[110:111], v[126:127], v[128:129]
	v_mul_f32_e32 v124, v72, v72
	v_mul_f32_e32 v130, v73, v73
	v_mul_f32_e32 v132, v44, v44
	v_mul_f32_e32 v134, v45, v45
	v_pk_add_f32 v[116:117], v[116:117], v[116:117] op_sel_hi:[0,1]
	v_pk_add_f32 v[100:101], v[112:113], v[100:101]
	v_mov_b32_e32 v141, v107
	v_mov_b32_e32 v147, v109
	v_mul_f32_e32 v104, v69, v69
	v_mul_f32_e32 v114, v43, v43
	v_mul_f32_e32 v152, v32, v32
	v_mul_f32_e32 v136, v34, v34
	v_mul_f32_e32 v138, v35, v35
	v_pk_add_f32 v[106:107], v[124:125], v[130:131]
	v_pk_add_f32 v[108:109], v[132:133], v[134:135]
	v_mov_b32_e32 v153, v111
	v_mul_f32_e32 v116, v33, v33
	v_pk_add_f32 v[100:101], v[100:101], v[102:103]
	v_pk_add_f32 v[102:103], v[140:141], v[104:105]
	v_pk_add_f32 v[104:105], v[146:147], v[114:115]
	v_pk_add_f32 v[110:111], v[136:137], v[138:139]
	v_pk_add_f32 v[112:113], v[152:153], v[116:117]
	v_add_f32_e32 v114, v100, v101
	v_pk_add_f32 v[100:101], v[102:103], v[106:107]
	v_pk_add_f32 v[102:103], v[104:105], v[108:109]
	v_pk_add_f32 v[104:105], v[112:113], v[110:111]
	v_add_f32_e32 v100, v100, v101
	v_add_f32_e32 v101, v102, v103
	ds_bpermute_b32 v103, v92, v114
	v_add_f32_e32 v102, v104, v105
	ds_bpermute_b32 v104, v92, v100
	ds_bpermute_b32 v105, v92, v101
	ds_bpermute_b32 v106, v92, v102
	s_waitcnt lgkmcnt(3)
	v_add_f32_e32 v103, v114, v103
	s_waitcnt lgkmcnt(2)
	v_add_f32_e32 v100, v100, v104
	ds_bpermute_b32 v104, v93, v103
	s_waitcnt lgkmcnt(2)
	v_add_f32_e32 v101, v101, v105
	s_waitcnt lgkmcnt(1)
	v_add_f32_e32 v102, v102, v106
	ds_bpermute_b32 v105, v93, v100
	ds_bpermute_b32 v106, v93, v101
	ds_bpermute_b32 v107, v93, v102
	s_waitcnt lgkmcnt(3)
	v_add_f32_e32 v103, v103, v104
	ds_bpermute_b32 v104, v94, v103
	s_waitcnt lgkmcnt(3)
	v_add_f32_e32 v100, v100, v105
	s_waitcnt lgkmcnt(2)
	v_add_f32_e32 v101, v101, v106
	s_waitcnt lgkmcnt(1)
	v_add_f32_e32 v102, v102, v107
	ds_bpermute_b32 v105, v94, v100
	ds_bpermute_b32 v106, v94, v101
	ds_bpermute_b32 v107, v94, v102
	s_waitcnt lgkmcnt(3)
	v_add_f32_e32 v103, v103, v104
	ds_bpermute_b32 v104, v95, v103
	s_waitcnt lgkmcnt(3)
	v_add_f32_e32 v100, v100, v105
	s_waitcnt lgkmcnt(2)
	v_add_f32_e32 v101, v101, v106
	s_waitcnt lgkmcnt(1)
	v_add_f32_e32 v102, v102, v107
	ds_bpermute_b32 v105, v95, v100
	ds_bpermute_b32 v106, v95, v101
	ds_bpermute_b32 v107, v95, v102
	s_waitcnt lgkmcnt(3)
	v_add_f32_e32 v103, v103, v104
	ds_bpermute_b32 v104, v96, v103
	s_waitcnt lgkmcnt(3)
	v_add_f32_e32 v100, v100, v105
	s_waitcnt lgkmcnt(2)
	v_add_f32_e32 v101, v101, v106
	s_waitcnt lgkmcnt(1)
	v_add_f32_e32 v102, v102, v107
	ds_bpermute_b32 v105, v96, v100
	ds_bpermute_b32 v106, v96, v101
	ds_bpermute_b32 v107, v96, v102
	s_waitcnt lgkmcnt(3)
	v_add_f32_e32 v103, v103, v104
	ds_bpermute_b32 v104, v97, v103
	s_waitcnt lgkmcnt(3)
	v_add_f32_e32 v100, v100, v105
	s_waitcnt lgkmcnt(2)
	v_add_f32_e32 v101, v101, v106
	s_waitcnt lgkmcnt(1)
	v_add_f32_e32 v102, v102, v107
	ds_bpermute_b32 v105, v97, v100
	ds_bpermute_b32 v106, v97, v101
	ds_bpermute_b32 v107, v97, v102
	s_waitcnt lgkmcnt(3)
	v_add_f32_e32 v103, v103, v104
	v_fmamk_f32 v103, v103, 0x3a800000, v98
	s_waitcnt lgkmcnt(2)
	v_add_f32_e32 v100, v100, v105
	v_mul_f32_e32 v104, 0x4f800000, v103
	v_cmp_gt_f32_e32 vcc, s16, v103
	s_waitcnt lgkmcnt(1)
	v_add_f32_e32 v101, v101, v106
	s_waitcnt lgkmcnt(0)
	v_add_f32_e32 v102, v102, v107
	v_fmamk_f32 v100, v100, 0x3a800000, v98
	v_cndmask_b32_e32 v103, v103, v104, vcc
	v_fmamk_f32 v101, v101, 0x3a800000, v98
	v_fmamk_f32 v102, v102, 0x3a800000, v98
	v_mul_f32_e32 v104, 0x4f800000, v100
	v_cmp_gt_f32_e64 s[0:1], s16, v100
	v_sqrt_f32_e32 v107, v103
	v_mul_f32_e32 v105, 0x4f800000, v101
	v_cmp_gt_f32_e64 s[2:3], s16, v101
	v_mul_f32_e32 v106, 0x4f800000, v102
	v_cmp_gt_f32_e64 s[4:5], s16, v102
	v_cndmask_b32_e64 v100, v100, v104, s[0:1]
	v_cndmask_b32_e64 v101, v101, v105, s[2:3]
	v_cndmask_b32_e64 v102, v102, v106, s[4:5]
	v_sqrt_f32_e32 v104, v100
	v_sqrt_f32_e32 v105, v101
	v_sqrt_f32_e32 v106, v102
	v_add_u32_e32 v108, -1, v107
	v_add_u32_e32 v109, 1, v107
	v_fma_f32 v110, -v108, v107, v103
	v_fma_f32 v111, -v109, v107, v103
	v_add_u32_e32 v112, -1, v104
	v_cmp_ge_f32_e64 s[6:7], 0, v110
	v_add_u32_e32 v113, 1, v104
	v_add_u32_e32 v114, -1, v105
	v_add_u32_e32 v116, -1, v106
	v_cndmask_b32_e64 v107, v107, v108, s[6:7]
	v_fma_f32 v108, -v112, v104, v100
	v_cmp_lt_f32_e64 s[6:7], 0, v111
	v_add_u32_e32 v115, 1, v105
	v_add_u32_e32 v117, 1, v106
	v_fma_f32 v110, -v113, v104, v100
	v_fma_f32 v118, -v114, v105, v101
	v_fma_f32 v120, -v116, v106, v102
	v_cndmask_b32_e64 v107, v107, v109, s[6:7]
	v_cmp_ge_f32_e64 s[6:7], 0, v108
	v_fma_f32 v119, -v115, v105, v101
	v_fma_f32 v121, -v117, v106, v102
	v_cndmask_b32_e64 v104, v104, v112, s[6:7]
	v_cmp_lt_f32_e64 s[6:7], 0, v110
	v_cmp_ge_f32_e64 s[8:9], 0, v118
; __device__ __forceinline__ void phase_final(const Ctx& C) {
;     ...
;         for (int r = 0; r < NRW; ++r) { const float rs = 1.0f / sqrtf(s[r] * (1.f / DM) + EPS);
; #pragma unroll
;             for (int j = 0; j < 2; ++j)
; #pragma unroll
;                 for (int q = 0; q < 2; ++q) *(f32x4*)(out_ + (size_t)(m0 + r) * DM + 512 * j + 8 * lane + 4 * q) = v[r][2 * j + q] * rs * g[2 * j + q]; }
	v_cmp_ge_f32_e64 s[10:11], 0, v120
	v_mul_f32_e32 v108, 0x37800000, v107
	v_cndmask_b32_e64 v105, v105, v114, s[8:9]
	v_cmp_lt_f32_e64 s[8:9], 0, v119
	v_cndmask_b32_e64 v106, v106, v116, s[10:11]
	v_cmp_lt_f32_e64 s[10:11], 0, v121
	v_cndmask_b32_e64 v104, v104, v113, s[6:7]
	v_cndmask_b32_e64 v105, v105, v115, s[8:9]
	v_cndmask_b32_e64 v106, v106, v117, s[10:11]
	v_cndmask_b32_e32 v107, v107, v108, vcc
	v_mul_f32_e32 v108, 0x37800000, v104
	v_cmp_class_f32_e32 vcc, v103, v99
	v_mul_f32_e32 v109, 0x37800000, v105
	v_mul_f32_e32 v110, 0x37800000, v106
	v_cndmask_b32_e32 v103, v107, v103, vcc
	v_cndmask_b32_e64 v104, v104, v108, s[0:1]
	v_cmp_class_f32_e32 vcc, v100, v99
	v_cndmask_b32_e64 v105, v105, v109, s[2:3]
	v_cmp_class_f32_e64 s[0:1], v101, v99
	v_cndmask_b32_e64 v106, v106, v110, s[4:5]
	v_div_scale_f32 v107, s[4:5], v103, v103, 1.0
	v_cndmask_b32_e32 v109, v104, v100, vcc
	v_cmp_class_f32_e64 s[2:3], v102, v99
	v_cndmask_b32_e64 v110, v105, v101, s[0:1]
	v_rcp_f32_e32 v100, v107
	v_div_scale_f32 v101, s[0:1], v109, v109, 1.0
	v_cndmask_b32_e64 v111, v106, v102, s[2:3]
	v_div_scale_f32 v104, s[2:3], v110, v110, 1.0
	v_rcp_f32_e32 v113, v101
	v_div_scale_f32 v106, s[6:7], v111, v111, 1.0
	v_rcp_f32_e32 v114, v104
	v_rcp_f32_e32 v115, v106
	v_fma_f32 v116, -v107, v100, 1.0
	v_div_scale_f32 v108, s[4:5], 1.0, v103, 1.0
	v_fmac_f32_e32 v100, v116, v100
	v_fma_f32 v116, -v101, v113, 1.0
	v_div_scale_f32 v102, s[0:1], 1.0, v109, 1.0
	v_fma_f32 v117, -v104, v114, 1.0
	v_mul_f32_e32 v119, v108, v100
	v_fmac_f32_e32 v113, v116, v113
	v_div_scale_f32 v105, s[2:3], 1.0, v110, 1.0
	v_fma_f32 v118, -v106, v115, 1.0
	v_fmac_f32_e32 v114, v117, v114
	v_fma_f32 v116, -v107, v119, v108
	v_mul_f32_e32 v117, v102, v113
	v_div_scale_f32 v112, s[6:7], 1.0, v111, 1.0
	v_fmac_f32_e32 v115, v118, v115
	v_mul_f32_e32 v118, v105, v114
	v_fmac_f32_e32 v119, v116, v100
	v_fma_f32 v116, -v101, v117, v102
	v_mul_f32_e32 v120, v112, v115
	v_fma_f32 v121, -v104, v118, v105
	v_fma_f32 v107, -v107, v119, v108
	v_fmac_f32_e32 v117, v116, v113
	s_mov_b64 vcc, s[4:5]
	v_fma_f32 v122, -v106, v120, v112
	v_fmac_f32_e32 v118, v121, v114
	v_div_fmas_f32 v100, v107, v100, v119
	v_fma_f32 v101, -v101, v117, v102
	s_mov_b64 vcc, s[0:1]
	v_fmac_f32_e32 v120, v122, v115
	v_fma_f32 v102, -v104, v118, v105
	v_div_fixup_f32 v100, v100, v103, 1.0
	v_div_fmas_f32 v103, v101, v113, v117
	s_mov_b64 vcc, s[2:3]
	v_fma_f32 v107, -v106, v120, v112
	v_pk_mul_f32 v[52:53], v[100:101], v[52:53] op_sel_hi:[0,1]
	v_pk_mul_f32 v[54:55], v[100:101], v[54:55] op_sel_hi:[0,1]
	v_pk_mul_f32 v[90:91], v[100:101], v[90:91] op_sel_hi:[0,1]
	v_pk_mul_f32 v[60:61], v[100:101], v[60:61] op_sel_hi:[0,1]
	v_pk_mul_f32 v[76:77], v[100:101], v[76:77] op_sel_hi:[0,1]
	v_div_fixup_f32 v106, v103, v109, 1.0
	v_div_fmas_f32 v108, v102, v114, v118
	s_mov_b64 vcc, s[6:7]
	v_pk_mul_f32 v[78:79], v[100:101], v[78:79] op_sel_hi:[0,1]
	v_pk_mul_f32 v[104:105], v[100:101], v[56:57] op_sel_hi:[0,1]
	v_pk_mul_f32 v[100:101], v[100:101], v[58:59] op_sel_hi:[0,1]
	v_pk_mul_f32 v[54:55], v[6:7], v[54:55]
	v_pk_mul_f32 v[52:53], v[4:5], v[52:53]
	v_pk_mul_f32 v[58:59], v[2:3], v[60:61]
	v_pk_mul_f32 v[56:57], v[0:1], v[90:91]
	v_pk_mul_f32 v[76:77], v[12:13], v[76:77]
	v_pk_mul_f32 v[60:61], v[106:107], v[62:63] op_sel_hi:[0,1]
	v_pk_mul_f32 v[62:63], v[106:107], v[66:67] op_sel_hi:[0,1]
	v_pk_mul_f32 v[66:67], v[106:107], v[88:89] op_sel_hi:[0,1]
	v_pk_mul_f32 v[88:89], v[106:107], v[68:69] op_sel_hi:[0,1]
	v_pk_mul_f32 v[68:69], v[106:107], v[72:73] op_sel_hi:[0,1]
	v_div_fixup_f32 v72, v108, v110, 1.0
	v_div_fmas_f32 v90, v107, v115, v120
	v_pk_mul_f32 v[78:79], v[14:15], v[78:79]
	v_pk_mul_f32 v[102:103], v[10:11], v[100:101]
	v_pk_mul_f32 v[100:101], v[8:9], v[104:105]
	v_pk_mul_f32 v[74:75], v[106:107], v[74:75] op_sel_hi:[0,1]
	v_pk_mul_f32 v[80:81], v[106:107], v[80:81] op_sel_hi:[0,1]
	v_pk_mul_f32 v[82:83], v[106:107], v[82:83] op_sel_hi:[0,1]
	flat_store_dwordx4 v[26:27], v[52:55]
	flat_store_dwordx4 v[26:27], v[56:59] offset:16
	flat_store_dwordx4 v[26:27], v[76:79] offset:2048
	flat_store_dwordx4 v[26:27], v[100:103] offset:2064
	v_pk_mul_f32 v[54:55], v[6:7], v[62:63]
	v_pk_mul_f32 v[52:53], v[4:5], v[60:61]
	v_pk_mul_f32 v[38:39], v[72:73], v[38:39] op_sel_hi:[0,1]
	v_pk_mul_f32 v[26:27], v[72:73], v[40:41] op_sel_hi:[0,1]
	v_div_fixup_f32 v76, v90, v111, 1.0
	v_pk_mul_f32 v[58:59], v[2:3], v[74:75]
	v_pk_mul_f32 v[56:57], v[0:1], v[66:67]
	v_pk_mul_f32 v[62:63], v[14:15], v[82:83]
	v_pk_mul_f32 v[60:61], v[12:13], v[80:81]
	v_pk_mul_f32 v[68:69], v[10:11], v[68:69]
	v_pk_mul_f32 v[66:67], v[8:9], v[88:89]
	v_pk_mul_f32 v[74:75], v[72:73], v[86:87] op_sel_hi:[0,1]
	v_pk_mul_f32 v[40:41], v[72:73], v[46:47] op_sel_hi:[0,1]
	v_pk_mul_f32 v[46:47], v[72:73], v[64:65] op_sel_hi:[0,1]
	v_pk_mul_f32 v[64:65], v[72:73], v[70:71] op_sel_hi:[0,1]
	v_pk_mul_f32 v[70:71], v[72:73], v[42:43] op_sel_hi:[0,1]
	v_pk_mul_f32 v[72:73], v[72:73], v[44:45] op_sel_hi:[0,1]
	flat_store_dwordx4 v[24:25], v[52:55]
	flat_store_dwordx4 v[24:25], v[56:59] offset:16
	flat_store_dwordx4 v[24:25], v[60:63] offset:2048
	flat_store_dwordx4 v[24:25], v[66:69] offset:2064
	v_pk_mul_f32 v[26:27], v[6:7], v[26:27]
	v_pk_mul_f32 v[24:25], v[4:5], v[38:39]
	v_pk_mul_f32 v[28:29], v[76:77], v[28:29] op_sel_hi:[0,1]
	v_pk_mul_f32 v[30:31], v[76:77], v[30:31] op_sel_hi:[0,1]
	v_pk_mul_f32 v[40:41], v[2:3], v[40:41]
	v_pk_mul_f32 v[38:39], v[0:1], v[74:75]
	v_pk_mul_f32 v[44:45], v[14:15], v[64:65]
	v_pk_mul_f32 v[42:43], v[12:13], v[46:47]
	v_pk_mul_f32 v[54:55], v[10:11], v[72:73]
	v_pk_mul_f32 v[52:53], v[8:9], v[70:71]
	v_pk_mul_f32 v[46:47], v[76:77], v[84:85] op_sel_hi:[0,1]
	v_pk_mul_f32 v[36:37], v[76:77], v[36:37] op_sel_hi:[0,1]
	v_pk_mul_f32 v[48:49], v[76:77], v[48:49] op_sel_hi:[0,1]
	v_pk_mul_f32 v[50:51], v[76:77], v[50:51] op_sel_hi:[0,1]
	v_pk_mul_f32 v[56:57], v[76:77], v[32:33] op_sel_hi:[0,1]
	v_pk_mul_f32 v[34:35], v[76:77], v[34:35] op_sel_hi:[0,1]
	flat_store_dwordx4 v[22:23], v[24:27]
	flat_store_dwordx4 v[22:23], v[38:41] offset:16
	flat_store_dwordx4 v[22:23], v[42:45] offset:2048
	flat_store_dwordx4 v[22:23], v[52:55] offset:2064
	v_pk_mul_f32 v[24:25], v[6:7], v[30:31]
	v_pk_mul_f32 v[22:23], v[4:5], v[28:29]
	v_pk_mul_f32 v[28:29], v[2:3], v[36:37]
	v_pk_mul_f32 v[26:27], v[0:1], v[46:47]
	v_pk_mul_f32 v[32:33], v[14:15], v[50:51]
	v_pk_mul_f32 v[30:31], v[12:13], v[48:49]
	v_pk_mul_f32 v[36:37], v[10:11], v[34:35]
	v_pk_mul_f32 v[34:35], v[8:9], v[56:57]
	flat_store_dwordx4 v[20:21], v[22:25]
	flat_store_dwordx4 v[20:21], v[26:29] offset:16
	flat_store_dwordx4 v[20:21], v[30:33] offset:2048
	flat_store_dwordx4 v[20:21], v[34:37] offset:2064
	s_cbranch_scc1 .LBB0_761
